# EpiRes rolling epilogue + GEMM loop late-A-piece waits deferred (vmcnt 8/10) + hmid stores without nt
# baseline (speedup 1.0000x reference)
.LBB0_42:
	s_add_u32 s82, s80, 0xfffc0080
	s_addc_u32 s83, s81, -1
	s_add_i32 s94, 0, 0x10000
	v_add_u32_e32 v0, s94, v189
	ds_read_b128 v[122:125], v0
	ds_read_b128 v[126:129], v0 offset:1024
	ds_read_b128 v[130:133], v0 offset:2048
	ds_read_b128 v[134:137], v0 offset:3072
	s_cmp_eq_u32 s93, 12
	s_cselect_b32 s85, s11, s83
	s_cselect_b32 s84, s89, s82
	s_cselect_b32 s83, s9, s92
	s_cselect_b32 s82, s90, s91
	v_lshl_add_u64 v[186:187], s[80:81], 0, v[184:185]
	s_add_i32 m0, s59, 0xc000
	ds_read_b128 v[146:149], v193
	ds_read_b128 v[150:153], v193 offset:1024
	ds_read_b128 v[154:157], v193 offset:2048
	ds_read_b128 v[158:161], v193 offset:3072
	ds_read_b128 v[162:165], v193 offset:4096
	ds_read_b128 v[166:169], v193 offset:5120
	ds_read_b128 v[170:173], v193 offset:6144
	ds_read_b128 v[174:177], v193 offset:7168
	global_load_lds_dwordx4 v[186:187], off
	v_lshl_add_u64 v[186:187], s[80:81], 0, v[182:183]
	s_add_i32 m0, s59, 0xe000
	s_nop 0
	global_load_lds_dwordx4 v[186:187], off
	s_waitcnt lgkmcnt(8)
	s_barrier
	s_waitcnt lgkmcnt(0)
	s_setprio 1
	s_waitcnt lgkmcnt(0)
	v_mfma_f32_16x16x32_bf16 v[142:145], v[122:125], v[146:149], v[142:145]
	v_mfma_f32_16x16x32_bf16 v[138:141], v[130:133], v[146:149], v[138:141]
	v_mfma_f32_16x16x32_bf16 v[110:113], v[122:125], v[154:157], v[110:113]
	v_mfma_f32_16x16x32_bf16 v[106:109], v[130:133], v[154:157], v[106:109]
	v_mfma_f32_16x16x32_bf16 v[94:97], v[122:125], v[162:165], v[94:97]
	v_mfma_f32_16x16x32_bf16 v[90:93], v[130:133], v[162:165], v[90:93]
	v_mfma_f32_16x16x32_bf16 v[78:81], v[122:125], v[170:173], v[78:81]
	v_mfma_f32_16x16x32_bf16 v[74:77], v[130:133], v[170:173], v[74:77]
	v_mfma_f32_16x16x32_bf16 v[142:145], v[126:129], v[150:153], v[142:145]
	v_mfma_f32_16x16x32_bf16 v[138:141], v[134:137], v[150:153], v[138:141]
	v_mfma_f32_16x16x32_bf16 v[110:113], v[126:129], v[158:161], v[110:113]
	v_mfma_f32_16x16x32_bf16 v[106:109], v[134:137], v[158:161], v[106:109]
	v_mfma_f32_16x16x32_bf16 v[94:97], v[126:129], v[166:169], v[94:97]
	v_mfma_f32_16x16x32_bf16 v[90:93], v[134:137], v[166:169], v[90:93]
	v_mfma_f32_16x16x32_bf16 v[78:81], v[126:129], v[174:177], v[78:81]
	v_mfma_f32_16x16x32_bf16 v[74:77], v[134:137], v[174:177], v[74:77]
	s_setprio 0
	s_barrier
	s_add_i32 s96, 0, 0x14000
	s_add_i32 s94, s94, s46
	v_add_u32_e32 v0, s96, v189
	v_lshl_add_u64 v[186:187], s[82:83], 0, v[180:181]
	s_mov_b32 m0, s94
	ds_read_b128 v[194:197], v0
	ds_read_b128 v[198:201], v0 offset:1024
	ds_read_b128 v[202:205], v0 offset:2048
	ds_read_b128 v[206:209], v0 offset:3072
	global_load_lds_dwordx4 v[186:187], off
	v_lshl_add_u64 v[210:211], s[82:83], 0, v[178:179]
	s_add_i32 m0, s94, 0x2000
	s_nop 0
	global_load_lds_dwordx4 v[210:211], off
	s_waitcnt vmcnt(10)
	s_barrier
	s_waitcnt lgkmcnt(0)
	s_setprio 1
	s_waitcnt lgkmcnt(0)
	v_mfma_f32_16x16x32_bf16 v[118:121], v[194:197], v[146:149], v[118:121]
	v_mfma_f32_16x16x32_bf16 v[114:117], v[202:205], v[146:149], v[114:117]
	v_mfma_f32_16x16x32_bf16 v[102:105], v[194:197], v[154:157], v[102:105]
	v_mfma_f32_16x16x32_bf16 v[98:101], v[202:205], v[154:157], v[98:101]
	v_mfma_f32_16x16x32_bf16 v[86:89], v[194:197], v[162:165], v[86:89]
	v_mfma_f32_16x16x32_bf16 v[82:85], v[202:205], v[162:165], v[82:85]
	v_mfma_f32_16x16x32_bf16 v[70:73], v[194:197], v[170:173], v[70:73]
	v_mfma_f32_16x16x32_bf16 v[66:69], v[202:205], v[170:173], v[66:69]
	v_mfma_f32_16x16x32_bf16 v[118:121], v[198:201], v[150:153], v[118:121]
	v_mfma_f32_16x16x32_bf16 v[114:117], v[206:209], v[150:153], v[114:117]
	v_mfma_f32_16x16x32_bf16 v[102:105], v[198:201], v[158:161], v[102:105]
	v_mfma_f32_16x16x32_bf16 v[98:101], v[206:209], v[158:161], v[98:101]
	v_mfma_f32_16x16x32_bf16 v[86:89], v[198:201], v[166:169], v[86:89]
	v_mfma_f32_16x16x32_bf16 v[82:85], v[206:209], v[166:169], v[82:85]
	v_mfma_f32_16x16x32_bf16 v[70:73], v[198:201], v[174:177], v[70:73]
	v_mfma_f32_16x16x32_bf16 v[66:69], v[206:209], v[174:177], v[66:69]
	s_setprio 0
	s_mov_b32 m0, s59
	v_lshl_add_u64 v[212:213], s[84:85], 0, v[180:181]
	s_barrier
	ds_read_b128 v[146:149], v193 offset:16384
	ds_read_b128 v[150:153], v193 offset:17408
	ds_read_b128 v[154:157], v193 offset:18432
	ds_read_b128 v[158:161], v193 offset:19456
	ds_read_b128 v[162:165], v193 offset:20480
	ds_read_b128 v[166:169], v193 offset:21504
	ds_read_b128 v[170:173], v193 offset:22528
	ds_read_b128 v[174:177], v193 offset:23552
	global_load_lds_dwordx4 v[212:213], off
	v_lshl_add_u64 v[214:215], s[84:85], 0, v[178:179]
	s_mov_b32 m0, s60
	s_nop 0
	global_load_lds_dwordx4 v[214:215], off
	s_barrier
	s_waitcnt lgkmcnt(0)
	s_setprio 1
	s_waitcnt lgkmcnt(0)
	v_mfma_f32_16x16x32_bf16 v[62:65], v[122:125], v[146:149], v[62:65]
	v_mfma_f32_16x16x32_bf16 v[58:61], v[130:133], v[146:149], v[58:61]
	v_mfma_f32_16x16x32_bf16 v[46:49], v[122:125], v[154:157], v[46:49]
	v_mfma_f32_16x16x32_bf16 v[42:45], v[130:133], v[154:157], v[42:45]
	v_mfma_f32_16x16x32_bf16 v[30:33], v[122:125], v[162:165], v[30:33]
	v_mfma_f32_16x16x32_bf16 v[26:29], v[130:133], v[162:165], v[26:29]
	v_mfma_f32_16x16x32_bf16 v[14:17], v[122:125], v[170:173], v[14:17]
	v_mfma_f32_16x16x32_bf16 v[10:13], v[130:133], v[170:173], v[10:13]
	v_mfma_f32_16x16x32_bf16 v[62:65], v[126:129], v[150:153], v[62:65]
	v_mfma_f32_16x16x32_bf16 v[58:61], v[134:137], v[150:153], v[58:61]
	v_mfma_f32_16x16x32_bf16 v[46:49], v[126:129], v[158:161], v[46:49]
	v_mfma_f32_16x16x32_bf16 v[42:45], v[134:137], v[158:161], v[42:45]
	v_mfma_f32_16x16x32_bf16 v[30:33], v[126:129], v[166:169], v[30:33]
	v_mfma_f32_16x16x32_bf16 v[26:29], v[134:137], v[166:169], v[26:29]
	v_mfma_f32_16x16x32_bf16 v[14:17], v[126:129], v[174:177], v[14:17]
	v_mfma_f32_16x16x32_bf16 v[10:13], v[134:137], v[174:177], v[10:13]
	s_setprio 0
	s_barrier
	s_add_u32 s94, s82, 0x40000
	s_addc_u32 s95, s83, 0
	s_add_i32 s96, s96, s46
	v_lshl_add_u64 v[122:123], s[94:95], 0, v[180:181]
	s_mov_b32 m0, s96
	s_nop 0
	global_load_lds_dwordx4 v[122:123], off
	v_lshl_add_u64 v[122:123], s[94:95], 0, v[178:179]
	s_add_i32 m0, s96, 0x2000
	s_nop 0
	global_load_lds_dwordx4 v[122:123], off
	s_waitcnt vmcnt(8)
	s_barrier
	s_setprio 1
	v_mfma_f32_16x16x32_bf16 v[54:57], v[194:197], v[146:149], v[54:57]
	v_mfma_f32_16x16x32_bf16 v[50:53], v[202:205], v[146:149], v[50:53]
	v_mfma_f32_16x16x32_bf16 v[38:41], v[194:197], v[154:157], v[38:41]
	v_mfma_f32_16x16x32_bf16 v[34:37], v[202:205], v[154:157], v[34:37]
	v_mfma_f32_16x16x32_bf16 v[22:25], v[194:197], v[162:165], v[22:25]
	v_mfma_f32_16x16x32_bf16 v[18:21], v[202:205], v[162:165], v[18:21]
	v_mfma_f32_16x16x32_bf16 v[6:9], v[194:197], v[170:173], v[6:9]
	v_mfma_f32_16x16x32_bf16 v[2:5], v[202:205], v[170:173], v[2:5]
	v_mfma_f32_16x16x32_bf16 v[54:57], v[198:201], v[150:153], v[54:57]
	v_mfma_f32_16x16x32_bf16 v[50:53], v[206:209], v[150:153], v[50:53]
	v_mfma_f32_16x16x32_bf16 v[38:41], v[198:201], v[158:161], v[38:41]
	v_mfma_f32_16x16x32_bf16 v[34:37], v[206:209], v[158:161], v[34:37]
	v_mfma_f32_16x16x32_bf16 v[22:25], v[198:201], v[166:169], v[22:25]
	v_mfma_f32_16x16x32_bf16 v[18:21], v[206:209], v[166:169], v[18:21]
	v_mfma_f32_16x16x32_bf16 v[6:9], v[198:201], v[174:177], v[6:9]
	v_mfma_f32_16x16x32_bf16 v[2:5], v[206:209], v[174:177], v[2:5]
	s_setprio 0
	s_add_i32 s94, 0, 0x18000
	v_add_u32_e32 v0, s94, v189
	s_barrier
	ds_read_b128 v[122:125], v0
	ds_read_b128 v[126:129], v0 offset:1024
	ds_read_b128 v[130:133], v0 offset:2048
	ds_read_b128 v[134:137], v0 offset:3072
	s_add_u32 s84, s84, 0x40000
	s_addc_u32 s85, s85, 0
	s_mov_b32 m0, s61
	v_lshl_add_u64 v[194:195], s[84:85], 0, v[180:181]
	ds_read_b128 v[146:149], v193 offset:32768
	ds_read_b128 v[150:153], v193 offset:33792
	ds_read_b128 v[154:157], v193 offset:34816
	ds_read_b128 v[158:161], v193 offset:35840
	ds_read_b128 v[162:165], v193 offset:36864
	ds_read_b128 v[166:169], v193 offset:37888
	ds_read_b128 v[170:173], v193 offset:38912
	ds_read_b128 v[174:177], v193 offset:39936
	global_load_lds_dwordx4 v[194:195], off
	v_lshl_add_u64 v[194:195], s[84:85], 0, v[178:179]
	s_mov_b32 m0, s76
	s_nop 0
	global_load_lds_dwordx4 v[194:195], off
	s_waitcnt lgkmcnt(8)
	s_barrier
	s_waitcnt lgkmcnt(0)
	s_setprio 1
	s_waitcnt lgkmcnt(0)
	v_mfma_f32_16x16x32_bf16 v[142:145], v[122:125], v[146:149], v[142:145]
	v_mfma_f32_16x16x32_bf16 v[138:141], v[130:133], v[146:149], v[138:141]
	v_mfma_f32_16x16x32_bf16 v[110:113], v[122:125], v[154:157], v[110:113]
	v_mfma_f32_16x16x32_bf16 v[106:109], v[130:133], v[154:157], v[106:109]
	v_mfma_f32_16x16x32_bf16 v[94:97], v[122:125], v[162:165], v[94:97]
	v_mfma_f32_16x16x32_bf16 v[90:93], v[130:133], v[162:165], v[90:93]
	v_mfma_f32_16x16x32_bf16 v[78:81], v[122:125], v[170:173], v[78:81]
	v_mfma_f32_16x16x32_bf16 v[74:77], v[130:133], v[170:173], v[74:77]
	v_mfma_f32_16x16x32_bf16 v[142:145], v[126:129], v[150:153], v[142:145]
	v_mfma_f32_16x16x32_bf16 v[138:141], v[134:137], v[150:153], v[138:141]
	v_mfma_f32_16x16x32_bf16 v[110:113], v[126:129], v[158:161], v[110:113]
	v_mfma_f32_16x16x32_bf16 v[106:109], v[134:137], v[158:161], v[106:109]
	v_mfma_f32_16x16x32_bf16 v[94:97], v[126:129], v[166:169], v[94:97]
	v_mfma_f32_16x16x32_bf16 v[90:93], v[134:137], v[166:169], v[90:93]
	v_mfma_f32_16x16x32_bf16 v[78:81], v[126:129], v[174:177], v[78:81]
	v_mfma_f32_16x16x32_bf16 v[74:77], v[134:137], v[174:177], v[74:77]
	s_setprio 0
	s_barrier
	s_add_i32 s84, 0, 0x1c000
	s_add_i32 s85, s94, s46
	v_add_u32_e32 v0, s84, v189
	v_lshl_add_u64 v[186:187], v[186:187], 0, s[48:49]
	s_mov_b32 m0, s85
	ds_read_b128 v[194:197], v0
	ds_read_b128 v[198:201], v0 offset:1024
	ds_read_b128 v[202:205], v0 offset:2048
	ds_read_b128 v[206:209], v0 offset:3072
	global_load_lds_dwordx4 v[186:187], off
	v_lshl_add_u64 v[186:187], v[210:211], 0, s[48:49]
	s_add_i32 m0, s85, 0x2000
	s_nop 0
	global_load_lds_dwordx4 v[186:187], off
	s_waitcnt vmcnt(10)
	s_barrier
	s_waitcnt lgkmcnt(0)
	s_setprio 1
	s_waitcnt lgkmcnt(0)
	v_mfma_f32_16x16x32_bf16 v[118:121], v[194:197], v[146:149], v[118:121]
	v_mfma_f32_16x16x32_bf16 v[114:117], v[202:205], v[146:149], v[114:117]
	v_mfma_f32_16x16x32_bf16 v[102:105], v[194:197], v[154:157], v[102:105]
	v_mfma_f32_16x16x32_bf16 v[98:101], v[202:205], v[154:157], v[98:101]
	v_mfma_f32_16x16x32_bf16 v[86:89], v[194:197], v[162:165], v[86:89]
	v_mfma_f32_16x16x32_bf16 v[82:85], v[202:205], v[162:165], v[82:85]
	v_mfma_f32_16x16x32_bf16 v[70:73], v[194:197], v[170:173], v[70:73]
	v_mfma_f32_16x16x32_bf16 v[66:69], v[202:205], v[170:173], v[66:69]
	v_mfma_f32_16x16x32_bf16 v[118:121], v[198:201], v[150:153], v[118:121]
	v_mfma_f32_16x16x32_bf16 v[114:117], v[206:209], v[150:153], v[114:117]
	v_mfma_f32_16x16x32_bf16 v[102:105], v[198:201], v[158:161], v[102:105]
	v_mfma_f32_16x16x32_bf16 v[98:101], v[206:209], v[158:161], v[98:101]
	v_mfma_f32_16x16x32_bf16 v[86:89], v[198:201], v[166:169], v[86:89]
	v_mfma_f32_16x16x32_bf16 v[82:85], v[206:209], v[166:169], v[82:85]
	v_mfma_f32_16x16x32_bf16 v[70:73], v[198:201], v[174:177], v[70:73]
	v_mfma_f32_16x16x32_bf16 v[66:69], v[206:209], v[174:177], v[66:69]
	s_setprio 0
	s_mov_b32 m0, s79
	v_lshl_add_u64 v[186:187], v[212:213], 0, s[48:49]
	s_barrier
	ds_read_b128 v[146:149], v193 offset:49152
	ds_read_b128 v[150:153], v193 offset:50176
	ds_read_b128 v[154:157], v193 offset:51200
	ds_read_b128 v[158:161], v193 offset:52224
	ds_read_b128 v[162:165], v193 offset:53248
	ds_read_b128 v[166:169], v193 offset:54272
	ds_read_b128 v[170:173], v193 offset:55296
	ds_read_b128 v[174:177], v193 offset:56320
	global_load_lds_dwordx4 v[186:187], off
	v_lshl_add_u64 v[186:187], v[214:215], 0, s[48:49]
	s_mov_b32 m0, s86
	s_nop 0
	global_load_lds_dwordx4 v[186:187], off
	s_barrier
; template <int CTRL> DEVI float dpp(float x) { return __builtin_bit_cast(float, __builtin_amdgcn_mov_dpp(__builtin_bit_cast(int, x), CTRL, 0xf, 0xf, true)); }
;     DEVI void operator()(AccRef acc, const pg8::Unit& u, int wr, int wc, int fr, int fq) const {
;         unsigned o = (unsigned)((u.pm * 256 + wr * 64 + fr) * DM + u.pn * 256 + wc * 32 + 4 * fq) * 4u;
;         const bool lo = fr < 8;
;         unsigned os = (unsigned)((u.pm * 256 + wr * 64 + (fr & 7)) * DM + u.pn * 256 + wc * 32 + 4 * fq) * 4u + (lo ? 0u : 64u);
; #pragma unroll
;         for (int ai = 0; ai < 2; ++ai) {
;             asm volatile("" : "+v"(o), "+v"(os));
;             f32x4 b[4][2][2];
; #pragma unroll
;             for (int m = 0; m < 4; ++m)
; #pragma unroll
;                 for (int bj = 0; bj < 2; ++bj)
; #pragma unroll
;                     for (int n = 0; n < 2; ++n) b[m][bj][n] = *(const f32x4*)((const char*)base + o + (unsigned)(m * 16 * DM * 4 + bj * 512 + n * 64));
; #pragma unroll
;             for (int m = 0; m < 4; ++m)
; #pragma unroll
;                 for (int bj = 0; bj < 2; ++bj) { const f32x4 d0 = b[m][bj][0] + alpha * acc[ai][bj][m][0], d1 = b[m][bj][1] + alpha * acc[ai][bj][m][1];
;                     f32x4 t0, t1;
; #pragma unroll
;                     for (int i = 0; i < 4; ++i) { t0[i] = dpp<0x128>(d0[i]); t1[i] = dpp<0x128>(d1[i]); }
;                     const f32x4 sa = lo ? d0 : t1, sb = lo ? t0 : d1;
;                     const unsigned oo = os + (unsigned)(m * 16 * DM * 4 + bj * 512);
;                     *(f32x4*)((char*)out + oo) = sa; *(f32x4*)((char*)out + oo + 8u * DM * 4u) = sb; }
;             o += 128u * DM * 4u; os += 128u * DM * 4u; }
	s_waitcnt lgkmcnt(0)
	s_setprio 1
	s_waitcnt lgkmcnt(0)
	v_mfma_f32_16x16x32_bf16 v[62:65], v[122:125], v[146:149], v[62:65]
	v_mfma_f32_16x16x32_bf16 v[58:61], v[130:133], v[146:149], v[58:61]
	v_mfma_f32_16x16x32_bf16 v[46:49], v[122:125], v[154:157], v[46:49]
	v_mfma_f32_16x16x32_bf16 v[42:45], v[130:133], v[154:157], v[42:45]
	v_mfma_f32_16x16x32_bf16 v[30:33], v[122:125], v[162:165], v[30:33]
	v_mfma_f32_16x16x32_bf16 v[26:29], v[130:133], v[162:165], v[26:29]
	v_mfma_f32_16x16x32_bf16 v[14:17], v[122:125], v[170:173], v[14:17]
	v_mfma_f32_16x16x32_bf16 v[10:13], v[130:133], v[170:173], v[10:13]
	v_mfma_f32_16x16x32_bf16 v[62:65], v[126:129], v[150:153], v[62:65]
	v_mfma_f32_16x16x32_bf16 v[58:61], v[134:137], v[150:153], v[58:61]
	v_mfma_f32_16x16x32_bf16 v[46:49], v[126:129], v[158:161], v[46:49]
	v_mfma_f32_16x16x32_bf16 v[42:45], v[134:137], v[158:161], v[42:45]
	v_mfma_f32_16x16x32_bf16 v[30:33], v[126:129], v[166:169], v[30:33]
	v_mfma_f32_16x16x32_bf16 v[26:29], v[134:137], v[166:169], v[26:29]
	v_mfma_f32_16x16x32_bf16 v[14:17], v[126:129], v[174:177], v[14:17]
	v_mfma_f32_16x16x32_bf16 v[10:13], v[134:137], v[174:177], v[10:13]
	s_setprio 0
	s_barrier
	s_add_u32 s82, s82, 0x40080
	s_addc_u32 s83, s83, 0
	s_add_i32 s84, s84, s46
	v_lshl_add_u64 v[122:123], s[82:83], 0, v[180:181]
	s_mov_b32 m0, s84
	s_nop 0
	global_load_lds_dwordx4 v[122:123], off
	v_lshl_add_u64 v[122:123], s[82:83], 0, v[178:179]
	s_add_i32 m0, s84, 0x2000
	s_nop 0
	global_load_lds_dwordx4 v[122:123], off
	s_waitcnt vmcnt(8)
	s_barrier
	s_setprio 1
	v_mfma_f32_16x16x32_bf16 v[54:57], v[194:197], v[146:149], v[54:57]
	v_mfma_f32_16x16x32_bf16 v[50:53], v[202:205], v[146:149], v[50:53]
	v_mfma_f32_16x16x32_bf16 v[38:41], v[194:197], v[154:157], v[38:41]
	v_mfma_f32_16x16x32_bf16 v[34:37], v[202:205], v[154:157], v[34:37]
	v_mfma_f32_16x16x32_bf16 v[22:25], v[194:197], v[162:165], v[22:25]
	v_mfma_f32_16x16x32_bf16 v[18:21], v[202:205], v[162:165], v[18:21]
	v_mfma_f32_16x16x32_bf16 v[6:9], v[194:197], v[170:173], v[6:9]
	v_mfma_f32_16x16x32_bf16 v[2:5], v[202:205], v[170:173], v[2:5]
	v_mfma_f32_16x16x32_bf16 v[54:57], v[198:201], v[150:153], v[54:57]
	v_mfma_f32_16x16x32_bf16 v[50:53], v[206:209], v[150:153], v[50:53]
	v_mfma_f32_16x16x32_bf16 v[38:41], v[198:201], v[158:161], v[38:41]
	v_mfma_f32_16x16x32_bf16 v[34:37], v[206:209], v[158:161], v[34:37]
	v_mfma_f32_16x16x32_bf16 v[22:25], v[198:201], v[166:169], v[22:25]
	v_mfma_f32_16x16x32_bf16 v[18:21], v[206:209], v[166:169], v[18:21]
	v_mfma_f32_16x16x32_bf16 v[6:9], v[198:201], v[174:177], v[6:9]
	v_mfma_f32_16x16x32_bf16 v[2:5], v[206:209], v[174:177], v[2:5]
	s_setprio 0
	s_add_i32 s93, s93, 2
	s_add_u32 s91, s91, 0x100
	s_addc_u32 s92, s92, 0
	s_add_u32 s80, s80, 0x100
	s_addc_u32 s81, s81, 0
	s_cmp_gt_u32 s93, 13
	s_barrier
	s_cbranch_scc0 .LBB0_42
	s_lshl_b32 s9, s78, 8
	s_add_i32 s9, s9, s77
	v_or_b32_e32 v0, s9, v188
	s_lshl_b32 s11, s88, 8
	v_or_b32_e32 v122, s9, v190
	v_lshl_add_u32 v0, v0, 10, s11
	v_lshl_add_u32 v122, v122, 10, s11
	v_or_b32_e32 v0, v0, v192
	v_or_b32_e32 v122, v122, v192
	v_lshlrev_b32_e32 v0, 2, v0
	v_lshl_or_b32 v186, v122, 2, v191
	s_mov_b32 s88, s8
	s_mov_b32 s78, s10
	s_mov_b64 s[80:81], s[24:25]
	s_mov_b64 s[82:83], s[22:23]
	v_add_u32_e32 v187, 0x8000, v186
	s_add_u32 s98, s28, 0x0
	s_addc_u32 s99, s29, 0
	global_load_dwordx4 v[194:197], v0, s[98:99]
	global_load_dwordx4 v[198:201], v0, s[98:99] offset:64
	global_load_dwordx4 v[202:205], v0, s[98:99] offset:512
	global_load_dwordx4 v[206:209], v0, s[98:99] offset:576
	s_add_u32 s98, s28, 0x10000
	s_addc_u32 s99, s29, 0
	global_load_dwordx4 v[174:177], v0, s[98:99]
	global_load_dwordx4 v[170:173], v0, s[98:99] offset:64
	global_load_dwordx4 v[166:169], v0, s[98:99] offset:512
	global_load_dwordx4 v[162:165], v0, s[98:99] offset:576
	s_add_u32 s98, s28, 0x20000
	s_addc_u32 s99, s29, 0
	global_load_dwordx4 v[158:161], v0, s[98:99]
	global_load_dwordx4 v[154:157], v0, s[98:99] offset:64
	global_load_dwordx4 v[150:153], v0, s[98:99] offset:512
	global_load_dwordx4 v[146:149], v0, s[98:99] offset:576
	s_add_u32 s98, s28, 0x30000
	s_addc_u32 s99, s29, 0
	global_load_dwordx4 v[134:137], v0, s[98:99]
	global_load_dwordx4 v[130:133], v0, s[98:99] offset:64
	global_load_dwordx4 v[126:129], v0, s[98:99] offset:512
	global_load_dwordx4 v[122:125], v0, s[98:99] offset:576
	s_waitcnt vmcnt(12)
	v_pk_add_f32 v[142:143], v[142:143], v[194:195]
	v_pk_add_f32 v[144:145], v[144:145], v[196:197]
	v_pk_add_f32 v[138:139], v[138:139], v[198:199]
	v_pk_add_f32 v[140:141], v[140:141], v[200:201]
	v_pk_add_f32 v[118:119], v[118:119], v[202:203]
	v_pk_add_f32 v[120:121], v[120:121], v[204:205]
	v_pk_add_f32 v[114:115], v[114:115], v[206:207]
	v_pk_add_f32 v[116:117], v[116:117], v[208:209]
	s_mov_b64 vcc, s[4:5]
	v_cndmask_b32_dpp v194, v138, v142, vcc row_ror:8 row_mask:0xf bank_mask:0xf bound_ctrl:1
	v_cndmask_b32_dpp v195, v139, v143, vcc row_ror:8 row_mask:0xf bank_mask:0xf bound_ctrl:1
	v_cndmask_b32_dpp v196, v140, v144, vcc row_ror:8 row_mask:0xf bank_mask:0xf bound_ctrl:1
	v_cndmask_b32_dpp v197, v141, v145, vcc row_ror:8 row_mask:0xf bank_mask:0xf bound_ctrl:1
	v_cndmask_b32_dpp v202, v114, v118, vcc row_ror:8 row_mask:0xf bank_mask:0xf bound_ctrl:1
	v_cndmask_b32_dpp v203, v115, v119, vcc row_ror:8 row_mask:0xf bank_mask:0xf bound_ctrl:1
	v_cndmask_b32_dpp v204, v116, v120, vcc row_ror:8 row_mask:0xf bank_mask:0xf bound_ctrl:1
	v_cndmask_b32_dpp v205, v117, v121, vcc row_ror:8 row_mask:0xf bank_mask:0xf bound_ctrl:1
	s_not_b64 vcc, s[4:5]
	v_cndmask_b32_dpp v198, v142, v138, vcc row_ror:8 row_mask:0xf bank_mask:0xf bound_ctrl:1
	v_cndmask_b32_dpp v199, v143, v139, vcc row_ror:8 row_mask:0xf bank_mask:0xf bound_ctrl:1
	v_cndmask_b32_dpp v200, v144, v140, vcc row_ror:8 row_mask:0xf bank_mask:0xf bound_ctrl:1
	v_cndmask_b32_dpp v201, v145, v141, vcc row_ror:8 row_mask:0xf bank_mask:0xf bound_ctrl:1
	v_cndmask_b32_dpp v206, v118, v114, vcc row_ror:8 row_mask:0xf bank_mask:0xf bound_ctrl:1
	v_cndmask_b32_dpp v207, v119, v115, vcc row_ror:8 row_mask:0xf bank_mask:0xf bound_ctrl:1
	v_cndmask_b32_dpp v208, v120, v116, vcc row_ror:8 row_mask:0xf bank_mask:0xf bound_ctrl:1
	v_cndmask_b32_dpp v209, v121, v117, vcc row_ror:8 row_mask:0xf bank_mask:0xf bound_ctrl:1
	s_add_u32 s100, s28, 0x0
	s_addc_u32 s101, s29, 0
	global_store_dwordx4 v186, v[194:197], s[100:101]
	global_store_dwordx4 v187, v[198:201], s[100:101]
	global_store_dwordx4 v186, v[202:205], s[100:101] offset:512
	global_store_dwordx4 v187, v[206:209], s[100:101] offset:512
	s_add_u32 s98, s28, 0x80000
	s_addc_u32 s99, s29, 0
	global_load_dwordx4 v[142:145], v0, s[98:99]
	global_load_dwordx4 v[138:141], v0, s[98:99] offset:64
	global_load_dwordx4 v[118:121], v0, s[98:99] offset:512
	global_load_dwordx4 v[114:117], v0, s[98:99] offset:576
	s_waitcnt vmcnt(16)
; template <int CTRL> DEVI float dpp(float x) { return __builtin_bit_cast(float, __builtin_amdgcn_mov_dpp(__builtin_bit_cast(int, x), CTRL, 0xf, 0xf, true)); }
;     DEVI void operator()(AccRef acc, const pg8::Unit& u, int wr, int wc, int fr, int fq) const {
;     ...
;         for (int ai = 0; ai < 2; ++ai) {
;             asm volatile("" : "+v"(o), "+v"(os));
;             f32x4 b[4][2][2];
; #pragma unroll
;             for (int m = 0; m < 4; ++m)
; #pragma unroll
;                 for (int bj = 0; bj < 2; ++bj)
; #pragma unroll
;                     for (int n = 0; n < 2; ++n) b[m][bj][n] = *(const f32x4*)((const char*)base + o + (unsigned)(m * 16 * DM * 4 + bj * 512 + n * 64));
; #pragma unroll
;             for (int m = 0; m < 4; ++m)
; #pragma unroll
;                 for (int bj = 0; bj < 2; ++bj) { const f32x4 d0 = b[m][bj][0] + alpha * acc[ai][bj][m][0], d1 = b[m][bj][1] + alpha * acc[ai][bj][m][1];
;                     f32x4 t0, t1;
; #pragma unroll
;                     for (int i = 0; i < 4; ++i) { t0[i] = dpp<0x128>(d0[i]); t1[i] = dpp<0x128>(d1[i]); }
;                     const f32x4 sa = lo ? d0 : t1, sb = lo ? t0 : d1;
;                     const unsigned oo = os + (unsigned)(m * 16 * DM * 4 + bj * 512);
;                     *(f32x4*)((char*)out + oo) = sa; *(f32x4*)((char*)out + oo + 8u * DM * 4u) = sb; }
;             o += 128u * DM * 4u; os += 128u * DM * 4u; }
	v_pk_add_f32 v[110:111], v[110:111], v[174:175]
	v_pk_add_f32 v[112:113], v[112:113], v[176:177]
	v_pk_add_f32 v[106:107], v[106:107], v[170:171]
	v_pk_add_f32 v[108:109], v[108:109], v[172:173]
	v_pk_add_f32 v[102:103], v[102:103], v[166:167]
	v_pk_add_f32 v[104:105], v[104:105], v[168:169]
	v_pk_add_f32 v[98:99], v[98:99], v[162:163]
	v_pk_add_f32 v[100:101], v[100:101], v[164:165]
	s_mov_b64 vcc, s[4:5]
	v_cndmask_b32_dpp v174, v106, v110, vcc row_ror:8 row_mask:0xf bank_mask:0xf bound_ctrl:1
	v_cndmask_b32_dpp v175, v107, v111, vcc row_ror:8 row_mask:0xf bank_mask:0xf bound_ctrl:1
	v_cndmask_b32_dpp v176, v108, v112, vcc row_ror:8 row_mask:0xf bank_mask:0xf bound_ctrl:1
	v_cndmask_b32_dpp v177, v109, v113, vcc row_ror:8 row_mask:0xf bank_mask:0xf bound_ctrl:1
	v_cndmask_b32_dpp v166, v98, v102, vcc row_ror:8 row_mask:0xf bank_mask:0xf bound_ctrl:1
	v_cndmask_b32_dpp v167, v99, v103, vcc row_ror:8 row_mask:0xf bank_mask:0xf bound_ctrl:1
	v_cndmask_b32_dpp v168, v100, v104, vcc row_ror:8 row_mask:0xf bank_mask:0xf bound_ctrl:1
	v_cndmask_b32_dpp v169, v101, v105, vcc row_ror:8 row_mask:0xf bank_mask:0xf bound_ctrl:1
	s_not_b64 vcc, s[4:5]
	v_cndmask_b32_dpp v170, v110, v106, vcc row_ror:8 row_mask:0xf bank_mask:0xf bound_ctrl:1
	v_cndmask_b32_dpp v171, v111, v107, vcc row_ror:8 row_mask:0xf bank_mask:0xf bound_ctrl:1
	v_cndmask_b32_dpp v172, v112, v108, vcc row_ror:8 row_mask:0xf bank_mask:0xf bound_ctrl:1
	v_cndmask_b32_dpp v173, v113, v109, vcc row_ror:8 row_mask:0xf bank_mask:0xf bound_ctrl:1
	v_cndmask_b32_dpp v162, v102, v98, vcc row_ror:8 row_mask:0xf bank_mask:0xf bound_ctrl:1
	v_cndmask_b32_dpp v163, v103, v99, vcc row_ror:8 row_mask:0xf bank_mask:0xf bound_ctrl:1
	v_cndmask_b32_dpp v164, v104, v100, vcc row_ror:8 row_mask:0xf bank_mask:0xf bound_ctrl:1
	v_cndmask_b32_dpp v165, v105, v101, vcc row_ror:8 row_mask:0xf bank_mask:0xf bound_ctrl:1
	s_add_u32 s100, s28, 0x10000
	s_addc_u32 s101, s29, 0
	global_store_dwordx4 v186, v[174:177], s[100:101]
	global_store_dwordx4 v187, v[170:173], s[100:101]
	global_store_dwordx4 v186, v[166:169], s[100:101] offset:512
	global_store_dwordx4 v187, v[162:165], s[100:101] offset:512
	s_add_u32 s98, s28, 0x90000
	s_addc_u32 s99, s29, 0
	global_load_dwordx4 v[110:113], v0, s[98:99]
	global_load_dwordx4 v[106:109], v0, s[98:99] offset:64
	global_load_dwordx4 v[102:105], v0, s[98:99] offset:512
	global_load_dwordx4 v[98:101], v0, s[98:99] offset:576
	s_waitcnt vmcnt(20)
	v_pk_add_f32 v[94:95], v[94:95], v[158:159]
	v_pk_add_f32 v[96:97], v[96:97], v[160:161]
	v_pk_add_f32 v[90:91], v[90:91], v[154:155]
	v_pk_add_f32 v[92:93], v[92:93], v[156:157]
	v_pk_add_f32 v[86:87], v[86:87], v[150:151]
	v_pk_add_f32 v[88:89], v[88:89], v[152:153]
	v_pk_add_f32 v[82:83], v[82:83], v[146:147]
	v_pk_add_f32 v[84:85], v[84:85], v[148:149]
	s_mov_b64 vcc, s[4:5]
	v_cndmask_b32_dpp v158, v90, v94, vcc row_ror:8 row_mask:0xf bank_mask:0xf bound_ctrl:1
	v_cndmask_b32_dpp v159, v91, v95, vcc row_ror:8 row_mask:0xf bank_mask:0xf bound_ctrl:1
	v_cndmask_b32_dpp v160, v92, v96, vcc row_ror:8 row_mask:0xf bank_mask:0xf bound_ctrl:1
	v_cndmask_b32_dpp v161, v93, v97, vcc row_ror:8 row_mask:0xf bank_mask:0xf bound_ctrl:1
	v_cndmask_b32_dpp v150, v82, v86, vcc row_ror:8 row_mask:0xf bank_mask:0xf bound_ctrl:1
	v_cndmask_b32_dpp v151, v83, v87, vcc row_ror:8 row_mask:0xf bank_mask:0xf bound_ctrl:1
	v_cndmask_b32_dpp v152, v84, v88, vcc row_ror:8 row_mask:0xf bank_mask:0xf bound_ctrl:1
	v_cndmask_b32_dpp v153, v85, v89, vcc row_ror:8 row_mask:0xf bank_mask:0xf bound_ctrl:1
	s_not_b64 vcc, s[4:5]
	v_cndmask_b32_dpp v154, v94, v90, vcc row_ror:8 row_mask:0xf bank_mask:0xf bound_ctrl:1
	v_cndmask_b32_dpp v155, v95, v91, vcc row_ror:8 row_mask:0xf bank_mask:0xf bound_ctrl:1
	v_cndmask_b32_dpp v156, v96, v92, vcc row_ror:8 row_mask:0xf bank_mask:0xf bound_ctrl:1
	v_cndmask_b32_dpp v157, v97, v93, vcc row_ror:8 row_mask:0xf bank_mask:0xf bound_ctrl:1
	v_cndmask_b32_dpp v146, v86, v82, vcc row_ror:8 row_mask:0xf bank_mask:0xf bound_ctrl:1
	v_cndmask_b32_dpp v147, v87, v83, vcc row_ror:8 row_mask:0xf bank_mask:0xf bound_ctrl:1
	v_cndmask_b32_dpp v148, v88, v84, vcc row_ror:8 row_mask:0xf bank_mask:0xf bound_ctrl:1
	v_cndmask_b32_dpp v149, v89, v85, vcc row_ror:8 row_mask:0xf bank_mask:0xf bound_ctrl:1
	s_add_u32 s100, s28, 0x20000
	s_addc_u32 s101, s29, 0
	global_store_dwordx4 v186, v[158:161], s[100:101]
	global_store_dwordx4 v187, v[154:157], s[100:101]
	global_store_dwordx4 v186, v[150:153], s[100:101] offset:512
	global_store_dwordx4 v187, v[146:149], s[100:101] offset:512
	s_add_u32 s98, s28, 0xa0000
	s_addc_u32 s99, s29, 0
	global_load_dwordx4 v[94:97], v0, s[98:99]
	global_load_dwordx4 v[90:93], v0, s[98:99] offset:64
	global_load_dwordx4 v[86:89], v0, s[98:99] offset:512
	global_load_dwordx4 v[82:85], v0, s[98:99] offset:576
	s_waitcnt vmcnt(24)
; template <int CTRL> DEVI float dpp(float x) { return __builtin_bit_cast(float, __builtin_amdgcn_mov_dpp(__builtin_bit_cast(int, x), CTRL, 0xf, 0xf, true)); }
;     DEVI void operator()(AccRef acc, const pg8::Unit& u, int wr, int wc, int fr, int fq) const {
;     ...
;         for (int ai = 0; ai < 2; ++ai) {
;             asm volatile("" : "+v"(o), "+v"(os));
;             f32x4 b[4][2][2];
; #pragma unroll
;             for (int m = 0; m < 4; ++m)
; #pragma unroll
;                 for (int bj = 0; bj < 2; ++bj)
; #pragma unroll
;                     for (int n = 0; n < 2; ++n) b[m][bj][n] = *(const f32x4*)((const char*)base + o + (unsigned)(m * 16 * DM * 4 + bj * 512 + n * 64));
; #pragma unroll
;             for (int m = 0; m < 4; ++m)
; #pragma unroll
;                 for (int bj = 0; bj < 2; ++bj) { const f32x4 d0 = b[m][bj][0] + alpha * acc[ai][bj][m][0], d1 = b[m][bj][1] + alpha * acc[ai][bj][m][1];
;                     f32x4 t0, t1;
; #pragma unroll
;                     for (int i = 0; i < 4; ++i) { t0[i] = dpp<0x128>(d0[i]); t1[i] = dpp<0x128>(d1[i]); }
;                     const f32x4 sa = lo ? d0 : t1, sb = lo ? t0 : d1;
;                     const unsigned oo = os + (unsigned)(m * 16 * DM * 4 + bj * 512);
;                     *(f32x4*)((char*)out + oo) = sa; *(f32x4*)((char*)out + oo + 8u * DM * 4u) = sb; }
;             o += 128u * DM * 4u; os += 128u * DM * 4u; }
	v_pk_add_f32 v[78:79], v[78:79], v[134:135]
	v_pk_add_f32 v[80:81], v[80:81], v[136:137]
	v_pk_add_f32 v[74:75], v[74:75], v[130:131]
	v_pk_add_f32 v[76:77], v[76:77], v[132:133]
	v_pk_add_f32 v[70:71], v[70:71], v[126:127]
	v_pk_add_f32 v[72:73], v[72:73], v[128:129]
	v_pk_add_f32 v[66:67], v[66:67], v[122:123]
	v_pk_add_f32 v[68:69], v[68:69], v[124:125]
	s_mov_b64 vcc, s[4:5]
	v_cndmask_b32_dpp v134, v74, v78, vcc row_ror:8 row_mask:0xf bank_mask:0xf bound_ctrl:1
	v_cndmask_b32_dpp v135, v75, v79, vcc row_ror:8 row_mask:0xf bank_mask:0xf bound_ctrl:1
	v_cndmask_b32_dpp v136, v76, v80, vcc row_ror:8 row_mask:0xf bank_mask:0xf bound_ctrl:1
	v_cndmask_b32_dpp v137, v77, v81, vcc row_ror:8 row_mask:0xf bank_mask:0xf bound_ctrl:1
	v_cndmask_b32_dpp v126, v66, v70, vcc row_ror:8 row_mask:0xf bank_mask:0xf bound_ctrl:1
	v_cndmask_b32_dpp v127, v67, v71, vcc row_ror:8 row_mask:0xf bank_mask:0xf bound_ctrl:1
	v_cndmask_b32_dpp v128, v68, v72, vcc row_ror:8 row_mask:0xf bank_mask:0xf bound_ctrl:1
	v_cndmask_b32_dpp v129, v69, v73, vcc row_ror:8 row_mask:0xf bank_mask:0xf bound_ctrl:1
	s_not_b64 vcc, s[4:5]
	v_cndmask_b32_dpp v130, v78, v74, vcc row_ror:8 row_mask:0xf bank_mask:0xf bound_ctrl:1
	v_cndmask_b32_dpp v131, v79, v75, vcc row_ror:8 row_mask:0xf bank_mask:0xf bound_ctrl:1
	v_cndmask_b32_dpp v132, v80, v76, vcc row_ror:8 row_mask:0xf bank_mask:0xf bound_ctrl:1
	v_cndmask_b32_dpp v133, v81, v77, vcc row_ror:8 row_mask:0xf bank_mask:0xf bound_ctrl:1
	v_cndmask_b32_dpp v122, v70, v66, vcc row_ror:8 row_mask:0xf bank_mask:0xf bound_ctrl:1
	v_cndmask_b32_dpp v123, v71, v67, vcc row_ror:8 row_mask:0xf bank_mask:0xf bound_ctrl:1
	v_cndmask_b32_dpp v124, v72, v68, vcc row_ror:8 row_mask:0xf bank_mask:0xf bound_ctrl:1
	v_cndmask_b32_dpp v125, v73, v69, vcc row_ror:8 row_mask:0xf bank_mask:0xf bound_ctrl:1
	s_add_u32 s100, s28, 0x30000
	s_addc_u32 s101, s29, 0
	global_store_dwordx4 v186, v[134:137], s[100:101]
	global_store_dwordx4 v187, v[130:133], s[100:101]
	global_store_dwordx4 v186, v[126:129], s[100:101] offset:512
	global_store_dwordx4 v187, v[122:125], s[100:101] offset:512
	s_add_u32 s98, s28, 0xb0000
	s_addc_u32 s99, s29, 0
	global_load_dwordx4 v[78:81], v0, s[98:99]
	global_load_dwordx4 v[74:77], v0, s[98:99] offset:64
	global_load_dwordx4 v[70:73], v0, s[98:99] offset:512
	global_load_dwordx4 v[66:69], v0, s[98:99] offset:576
	s_waitcnt vmcnt(24)
	v_pk_add_f32 v[62:63], v[62:63], v[142:143]
	v_pk_add_f32 v[64:65], v[64:65], v[144:145]
	v_pk_add_f32 v[58:59], v[58:59], v[138:139]
	v_pk_add_f32 v[60:61], v[60:61], v[140:141]
	v_pk_add_f32 v[54:55], v[54:55], v[118:119]
	v_pk_add_f32 v[56:57], v[56:57], v[120:121]
	v_pk_add_f32 v[50:51], v[50:51], v[114:115]
	v_pk_add_f32 v[52:53], v[52:53], v[116:117]
	s_mov_b64 vcc, s[4:5]
	v_cndmask_b32_dpp v142, v58, v62, vcc row_ror:8 row_mask:0xf bank_mask:0xf bound_ctrl:1
	v_cndmask_b32_dpp v143, v59, v63, vcc row_ror:8 row_mask:0xf bank_mask:0xf bound_ctrl:1
	v_cndmask_b32_dpp v144, v60, v64, vcc row_ror:8 row_mask:0xf bank_mask:0xf bound_ctrl:1
	v_cndmask_b32_dpp v145, v61, v65, vcc row_ror:8 row_mask:0xf bank_mask:0xf bound_ctrl:1
	v_cndmask_b32_dpp v118, v50, v54, vcc row_ror:8 row_mask:0xf bank_mask:0xf bound_ctrl:1
	v_cndmask_b32_dpp v119, v51, v55, vcc row_ror:8 row_mask:0xf bank_mask:0xf bound_ctrl:1
	v_cndmask_b32_dpp v120, v52, v56, vcc row_ror:8 row_mask:0xf bank_mask:0xf bound_ctrl:1
	v_cndmask_b32_dpp v121, v53, v57, vcc row_ror:8 row_mask:0xf bank_mask:0xf bound_ctrl:1
	s_not_b64 vcc, s[4:5]
	v_cndmask_b32_dpp v138, v62, v58, vcc row_ror:8 row_mask:0xf bank_mask:0xf bound_ctrl:1
	v_cndmask_b32_dpp v139, v63, v59, vcc row_ror:8 row_mask:0xf bank_mask:0xf bound_ctrl:1
	v_cndmask_b32_dpp v140, v64, v60, vcc row_ror:8 row_mask:0xf bank_mask:0xf bound_ctrl:1
	v_cndmask_b32_dpp v141, v65, v61, vcc row_ror:8 row_mask:0xf bank_mask:0xf bound_ctrl:1
	v_cndmask_b32_dpp v114, v54, v50, vcc row_ror:8 row_mask:0xf bank_mask:0xf bound_ctrl:1
	v_cndmask_b32_dpp v115, v55, v51, vcc row_ror:8 row_mask:0xf bank_mask:0xf bound_ctrl:1
	v_cndmask_b32_dpp v116, v56, v52, vcc row_ror:8 row_mask:0xf bank_mask:0xf bound_ctrl:1
	v_cndmask_b32_dpp v117, v57, v53, vcc row_ror:8 row_mask:0xf bank_mask:0xf bound_ctrl:1
	s_add_u32 s100, s28, 0x80000
	s_addc_u32 s101, s29, 0
	global_store_dwordx4 v186, v[142:145], s[100:101]
	global_store_dwordx4 v187, v[138:141], s[100:101]
	global_store_dwordx4 v186, v[118:121], s[100:101] offset:512
	global_store_dwordx4 v187, v[114:117], s[100:101] offset:512
	s_waitcnt vmcnt(20)
; template <int CTRL> DEVI float dpp(float x) { return __builtin_bit_cast(float, __builtin_amdgcn_mov_dpp(__builtin_bit_cast(int, x), CTRL, 0xf, 0xf, true)); }
;     DEVI void operator()(AccRef acc, const pg8::Unit& u, int wr, int wc, int fr, int fq) const {
;     ...
;         for (int ai = 0; ai < 2; ++ai) {
;             asm volatile("" : "+v"(o), "+v"(os));
;             f32x4 b[4][2][2];
; #pragma unroll
;             for (int m = 0; m < 4; ++m)
; #pragma unroll
;                 for (int bj = 0; bj < 2; ++bj)
; #pragma unroll
;                     for (int n = 0; n < 2; ++n) b[m][bj][n] = *(const f32x4*)((const char*)base + o + (unsigned)(m * 16 * DM * 4 + bj * 512 + n * 64));
; #pragma unroll
;             for (int m = 0; m < 4; ++m)
; #pragma unroll
;                 for (int bj = 0; bj < 2; ++bj) { const f32x4 d0 = b[m][bj][0] + alpha * acc[ai][bj][m][0], d1 = b[m][bj][1] + alpha * acc[ai][bj][m][1];
;                     f32x4 t0, t1;
; #pragma unroll
;                     for (int i = 0; i < 4; ++i) { t0[i] = dpp<0x128>(d0[i]); t1[i] = dpp<0x128>(d1[i]); }
;                     const f32x4 sa = lo ? d0 : t1, sb = lo ? t0 : d1;
;                     const unsigned oo = os + (unsigned)(m * 16 * DM * 4 + bj * 512);
;                     *(f32x4*)((char*)out + oo) = sa; *(f32x4*)((char*)out + oo + 8u * DM * 4u) = sb; }
;             o += 128u * DM * 4u; os += 128u * DM * 4u; }
;     }
	v_pk_add_f32 v[46:47], v[46:47], v[110:111]
	v_pk_add_f32 v[48:49], v[48:49], v[112:113]
	v_pk_add_f32 v[42:43], v[42:43], v[106:107]
	v_pk_add_f32 v[44:45], v[44:45], v[108:109]
	v_pk_add_f32 v[38:39], v[38:39], v[102:103]
	v_pk_add_f32 v[40:41], v[40:41], v[104:105]
	v_pk_add_f32 v[34:35], v[34:35], v[98:99]
	v_pk_add_f32 v[36:37], v[36:37], v[100:101]
	s_mov_b64 vcc, s[4:5]
	v_cndmask_b32_dpp v110, v42, v46, vcc row_ror:8 row_mask:0xf bank_mask:0xf bound_ctrl:1
	v_cndmask_b32_dpp v111, v43, v47, vcc row_ror:8 row_mask:0xf bank_mask:0xf bound_ctrl:1
	v_cndmask_b32_dpp v112, v44, v48, vcc row_ror:8 row_mask:0xf bank_mask:0xf bound_ctrl:1
	v_cndmask_b32_dpp v113, v45, v49, vcc row_ror:8 row_mask:0xf bank_mask:0xf bound_ctrl:1
	v_cndmask_b32_dpp v102, v34, v38, vcc row_ror:8 row_mask:0xf bank_mask:0xf bound_ctrl:1
	v_cndmask_b32_dpp v103, v35, v39, vcc row_ror:8 row_mask:0xf bank_mask:0xf bound_ctrl:1
	v_cndmask_b32_dpp v104, v36, v40, vcc row_ror:8 row_mask:0xf bank_mask:0xf bound_ctrl:1
	v_cndmask_b32_dpp v105, v37, v41, vcc row_ror:8 row_mask:0xf bank_mask:0xf bound_ctrl:1
	s_not_b64 vcc, s[4:5]
	v_cndmask_b32_dpp v106, v46, v42, vcc row_ror:8 row_mask:0xf bank_mask:0xf bound_ctrl:1
	v_cndmask_b32_dpp v107, v47, v43, vcc row_ror:8 row_mask:0xf bank_mask:0xf bound_ctrl:1
	v_cndmask_b32_dpp v108, v48, v44, vcc row_ror:8 row_mask:0xf bank_mask:0xf bound_ctrl:1
	v_cndmask_b32_dpp v109, v49, v45, vcc row_ror:8 row_mask:0xf bank_mask:0xf bound_ctrl:1
	v_cndmask_b32_dpp v98, v38, v34, vcc row_ror:8 row_mask:0xf bank_mask:0xf bound_ctrl:1
	v_cndmask_b32_dpp v99, v39, v35, vcc row_ror:8 row_mask:0xf bank_mask:0xf bound_ctrl:1
	v_cndmask_b32_dpp v100, v40, v36, vcc row_ror:8 row_mask:0xf bank_mask:0xf bound_ctrl:1
	v_cndmask_b32_dpp v101, v41, v37, vcc row_ror:8 row_mask:0xf bank_mask:0xf bound_ctrl:1
	s_add_u32 s100, s28, 0x90000
	s_addc_u32 s101, s29, 0
	global_store_dwordx4 v186, v[110:113], s[100:101]
	global_store_dwordx4 v187, v[106:109], s[100:101]
	global_store_dwordx4 v186, v[102:105], s[100:101] offset:512
	global_store_dwordx4 v187, v[98:101], s[100:101] offset:512
	s_waitcnt vmcnt(16)
	v_pk_add_f32 v[30:31], v[30:31], v[94:95]
	v_pk_add_f32 v[32:33], v[32:33], v[96:97]
	v_pk_add_f32 v[26:27], v[26:27], v[90:91]
	v_pk_add_f32 v[28:29], v[28:29], v[92:93]
	v_pk_add_f32 v[22:23], v[22:23], v[86:87]
	v_pk_add_f32 v[24:25], v[24:25], v[88:89]
	v_pk_add_f32 v[18:19], v[18:19], v[82:83]
	v_pk_add_f32 v[20:21], v[20:21], v[84:85]
	s_mov_b64 vcc, s[4:5]
	v_cndmask_b32_dpp v94, v26, v30, vcc row_ror:8 row_mask:0xf bank_mask:0xf bound_ctrl:1
	v_cndmask_b32_dpp v95, v27, v31, vcc row_ror:8 row_mask:0xf bank_mask:0xf bound_ctrl:1
	v_cndmask_b32_dpp v96, v28, v32, vcc row_ror:8 row_mask:0xf bank_mask:0xf bound_ctrl:1
	v_cndmask_b32_dpp v97, v29, v33, vcc row_ror:8 row_mask:0xf bank_mask:0xf bound_ctrl:1
	v_cndmask_b32_dpp v86, v18, v22, vcc row_ror:8 row_mask:0xf bank_mask:0xf bound_ctrl:1
	v_cndmask_b32_dpp v87, v19, v23, vcc row_ror:8 row_mask:0xf bank_mask:0xf bound_ctrl:1
	v_cndmask_b32_dpp v88, v20, v24, vcc row_ror:8 row_mask:0xf bank_mask:0xf bound_ctrl:1
	v_cndmask_b32_dpp v89, v21, v25, vcc row_ror:8 row_mask:0xf bank_mask:0xf bound_ctrl:1
	s_not_b64 vcc, s[4:5]
	v_cndmask_b32_dpp v90, v30, v26, vcc row_ror:8 row_mask:0xf bank_mask:0xf bound_ctrl:1
	v_cndmask_b32_dpp v91, v31, v27, vcc row_ror:8 row_mask:0xf bank_mask:0xf bound_ctrl:1
	v_cndmask_b32_dpp v92, v32, v28, vcc row_ror:8 row_mask:0xf bank_mask:0xf bound_ctrl:1
	v_cndmask_b32_dpp v93, v33, v29, vcc row_ror:8 row_mask:0xf bank_mask:0xf bound_ctrl:1
	v_cndmask_b32_dpp v82, v22, v18, vcc row_ror:8 row_mask:0xf bank_mask:0xf bound_ctrl:1
	v_cndmask_b32_dpp v83, v23, v19, vcc row_ror:8 row_mask:0xf bank_mask:0xf bound_ctrl:1
	v_cndmask_b32_dpp v84, v24, v20, vcc row_ror:8 row_mask:0xf bank_mask:0xf bound_ctrl:1
	v_cndmask_b32_dpp v85, v25, v21, vcc row_ror:8 row_mask:0xf bank_mask:0xf bound_ctrl:1
	s_add_u32 s100, s28, 0xa0000
	s_addc_u32 s101, s29, 0
	global_store_dwordx4 v186, v[94:97], s[100:101]
	global_store_dwordx4 v187, v[90:93], s[100:101]
	global_store_dwordx4 v186, v[86:89], s[100:101] offset:512
	global_store_dwordx4 v187, v[82:85], s[100:101] offset:512
	s_waitcnt vmcnt(12)
	v_pk_add_f32 v[14:15], v[14:15], v[78:79]
	v_pk_add_f32 v[16:17], v[16:17], v[80:81]
	v_pk_add_f32 v[10:11], v[10:11], v[74:75]
	v_pk_add_f32 v[12:13], v[12:13], v[76:77]
	v_pk_add_f32 v[6:7], v[6:7], v[70:71]
	v_pk_add_f32 v[8:9], v[8:9], v[72:73]
	v_pk_add_f32 v[2:3], v[2:3], v[66:67]
	v_pk_add_f32 v[4:5], v[4:5], v[68:69]
	s_mov_b64 vcc, s[4:5]
	v_cndmask_b32_dpp v78, v10, v14, vcc row_ror:8 row_mask:0xf bank_mask:0xf bound_ctrl:1
	v_cndmask_b32_dpp v79, v11, v15, vcc row_ror:8 row_mask:0xf bank_mask:0xf bound_ctrl:1
	v_cndmask_b32_dpp v80, v12, v16, vcc row_ror:8 row_mask:0xf bank_mask:0xf bound_ctrl:1
	v_cndmask_b32_dpp v81, v13, v17, vcc row_ror:8 row_mask:0xf bank_mask:0xf bound_ctrl:1
	v_cndmask_b32_dpp v70, v2, v6, vcc row_ror:8 row_mask:0xf bank_mask:0xf bound_ctrl:1
	v_cndmask_b32_dpp v71, v3, v7, vcc row_ror:8 row_mask:0xf bank_mask:0xf bound_ctrl:1
	v_cndmask_b32_dpp v72, v4, v8, vcc row_ror:8 row_mask:0xf bank_mask:0xf bound_ctrl:1
	v_cndmask_b32_dpp v73, v5, v9, vcc row_ror:8 row_mask:0xf bank_mask:0xf bound_ctrl:1
	s_not_b64 vcc, s[4:5]
	v_cndmask_b32_dpp v74, v14, v10, vcc row_ror:8 row_mask:0xf bank_mask:0xf bound_ctrl:1
	v_cndmask_b32_dpp v75, v15, v11, vcc row_ror:8 row_mask:0xf bank_mask:0xf bound_ctrl:1
	v_cndmask_b32_dpp v76, v16, v12, vcc row_ror:8 row_mask:0xf bank_mask:0xf bound_ctrl:1
	v_cndmask_b32_dpp v77, v17, v13, vcc row_ror:8 row_mask:0xf bank_mask:0xf bound_ctrl:1
	v_cndmask_b32_dpp v66, v6, v2, vcc row_ror:8 row_mask:0xf bank_mask:0xf bound_ctrl:1
	v_cndmask_b32_dpp v67, v7, v3, vcc row_ror:8 row_mask:0xf bank_mask:0xf bound_ctrl:1
	v_cndmask_b32_dpp v68, v8, v4, vcc row_ror:8 row_mask:0xf bank_mask:0xf bound_ctrl:1
	v_cndmask_b32_dpp v69, v9, v5, vcc row_ror:8 row_mask:0xf bank_mask:0xf bound_ctrl:1
	s_add_u32 s100, s28, 0xb0000
	s_addc_u32 s101, s29, 0
	global_store_dwordx4 v186, v[78:81], s[100:101]
	global_store_dwordx4 v187, v[74:77], s[100:101]
	global_store_dwordx4 v186, v[70:73], s[100:101] offset:512
	global_store_dwordx4 v187, v[66:69], s[100:101] offset:512
	s_and_b64 vcc, exec, s[6:7]
	s_cbranch_vccz .LBB0_35
	s_waitcnt vmcnt(0)
	s_cmpk_gt_u32 s13, 0xff
	s_cbranch_scc1 .LBB0_46
	s_barrier

.LBB0_63:
	s_add_i32 s96, s96, 2
	s_cmp_gt_u32 s96, 15
	s_cselect_b32 s97, 0x13fff800, 0
	s_cmp_gt_u32 s96, 13
	s_cselect_b32 s86, 0x13fff800, 0
	s_add_u32 s86, s86, s84
	s_addc_u32 s87, 0, s85
	s_add_u32 s86, s82, s86
	s_addc_u32 s87, s83, s87
	s_add_u32 s86, s86, 0x100
	s_addc_u32 s87, s87, 0
	s_add_u32 vcc_lo, s94, s84
	s_addc_u32 vcc_hi, s95, s85
	s_add_i32 s13, 0, 0x10000
	v_add_u32_e32 v0, s13, v202
	ds_read_b128 v[132:135], v0
	ds_read_b128 v[136:139], v0 offset:1024
	ds_read_b128 v[140:143], v0 offset:2048
	ds_read_b128 v[144:147], v0 offset:3072
	s_cmpk_eq_i32 s84, 0xf00
	s_cselect_b32 s89, s25, s87
	s_cselect_b32 s88, s92, s86
	s_cselect_b32 s87, s23, vcc_hi
	s_cselect_b32 s86, s93, vcc_lo
	s_add_u32 vcc_lo, s97, s84
	s_addc_u32 vcc_hi, 0, s85
	v_lshl_add_u64 v[2:3], v[200:201], 0, vcc
	s_add_i32 m0, s59, 0xc000
	ds_read_b128 v[148:151], v204
	ds_read_b128 v[152:155], v204 offset:1024
	ds_read_b128 v[156:159], v204 offset:2048
	ds_read_b128 v[160:163], v204 offset:3072
	ds_read_b128 v[164:167], v204 offset:4096
	ds_read_b128 v[168:171], v204 offset:5120
	ds_read_b128 v[172:175], v204 offset:6144
	ds_read_b128 v[176:179], v204 offset:7168
	global_load_lds_dwordx4 v[2:3], off
	v_lshl_add_u64 v[2:3], v[194:195], 0, vcc
	s_add_i32 m0, s59, 0xe000
	s_nop 0
	global_load_lds_dwordx4 v[2:3], off
	s_waitcnt lgkmcnt(8)
	s_barrier
	s_waitcnt lgkmcnt(0)
	s_setprio 1
	s_waitcnt lgkmcnt(0)
	v_mfma_f32_16x16x32_bf16 v[128:131], v[132:135], v[148:151], v[128:131]
	v_mfma_f32_16x16x32_bf16 v[124:127], v[140:143], v[148:151], v[124:127]
	v_mfma_f32_16x16x32_bf16 v[112:115], v[132:135], v[156:159], v[112:115]
	v_mfma_f32_16x16x32_bf16 v[108:111], v[140:143], v[156:159], v[108:111]
	v_mfma_f32_16x16x32_bf16 v[96:99], v[132:135], v[164:167], v[96:99]
	v_mfma_f32_16x16x32_bf16 v[92:95], v[140:143], v[164:167], v[92:95]
	v_mfma_f32_16x16x32_bf16 v[80:83], v[132:135], v[172:175], v[80:83]
	v_mfma_f32_16x16x32_bf16 v[76:79], v[140:143], v[172:175], v[76:79]
	v_mfma_f32_16x16x32_bf16 v[128:131], v[136:139], v[152:155], v[128:131]
	v_mfma_f32_16x16x32_bf16 v[124:127], v[144:147], v[152:155], v[124:127]
	v_mfma_f32_16x16x32_bf16 v[112:115], v[136:139], v[160:163], v[112:115]
	v_mfma_f32_16x16x32_bf16 v[108:111], v[144:147], v[160:163], v[108:111]
	v_mfma_f32_16x16x32_bf16 v[96:99], v[136:139], v[168:171], v[96:99]
	v_mfma_f32_16x16x32_bf16 v[92:95], v[144:147], v[168:171], v[92:95]
	v_mfma_f32_16x16x32_bf16 v[80:83], v[136:139], v[176:179], v[80:83]
	v_mfma_f32_16x16x32_bf16 v[76:79], v[144:147], v[176:179], v[76:79]
	s_setprio 0
	s_barrier
	s_add_i32 s97, 0, 0x14000
	s_add_i32 s13, s13, s46
	v_add_u32_e32 v0, s97, v202
	v_lshl_add_u64 v[214:215], s[86:87], 0, v[184:185]
	s_mov_b32 m0, s13
	ds_read_b128 v[196:199], v0
	ds_read_b128 v[206:209], v0 offset:1024
	ds_read_b128 v[210:213], v0 offset:2048
	ds_read_b128 v[218:221], v0 offset:3072
	global_load_lds_dwordx4 v[214:215], off
	v_lshl_add_u64 v[222:223], s[86:87], 0, v[180:181]
	s_add_i32 m0, s13, 0x2000
	s_nop 0
	global_load_lds_dwordx4 v[222:223], off
	s_waitcnt vmcnt(10)
	s_barrier
	s_waitcnt lgkmcnt(0)
	s_setprio 1
	s_waitcnt lgkmcnt(0)
	v_mfma_f32_16x16x32_bf16 v[120:123], v[196:199], v[148:151], v[120:123]
	v_mfma_f32_16x16x32_bf16 v[116:119], v[210:213], v[148:151], v[116:119]
	v_mfma_f32_16x16x32_bf16 v[104:107], v[196:199], v[156:159], v[104:107]
	v_mfma_f32_16x16x32_bf16 v[100:103], v[210:213], v[156:159], v[100:103]
	v_mfma_f32_16x16x32_bf16 v[88:91], v[196:199], v[164:167], v[88:91]
	v_mfma_f32_16x16x32_bf16 v[84:87], v[210:213], v[164:167], v[84:87]
	v_mfma_f32_16x16x32_bf16 v[72:75], v[196:199], v[172:175], v[72:75]
	v_mfma_f32_16x16x32_bf16 v[68:71], v[210:213], v[172:175], v[68:71]
	v_mfma_f32_16x16x32_bf16 v[120:123], v[206:209], v[152:155], v[120:123]
	v_mfma_f32_16x16x32_bf16 v[116:119], v[218:221], v[152:155], v[116:119]
	v_mfma_f32_16x16x32_bf16 v[104:107], v[206:209], v[160:163], v[104:107]
	v_mfma_f32_16x16x32_bf16 v[100:103], v[218:221], v[160:163], v[100:103]
	v_mfma_f32_16x16x32_bf16 v[88:91], v[206:209], v[168:171], v[88:91]
	v_mfma_f32_16x16x32_bf16 v[84:87], v[218:221], v[168:171], v[84:87]
	v_mfma_f32_16x16x32_bf16 v[72:75], v[206:209], v[176:179], v[72:75]
	v_mfma_f32_16x16x32_bf16 v[68:71], v[218:221], v[176:179], v[68:71]
	s_setprio 0
	s_mov_b32 m0, s59
	v_lshl_add_u64 v[224:225], s[88:89], 0, v[186:187]
	s_barrier
	ds_read_b128 v[148:151], v204 offset:16384
	ds_read_b128 v[152:155], v204 offset:17408
	ds_read_b128 v[156:159], v204 offset:18432
	ds_read_b128 v[160:163], v204 offset:19456
	ds_read_b128 v[164:167], v204 offset:20480
	ds_read_b128 v[168:171], v204 offset:21504
	ds_read_b128 v[172:175], v204 offset:22528
	ds_read_b128 v[176:179], v204 offset:23552
	global_load_lds_dwordx4 v[224:225], off
	v_lshl_add_u64 v[226:227], s[88:89], 0, v[182:183]
	s_mov_b32 m0, s60
	s_nop 0
	global_load_lds_dwordx4 v[226:227], off
	s_barrier
	s_waitcnt lgkmcnt(0)
	s_setprio 1
	s_waitcnt lgkmcnt(0)
	v_mfma_f32_16x16x32_bf16 v[64:67], v[132:135], v[148:151], v[64:67]
	v_mfma_f32_16x16x32_bf16 v[60:63], v[140:143], v[148:151], v[60:63]
	v_mfma_f32_16x16x32_bf16 v[48:51], v[132:135], v[156:159], v[48:51]
	v_mfma_f32_16x16x32_bf16 v[44:47], v[140:143], v[156:159], v[44:47]
	v_mfma_f32_16x16x32_bf16 v[32:35], v[132:135], v[164:167], v[32:35]
	v_mfma_f32_16x16x32_bf16 v[28:31], v[140:143], v[164:167], v[28:31]
	v_mfma_f32_16x16x32_bf16 v[16:19], v[132:135], v[172:175], v[16:19]
	v_mfma_f32_16x16x32_bf16 v[12:15], v[140:143], v[172:175], v[12:15]
	v_mfma_f32_16x16x32_bf16 v[64:67], v[136:139], v[152:155], v[64:67]
	v_mfma_f32_16x16x32_bf16 v[60:63], v[144:147], v[152:155], v[60:63]
	v_mfma_f32_16x16x32_bf16 v[48:51], v[136:139], v[160:163], v[48:51]
	v_mfma_f32_16x16x32_bf16 v[44:47], v[144:147], v[160:163], v[44:47]
	v_mfma_f32_16x16x32_bf16 v[32:35], v[136:139], v[168:171], v[32:35]
	v_mfma_f32_16x16x32_bf16 v[28:31], v[144:147], v[168:171], v[28:31]
	v_mfma_f32_16x16x32_bf16 v[16:19], v[136:139], v[176:179], v[16:19]
	v_mfma_f32_16x16x32_bf16 v[12:15], v[144:147], v[176:179], v[12:15]
	s_setprio 0
	s_barrier
	s_add_u32 vcc_lo, s86, 0x80000
	s_addc_u32 vcc_hi, s87, 0
	s_add_i32 s13, s97, s46
	v_lshl_add_u64 v[2:3], vcc, 0, v[184:185]
	s_mov_b32 m0, s13
	s_nop 0
	global_load_lds_dwordx4 v[2:3], off
	v_lshl_add_u64 v[2:3], vcc, 0, v[180:181]
	s_add_i32 m0, s13, 0x2000
	s_nop 0
	global_load_lds_dwordx4 v[2:3], off
	s_waitcnt vmcnt(8)
	s_barrier
	s_setprio 1
	v_mfma_f32_16x16x32_bf16 v[56:59], v[196:199], v[148:151], v[56:59]
	v_mfma_f32_16x16x32_bf16 v[52:55], v[210:213], v[148:151], v[52:55]
	v_mfma_f32_16x16x32_bf16 v[40:43], v[196:199], v[156:159], v[40:43]
	v_mfma_f32_16x16x32_bf16 v[36:39], v[210:213], v[156:159], v[36:39]
	v_mfma_f32_16x16x32_bf16 v[24:27], v[196:199], v[164:167], v[24:27]
	v_mfma_f32_16x16x32_bf16 v[20:23], v[210:213], v[164:167], v[20:23]
	v_mfma_f32_16x16x32_bf16 v[8:11], v[196:199], v[172:175], v[8:11]
	v_mfma_f32_16x16x32_bf16 v[2:5], v[210:213], v[172:175], v[4:7]
	v_mfma_f32_16x16x32_bf16 v[56:59], v[206:209], v[152:155], v[56:59]
	v_mfma_f32_16x16x32_bf16 v[52:55], v[218:221], v[152:155], v[52:55]
	v_mfma_f32_16x16x32_bf16 v[40:43], v[206:209], v[160:163], v[40:43]
	v_mfma_f32_16x16x32_bf16 v[36:39], v[218:221], v[160:163], v[36:39]
	v_mfma_f32_16x16x32_bf16 v[24:27], v[206:209], v[168:171], v[24:27]
	v_mfma_f32_16x16x32_bf16 v[20:23], v[218:221], v[168:171], v[20:23]
	v_mfma_f32_16x16x32_bf16 v[8:11], v[206:209], v[176:179], v[8:11]
	v_mfma_f32_16x16x32_bf16 v[2:5], v[218:221], v[176:179], v[2:5]
	s_setprio 0
	s_add_i32 s13, 0, 0x18000
	v_add_u32_e32 v0, s13, v202
	s_barrier
	ds_read_b128 v[132:135], v0
	ds_read_b128 v[136:139], v0 offset:1024
	ds_read_b128 v[140:143], v0 offset:2048
	ds_read_b128 v[144:147], v0 offset:3072
	s_add_u32 s88, s88, 0x40000
	s_addc_u32 s89, s89, 0
	s_mov_b32 m0, s61
	v_lshl_add_u64 v[6:7], s[88:89], 0, v[186:187]
	ds_read_b128 v[148:151], v204 offset:32768
	ds_read_b128 v[152:155], v204 offset:33792
	ds_read_b128 v[156:159], v204 offset:34816
	ds_read_b128 v[160:163], v204 offset:35840
	ds_read_b128 v[164:167], v204 offset:36864
	ds_read_b128 v[168:171], v204 offset:37888
	ds_read_b128 v[172:175], v204 offset:38912
	ds_read_b128 v[176:179], v204 offset:39936
	global_load_lds_dwordx4 v[6:7], off
	v_lshl_add_u64 v[6:7], s[88:89], 0, v[182:183]
	s_mov_b32 m0, s76
	s_nop 0
	global_load_lds_dwordx4 v[6:7], off
	s_waitcnt lgkmcnt(8)
	s_barrier
	s_waitcnt lgkmcnt(0)
	s_setprio 1
	s_waitcnt lgkmcnt(0)
	v_mfma_f32_16x16x32_bf16 v[128:131], v[132:135], v[148:151], v[128:131]
	v_mfma_f32_16x16x32_bf16 v[124:127], v[140:143], v[148:151], v[124:127]
	v_mfma_f32_16x16x32_bf16 v[112:115], v[132:135], v[156:159], v[112:115]
	v_mfma_f32_16x16x32_bf16 v[108:111], v[140:143], v[156:159], v[108:111]
	v_mfma_f32_16x16x32_bf16 v[96:99], v[132:135], v[164:167], v[96:99]
	v_mfma_f32_16x16x32_bf16 v[92:95], v[140:143], v[164:167], v[92:95]
	v_mfma_f32_16x16x32_bf16 v[80:83], v[132:135], v[172:175], v[80:83]
	v_mfma_f32_16x16x32_bf16 v[76:79], v[140:143], v[172:175], v[76:79]
	v_mfma_f32_16x16x32_bf16 v[128:131], v[136:139], v[152:155], v[128:131]
	v_mfma_f32_16x16x32_bf16 v[124:127], v[144:147], v[152:155], v[124:127]
	v_mfma_f32_16x16x32_bf16 v[112:115], v[136:139], v[160:163], v[112:115]
	v_mfma_f32_16x16x32_bf16 v[108:111], v[144:147], v[160:163], v[108:111]
	v_mfma_f32_16x16x32_bf16 v[96:99], v[136:139], v[168:171], v[96:99]
	v_mfma_f32_16x16x32_bf16 v[92:95], v[144:147], v[168:171], v[92:95]
	v_mfma_f32_16x16x32_bf16 v[80:83], v[136:139], v[176:179], v[80:83]
	v_mfma_f32_16x16x32_bf16 v[76:79], v[144:147], v[176:179], v[76:79]
	s_setprio 0
	s_barrier
	s_add_i32 s88, 0, 0x1c000
	s_add_i32 s13, s13, s46
	v_add_u32_e32 v0, s88, v202
	v_lshl_add_u64 v[6:7], v[214:215], 0, s[48:49]
	s_mov_b32 m0, s13
	ds_read_b128 v[196:199], v0
	ds_read_b128 v[206:209], v0 offset:1024
	ds_read_b128 v[210:213], v0 offset:2048
	ds_read_b128 v[218:221], v0 offset:3072
	global_load_lds_dwordx4 v[6:7], off
	v_lshl_add_u64 v[6:7], v[222:223], 0, s[48:49]
	s_add_i32 m0, s13, 0x2000
	s_nop 0
	global_load_lds_dwordx4 v[6:7], off
	s_waitcnt vmcnt(10)
	s_barrier
	s_waitcnt lgkmcnt(0)
	s_setprio 1
	s_waitcnt lgkmcnt(0)
	v_mfma_f32_16x16x32_bf16 v[120:123], v[196:199], v[148:151], v[120:123]
	v_mfma_f32_16x16x32_bf16 v[116:119], v[210:213], v[148:151], v[116:119]
	v_mfma_f32_16x16x32_bf16 v[104:107], v[196:199], v[156:159], v[104:107]
	v_mfma_f32_16x16x32_bf16 v[100:103], v[210:213], v[156:159], v[100:103]
	v_mfma_f32_16x16x32_bf16 v[88:91], v[196:199], v[164:167], v[88:91]
	v_mfma_f32_16x16x32_bf16 v[84:87], v[210:213], v[164:167], v[84:87]
	v_mfma_f32_16x16x32_bf16 v[72:75], v[196:199], v[172:175], v[72:75]
	v_mfma_f32_16x16x32_bf16 v[68:71], v[210:213], v[172:175], v[68:71]
	v_mfma_f32_16x16x32_bf16 v[120:123], v[206:209], v[152:155], v[120:123]
	v_mfma_f32_16x16x32_bf16 v[116:119], v[218:221], v[152:155], v[116:119]
	v_mfma_f32_16x16x32_bf16 v[104:107], v[206:209], v[160:163], v[104:107]
	v_mfma_f32_16x16x32_bf16 v[100:103], v[218:221], v[160:163], v[100:103]
	v_mfma_f32_16x16x32_bf16 v[88:91], v[206:209], v[168:171], v[88:91]
	v_mfma_f32_16x16x32_bf16 v[84:87], v[218:221], v[168:171], v[84:87]
	v_mfma_f32_16x16x32_bf16 v[72:75], v[206:209], v[176:179], v[72:75]
	v_mfma_f32_16x16x32_bf16 v[68:71], v[218:221], v[176:179], v[68:71]
	s_setprio 0
	s_mov_b32 m0, s77
	v_lshl_add_u64 v[6:7], v[224:225], 0, s[48:49]
	s_barrier
	ds_read_b128 v[148:151], v204 offset:49152
	ds_read_b128 v[152:155], v204 offset:50176
	ds_read_b128 v[156:159], v204 offset:51200
	ds_read_b128 v[160:163], v204 offset:52224
	ds_read_b128 v[164:167], v204 offset:53248
	ds_read_b128 v[168:171], v204 offset:54272
	ds_read_b128 v[172:175], v204 offset:55296
	ds_read_b128 v[176:179], v204 offset:56320
	global_load_lds_dwordx4 v[6:7], off
	v_lshl_add_u64 v[6:7], v[226:227], 0, s[48:49]
	s_mov_b32 m0, s90
	s_nop 0
	global_load_lds_dwordx4 v[6:7], off
	s_barrier
	s_waitcnt lgkmcnt(0)
	s_setprio 1
	s_waitcnt lgkmcnt(0)
	v_mfma_f32_16x16x32_bf16 v[64:67], v[132:135], v[148:151], v[64:67]
	v_mfma_f32_16x16x32_bf16 v[60:63], v[140:143], v[148:151], v[60:63]
	v_mfma_f32_16x16x32_bf16 v[48:51], v[132:135], v[156:159], v[48:51]
	v_mfma_f32_16x16x32_bf16 v[44:47], v[140:143], v[156:159], v[44:47]
	v_mfma_f32_16x16x32_bf16 v[32:35], v[132:135], v[164:167], v[32:35]
	v_mfma_f32_16x16x32_bf16 v[28:31], v[140:143], v[164:167], v[28:31]
	v_mfma_f32_16x16x32_bf16 v[16:19], v[132:135], v[172:175], v[16:19]
	v_mfma_f32_16x16x32_bf16 v[12:15], v[140:143], v[172:175], v[12:15]
	v_mfma_f32_16x16x32_bf16 v[64:67], v[136:139], v[152:155], v[64:67]
	v_mfma_f32_16x16x32_bf16 v[60:63], v[144:147], v[152:155], v[60:63]
	v_mfma_f32_16x16x32_bf16 v[48:51], v[136:139], v[160:163], v[48:51]
	v_mfma_f32_16x16x32_bf16 v[44:47], v[144:147], v[160:163], v[44:47]
	v_mfma_f32_16x16x32_bf16 v[32:35], v[136:139], v[168:171], v[32:35]
	v_mfma_f32_16x16x32_bf16 v[28:31], v[144:147], v[168:171], v[28:31]
	v_mfma_f32_16x16x32_bf16 v[16:19], v[136:139], v[176:179], v[16:19]
	v_mfma_f32_16x16x32_bf16 v[12:15], v[144:147], v[176:179], v[12:15]
	s_setprio 0
	s_barrier
	s_add_u32 s86, s86, 0x80080
	s_addc_u32 s87, s87, 0
	s_add_i32 s13, s88, s46
	v_lshl_add_u64 v[6:7], s[86:87], 0, v[184:185]
	s_mov_b32 m0, s13
	s_nop 0
	global_load_lds_dwordx4 v[6:7], off
	v_lshl_add_u64 v[6:7], s[86:87], 0, v[180:181]
	s_add_i32 m0, s13, 0x2000
	s_nop 0
	global_load_lds_dwordx4 v[6:7], off
	s_waitcnt vmcnt(8)
	s_barrier
	s_setprio 1
	v_mfma_f32_16x16x32_bf16 v[56:59], v[196:199], v[148:151], v[56:59]
	v_mfma_f32_16x16x32_bf16 v[52:55], v[210:213], v[148:151], v[52:55]
	v_mfma_f32_16x16x32_bf16 v[40:43], v[196:199], v[156:159], v[40:43]
	v_mfma_f32_16x16x32_bf16 v[36:39], v[210:213], v[156:159], v[36:39]
	v_mfma_f32_16x16x32_bf16 v[24:27], v[196:199], v[164:167], v[24:27]
	v_mfma_f32_16x16x32_bf16 v[20:23], v[210:213], v[164:167], v[20:23]
	v_mfma_f32_16x16x32_bf16 v[6:9], v[196:199], v[172:175], v[8:11]
	v_mfma_f32_16x16x32_bf16 v[2:5], v[210:213], v[172:175], v[2:5]
	v_mfma_f32_16x16x32_bf16 v[56:59], v[206:209], v[152:155], v[56:59]
	v_mfma_f32_16x16x32_bf16 v[52:55], v[218:221], v[152:155], v[52:55]
	v_mfma_f32_16x16x32_bf16 v[40:43], v[206:209], v[160:163], v[40:43]
	v_mfma_f32_16x16x32_bf16 v[36:39], v[218:221], v[160:163], v[36:39]
	v_mfma_f32_16x16x32_bf16 v[24:27], v[206:209], v[168:171], v[24:27]
	v_mfma_f32_16x16x32_bf16 v[20:23], v[218:221], v[168:171], v[20:23]
	v_mfma_f32_16x16x32_bf16 v[8:11], v[206:209], v[176:179], v[6:9]
	v_mfma_f32_16x16x32_bf16 v[4:7], v[218:221], v[176:179], v[2:5]
	s_setprio 0
	s_add_u32 s84, s84, 0x100
	s_addc_u32 s85, 0, s85
	s_cmp_gt_u32 s96, 29
	s_barrier
	s_cbranch_scc1 .LBB0_55

.LBB0_409:
	s_add_u32 s8, s84, 0xfffc0080
	s_addc_u32 s9, s85, -1
	s_add_i32 s10, 0, 0x10000
	v_add_u32_e32 v0, s10, v159
	ds_read_b128 v[142:145], v0
	ds_read_b128 v[146:149], v0 offset:1024
	ds_read_b128 v[150:153], v0 offset:2048
	ds_read_b128 v[154:157], v0 offset:3072
	s_cmp_eq_u32 s46, 12
	s_cselect_b32 s89, s23, s9
	s_cselect_b32 s88, s60, s8
	s_cselect_b32 s87, s21, vcc_hi
	s_cselect_b32 s86, s61, vcc_lo
	v_lshl_add_u64 v[196:197], s[84:85], 0, v[140:141]
	s_add_i32 m0, s25, 0xc000
	ds_read_b128 v[180:183], v177
	ds_read_b128 v[184:187], v177 offset:1024
	ds_read_b128 v[188:191], v177 offset:2048
	ds_read_b128 v[192:195], v177 offset:3072
	ds_read_b128 v[200:203], v177 offset:4096
	ds_read_b128 v[204:207], v177 offset:5120
	ds_read_b128 v[208:211], v177 offset:6144
	ds_read_b128 v[212:215], v177 offset:7168
	global_load_lds_dwordx4 v[196:197], off
	v_lshl_add_u64 v[196:197], s[84:85], 0, v[138:139]
	s_add_i32 m0, s25, 0xe000
	s_nop 0
	global_load_lds_dwordx4 v[196:197], off
	s_waitcnt lgkmcnt(8)
	s_barrier
	s_waitcnt lgkmcnt(0)
	s_setprio 1
	s_waitcnt lgkmcnt(0)
	v_mfma_f32_16x16x32_bf16 v[126:129], v[142:145], v[180:183], v[126:129]
	v_mfma_f32_16x16x32_bf16 v[118:121], v[150:153], v[180:183], v[118:121]
	v_mfma_f32_16x16x32_bf16 v[122:125], v[142:145], v[188:191], v[122:125]
	v_mfma_f32_16x16x32_bf16 v[110:113], v[150:153], v[188:191], v[110:113]
	v_mfma_f32_16x16x32_bf16 v[114:117], v[142:145], v[200:203], v[114:117]
	v_mfma_f32_16x16x32_bf16 v[102:105], v[150:153], v[200:203], v[102:105]
	v_mfma_f32_16x16x32_bf16 v[106:109], v[142:145], v[208:211], v[106:109]
	v_mfma_f32_16x16x32_bf16 v[98:101], v[150:153], v[208:211], v[98:101]
	v_mfma_f32_16x16x32_bf16 v[126:129], v[146:149], v[184:187], v[126:129]
	v_mfma_f32_16x16x32_bf16 v[118:121], v[154:157], v[184:187], v[118:121]
	v_mfma_f32_16x16x32_bf16 v[122:125], v[146:149], v[192:195], v[122:125]
	v_mfma_f32_16x16x32_bf16 v[110:113], v[154:157], v[192:195], v[110:113]
	v_mfma_f32_16x16x32_bf16 v[114:117], v[146:149], v[204:207], v[114:117]
	v_mfma_f32_16x16x32_bf16 v[102:105], v[154:157], v[204:207], v[102:105]
	v_mfma_f32_16x16x32_bf16 v[106:109], v[146:149], v[212:215], v[106:109]
	v_mfma_f32_16x16x32_bf16 v[98:101], v[154:157], v[212:215], v[98:101]
	s_setprio 0
	s_barrier
	s_add_i32 s11, 0, 0x14000
	s_add_i32 s8, s10, s59
	v_add_u32_e32 v0, s11, v159
	v_lshl_add_u64 v[196:197], s[86:87], 0, v[132:133]
	s_mov_b32 m0, s8
	ds_read_b128 v[218:221], v0
	ds_read_b128 v[222:225], v0 offset:1024
	ds_read_b128 v[226:229], v0 offset:2048
	ds_read_b128 v[230:233], v0 offset:3072
	global_load_lds_dwordx4 v[196:197], off
	v_lshl_add_u64 v[198:199], s[86:87], 0, v[136:137]
	s_add_i32 m0, s8, 0x2000
	s_nop 0
	global_load_lds_dwordx4 v[198:199], off
	s_waitcnt vmcnt(10)
	s_barrier
	s_waitcnt lgkmcnt(0)
	s_setprio 1
	s_waitcnt lgkmcnt(0)
	v_mfma_f32_16x16x32_bf16 v[62:65], v[218:221], v[180:183], v[62:65]
	v_mfma_f32_16x16x32_bf16 v[54:57], v[226:229], v[180:183], v[54:57]
	v_mfma_f32_16x16x32_bf16 v[58:61], v[218:221], v[188:191], v[58:61]
	v_mfma_f32_16x16x32_bf16 v[46:49], v[226:229], v[188:191], v[46:49]
	v_mfma_f32_16x16x32_bf16 v[50:53], v[218:221], v[200:203], v[50:53]
	v_mfma_f32_16x16x32_bf16 v[38:41], v[226:229], v[200:203], v[38:41]
	v_mfma_f32_16x16x32_bf16 v[42:45], v[218:221], v[208:211], v[42:45]
	v_mfma_f32_16x16x32_bf16 v[34:37], v[226:229], v[208:211], v[34:37]
	v_mfma_f32_16x16x32_bf16 v[62:65], v[222:225], v[184:187], v[62:65]
	v_mfma_f32_16x16x32_bf16 v[54:57], v[230:233], v[184:187], v[54:57]
	v_mfma_f32_16x16x32_bf16 v[58:61], v[222:225], v[192:195], v[58:61]
	v_mfma_f32_16x16x32_bf16 v[46:49], v[230:233], v[192:195], v[46:49]
	v_mfma_f32_16x16x32_bf16 v[50:53], v[222:225], v[204:207], v[50:53]
	v_mfma_f32_16x16x32_bf16 v[38:41], v[230:233], v[204:207], v[38:41]
	v_mfma_f32_16x16x32_bf16 v[42:45], v[222:225], v[212:215], v[42:45]
	v_mfma_f32_16x16x32_bf16 v[34:37], v[230:233], v[212:215], v[34:37]
	s_setprio 0
	s_mov_b32 m0, s25
	v_lshl_add_u64 v[234:235], s[88:89], 0, v[130:131]
	s_barrier
	ds_read_b128 v[180:183], v177 offset:16384
	ds_read_b128 v[184:187], v177 offset:17408
	ds_read_b128 v[188:191], v177 offset:18432
	ds_read_b128 v[192:195], v177 offset:19456
	ds_read_b128 v[200:203], v177 offset:20480
	ds_read_b128 v[204:207], v177 offset:21504
	ds_read_b128 v[208:211], v177 offset:22528
	ds_read_b128 v[212:215], v177 offset:23552
	global_load_lds_dwordx4 v[234:235], off
	v_lshl_add_u64 v[236:237], s[88:89], 0, v[134:135]
	s_mov_b32 m0, s76
	s_nop 0
	global_load_lds_dwordx4 v[236:237], off
	s_barrier
	s_waitcnt lgkmcnt(0)
	s_setprio 1
	s_waitcnt lgkmcnt(0)
	v_mfma_f32_16x16x32_bf16 v[94:97], v[142:145], v[180:183], v[94:97]
	v_mfma_f32_16x16x32_bf16 v[86:89], v[150:153], v[180:183], v[86:89]
	v_mfma_f32_16x16x32_bf16 v[90:93], v[142:145], v[188:191], v[90:93]
	v_mfma_f32_16x16x32_bf16 v[78:81], v[150:153], v[188:191], v[78:81]
	v_mfma_f32_16x16x32_bf16 v[82:85], v[142:145], v[200:203], v[82:85]
	v_mfma_f32_16x16x32_bf16 v[70:73], v[150:153], v[200:203], v[70:73]
	v_mfma_f32_16x16x32_bf16 v[74:77], v[142:145], v[208:211], v[74:77]
	v_mfma_f32_16x16x32_bf16 v[66:69], v[150:153], v[208:211], v[66:69]
	v_mfma_f32_16x16x32_bf16 v[94:97], v[146:149], v[184:187], v[94:97]
	v_mfma_f32_16x16x32_bf16 v[86:89], v[154:157], v[184:187], v[86:89]
	v_mfma_f32_16x16x32_bf16 v[90:93], v[146:149], v[192:195], v[90:93]
	v_mfma_f32_16x16x32_bf16 v[78:81], v[154:157], v[192:195], v[78:81]
	v_mfma_f32_16x16x32_bf16 v[82:85], v[146:149], v[204:207], v[82:85]
	v_mfma_f32_16x16x32_bf16 v[70:73], v[154:157], v[204:207], v[70:73]
	v_mfma_f32_16x16x32_bf16 v[74:77], v[146:149], v[212:215], v[74:77]
	v_mfma_f32_16x16x32_bf16 v[66:69], v[154:157], v[212:215], v[66:69]
	s_setprio 0
	s_barrier
	s_add_u32 s8, s86, 0x40000
	s_addc_u32 s9, s87, 0
	s_add_i32 s10, s11, s59
	v_lshl_add_u64 v[142:143], s[8:9], 0, v[132:133]
	s_mov_b32 m0, s10
	s_nop 0
	global_load_lds_dwordx4 v[142:143], off
	v_lshl_add_u64 v[142:143], s[8:9], 0, v[136:137]
	s_add_i32 m0, s10, 0x2000
	s_nop 0
	global_load_lds_dwordx4 v[142:143], off
	s_waitcnt vmcnt(8)
	s_barrier
	s_setprio 1
	v_mfma_f32_16x16x32_bf16 v[30:33], v[218:221], v[180:183], v[30:33]
	v_mfma_f32_16x16x32_bf16 v[22:25], v[226:229], v[180:183], v[22:25]
	v_mfma_f32_16x16x32_bf16 v[26:29], v[218:221], v[188:191], v[26:29]
	v_mfma_f32_16x16x32_bf16 v[14:17], v[226:229], v[188:191], v[14:17]
	v_mfma_f32_16x16x32_bf16 v[18:21], v[218:221], v[200:203], v[18:21]
	v_mfma_f32_16x16x32_bf16 v[6:9], v[226:229], v[200:203], v[6:9]
	v_mfma_f32_16x16x32_bf16 v[10:13], v[218:221], v[208:211], v[10:13]
	v_mfma_f32_16x16x32_bf16 v[2:5], v[226:229], v[208:211], v[2:5]
	v_mfma_f32_16x16x32_bf16 v[30:33], v[222:225], v[184:187], v[30:33]
	v_mfma_f32_16x16x32_bf16 v[22:25], v[230:233], v[184:187], v[22:25]
	v_mfma_f32_16x16x32_bf16 v[26:29], v[222:225], v[192:195], v[26:29]
	v_mfma_f32_16x16x32_bf16 v[14:17], v[230:233], v[192:195], v[14:17]
	v_mfma_f32_16x16x32_bf16 v[18:21], v[222:225], v[204:207], v[18:21]
	v_mfma_f32_16x16x32_bf16 v[6:9], v[230:233], v[204:207], v[6:9]
	v_mfma_f32_16x16x32_bf16 v[10:13], v[222:225], v[212:215], v[10:13]
	v_mfma_f32_16x16x32_bf16 v[2:5], v[230:233], v[212:215], v[2:5]
	s_setprio 0
	s_add_i32 s10, 0, 0x18000
	v_add_u32_e32 v0, s10, v159
	s_barrier
	ds_read_b128 v[142:145], v0
	ds_read_b128 v[146:149], v0 offset:1024
	ds_read_b128 v[150:153], v0 offset:2048
	ds_read_b128 v[154:157], v0 offset:3072
	s_add_u32 s8, s88, 0x40000
	s_addc_u32 s9, s89, 0
	s_mov_b32 m0, s79
	v_lshl_add_u64 v[218:219], s[8:9], 0, v[130:131]
	ds_read_b128 v[180:183], v177 offset:32768
	ds_read_b128 v[184:187], v177 offset:33792
	ds_read_b128 v[188:191], v177 offset:34816
	ds_read_b128 v[192:195], v177 offset:35840
	ds_read_b128 v[200:203], v177 offset:36864
	ds_read_b128 v[204:207], v177 offset:37888
	ds_read_b128 v[208:211], v177 offset:38912
	ds_read_b128 v[212:215], v177 offset:39936
	global_load_lds_dwordx4 v[218:219], off
	v_lshl_add_u64 v[218:219], s[8:9], 0, v[134:135]
	s_mov_b32 m0, s93
	s_nop 0
	global_load_lds_dwordx4 v[218:219], off
	s_waitcnt lgkmcnt(8)
	s_barrier
	s_waitcnt lgkmcnt(0)
	s_setprio 1
	s_waitcnt lgkmcnt(0)
	v_mfma_f32_16x16x32_bf16 v[126:129], v[142:145], v[180:183], v[126:129]
	v_mfma_f32_16x16x32_bf16 v[118:121], v[150:153], v[180:183], v[118:121]
	v_mfma_f32_16x16x32_bf16 v[122:125], v[142:145], v[188:191], v[122:125]
	v_mfma_f32_16x16x32_bf16 v[110:113], v[150:153], v[188:191], v[110:113]
	v_mfma_f32_16x16x32_bf16 v[114:117], v[142:145], v[200:203], v[114:117]
	v_mfma_f32_16x16x32_bf16 v[102:105], v[150:153], v[200:203], v[102:105]
	v_mfma_f32_16x16x32_bf16 v[106:109], v[142:145], v[208:211], v[106:109]
	v_mfma_f32_16x16x32_bf16 v[98:101], v[150:153], v[208:211], v[98:101]
	v_mfma_f32_16x16x32_bf16 v[126:129], v[146:149], v[184:187], v[126:129]
	v_mfma_f32_16x16x32_bf16 v[118:121], v[154:157], v[184:187], v[118:121]
	v_mfma_f32_16x16x32_bf16 v[122:125], v[146:149], v[192:195], v[122:125]
	v_mfma_f32_16x16x32_bf16 v[110:113], v[154:157], v[192:195], v[110:113]
	v_mfma_f32_16x16x32_bf16 v[114:117], v[146:149], v[204:207], v[114:117]
	v_mfma_f32_16x16x32_bf16 v[102:105], v[154:157], v[204:207], v[102:105]
	v_mfma_f32_16x16x32_bf16 v[106:109], v[146:149], v[212:215], v[106:109]
	v_mfma_f32_16x16x32_bf16 v[98:101], v[154:157], v[212:215], v[98:101]
	s_setprio 0
	s_barrier
	s_add_i32 s11, 0, 0x1c000
	s_add_i32 s8, s10, s59
	v_add_u32_e32 v0, s11, v159
	v_lshl_add_u64 v[196:197], v[196:197], 0, s[48:49]
	s_mov_b32 m0, s8
	ds_read_b128 v[218:221], v0
	ds_read_b128 v[222:225], v0 offset:1024
	ds_read_b128 v[226:229], v0 offset:2048
	ds_read_b128 v[230:233], v0 offset:3072
	global_load_lds_dwordx4 v[196:197], off
	v_lshl_add_u64 v[196:197], v[198:199], 0, s[48:49]
	s_add_i32 m0, s8, 0x2000
	s_nop 0
	global_load_lds_dwordx4 v[196:197], off
	s_waitcnt vmcnt(10)
	s_barrier
	s_waitcnt lgkmcnt(0)
	s_setprio 1
	s_waitcnt lgkmcnt(0)
	v_mfma_f32_16x16x32_bf16 v[62:65], v[218:221], v[180:183], v[62:65]
	v_mfma_f32_16x16x32_bf16 v[54:57], v[226:229], v[180:183], v[54:57]
	v_mfma_f32_16x16x32_bf16 v[58:61], v[218:221], v[188:191], v[58:61]
	v_mfma_f32_16x16x32_bf16 v[46:49], v[226:229], v[188:191], v[46:49]
	v_mfma_f32_16x16x32_bf16 v[50:53], v[218:221], v[200:203], v[50:53]
	v_mfma_f32_16x16x32_bf16 v[38:41], v[226:229], v[200:203], v[38:41]
	v_mfma_f32_16x16x32_bf16 v[42:45], v[218:221], v[208:211], v[42:45]
	v_mfma_f32_16x16x32_bf16 v[34:37], v[226:229], v[208:211], v[34:37]
	v_mfma_f32_16x16x32_bf16 v[62:65], v[222:225], v[184:187], v[62:65]
	v_mfma_f32_16x16x32_bf16 v[54:57], v[230:233], v[184:187], v[54:57]
	v_mfma_f32_16x16x32_bf16 v[58:61], v[222:225], v[192:195], v[58:61]
	v_mfma_f32_16x16x32_bf16 v[46:49], v[230:233], v[192:195], v[46:49]
	v_mfma_f32_16x16x32_bf16 v[50:53], v[222:225], v[204:207], v[50:53]
	v_mfma_f32_16x16x32_bf16 v[38:41], v[230:233], v[204:207], v[38:41]
	v_mfma_f32_16x16x32_bf16 v[42:45], v[222:225], v[212:215], v[42:45]
	v_mfma_f32_16x16x32_bf16 v[34:37], v[230:233], v[212:215], v[34:37]
	s_setprio 0
	s_mov_b32 m0, s94
	v_lshl_add_u64 v[196:197], v[234:235], 0, s[48:49]
	s_barrier
	ds_read_b128 v[180:183], v177 offset:49152
	ds_read_b128 v[184:187], v177 offset:50176
	ds_read_b128 v[188:191], v177 offset:51200
	ds_read_b128 v[192:195], v177 offset:52224
	ds_read_b128 v[200:203], v177 offset:53248
	ds_read_b128 v[204:207], v177 offset:54272
	ds_read_b128 v[208:211], v177 offset:55296
	ds_read_b128 v[212:215], v177 offset:56320
	global_load_lds_dwordx4 v[196:197], off
	v_lshl_add_u64 v[196:197], v[236:237], 0, s[48:49]
	s_mov_b32 m0, s95
	s_nop 0
	global_load_lds_dwordx4 v[196:197], off
	s_barrier
;     DEVI void operator()(AccRef acc, const pg8::Unit& u, int wr, int wc, int fr, int fq) const {
;         const int sel = u.pn >> 2; bf16_t* dst = (bf16_t*)(ws + (size_t)(sel + 1) * UNIT);
;         const int row0 = u.pm * 256 + wr * 64 + fr, col0 = (u.pn & 3) * 256 + wc * 32 + 8 * fq, bcol0 = u.pn * 256 + wc * 32 + 8 * fq + (u.pn >= 12 ? 8 : 0);
; #pragma unroll
;         for (int bj = 0; bj < 2; ++bj)
; #pragma unroll
;             for (int n = 0; n < 2; ++n) { const f32x4 bv = *(const f32x4*)(bias + bcol0 + bj * 128 + n * 4);
; #pragma unroll
;                 for (int ai = 0; ai < 2; ++ai)
; #pragma unroll
;                     for (int m = 0; m < 4; ++m) acc[ai][bj][m][n] += bv; }
	s_waitcnt lgkmcnt(0)
	s_setprio 1
	s_waitcnt lgkmcnt(0)
	v_mfma_f32_16x16x32_bf16 v[94:97], v[142:145], v[180:183], v[94:97]
	v_mfma_f32_16x16x32_bf16 v[86:89], v[150:153], v[180:183], v[86:89]
	v_mfma_f32_16x16x32_bf16 v[90:93], v[142:145], v[188:191], v[90:93]
	v_mfma_f32_16x16x32_bf16 v[78:81], v[150:153], v[188:191], v[78:81]
	v_mfma_f32_16x16x32_bf16 v[82:85], v[142:145], v[200:203], v[82:85]
	v_mfma_f32_16x16x32_bf16 v[70:73], v[150:153], v[200:203], v[70:73]
	v_mfma_f32_16x16x32_bf16 v[74:77], v[142:145], v[208:211], v[74:77]
	v_mfma_f32_16x16x32_bf16 v[66:69], v[150:153], v[208:211], v[66:69]
	v_mfma_f32_16x16x32_bf16 v[94:97], v[146:149], v[184:187], v[94:97]
	v_mfma_f32_16x16x32_bf16 v[86:89], v[154:157], v[184:187], v[86:89]
	v_mfma_f32_16x16x32_bf16 v[90:93], v[146:149], v[192:195], v[90:93]
	v_mfma_f32_16x16x32_bf16 v[78:81], v[154:157], v[192:195], v[78:81]
	v_mfma_f32_16x16x32_bf16 v[82:85], v[146:149], v[204:207], v[82:85]
	v_mfma_f32_16x16x32_bf16 v[70:73], v[154:157], v[204:207], v[70:73]
	v_mfma_f32_16x16x32_bf16 v[74:77], v[146:149], v[212:215], v[74:77]
	v_mfma_f32_16x16x32_bf16 v[66:69], v[154:157], v[212:215], v[66:69]
	s_setprio 0
	s_barrier
	s_add_u32 s8, s86, 0x40080
	s_addc_u32 s9, s87, 0
	s_add_i32 s10, s11, s59
	v_lshl_add_u64 v[142:143], s[8:9], 0, v[132:133]
	s_mov_b32 m0, s10
	s_nop 0
	global_load_lds_dwordx4 v[142:143], off
	v_lshl_add_u64 v[142:143], s[8:9], 0, v[136:137]
	s_add_i32 m0, s10, 0x2000
	s_nop 0
	global_load_lds_dwordx4 v[142:143], off
	s_waitcnt vmcnt(8)
	s_barrier
	s_setprio 1
	v_mfma_f32_16x16x32_bf16 v[30:33], v[218:221], v[180:183], v[30:33]
	v_mfma_f32_16x16x32_bf16 v[22:25], v[226:229], v[180:183], v[22:25]
	v_mfma_f32_16x16x32_bf16 v[26:29], v[218:221], v[188:191], v[26:29]
	v_mfma_f32_16x16x32_bf16 v[14:17], v[226:229], v[188:191], v[14:17]
	v_mfma_f32_16x16x32_bf16 v[18:21], v[218:221], v[200:203], v[18:21]
	v_mfma_f32_16x16x32_bf16 v[6:9], v[226:229], v[200:203], v[6:9]
	v_mfma_f32_16x16x32_bf16 v[10:13], v[218:221], v[208:211], v[10:13]
	v_mfma_f32_16x16x32_bf16 v[2:5], v[226:229], v[208:211], v[2:5]
	v_mfma_f32_16x16x32_bf16 v[30:33], v[222:225], v[184:187], v[30:33]
	v_mfma_f32_16x16x32_bf16 v[22:25], v[230:233], v[184:187], v[22:25]
	v_mfma_f32_16x16x32_bf16 v[26:29], v[222:225], v[192:195], v[26:29]
	v_mfma_f32_16x16x32_bf16 v[14:17], v[230:233], v[192:195], v[14:17]
	v_mfma_f32_16x16x32_bf16 v[18:21], v[222:225], v[204:207], v[18:21]
	v_mfma_f32_16x16x32_bf16 v[6:9], v[230:233], v[204:207], v[6:9]
	v_mfma_f32_16x16x32_bf16 v[10:13], v[222:225], v[212:215], v[10:13]
	v_mfma_f32_16x16x32_bf16 v[2:5], v[230:233], v[212:215], v[2:5]
	s_setprio 0
	s_add_i32 s46, s46, 2
	s_add_u32 vcc_lo, vcc_lo, 0x100
	s_addc_u32 vcc_hi, vcc_hi, 0
	s_add_u32 s84, s84, 0x100
	s_addc_u32 s85, s85, 0
	s_cmp_gt_u32 s46, 13
	s_barrier
	s_cbranch_scc0 .LBB0_409
	s_lshl_b32 s21, s24, 8
	s_cmp_gt_i32 s24, 11
	s_cselect_b32 s8, 8, 0
	v_or_b32_e32 v0, s21, v160
	v_add_u32_e32 v142, s8, v0
	v_ashrrev_i32_e32 v143, 31, v142
	v_lshl_add_u64 v[146:147], v[142:143], 2, s[16:17]
	global_load_dwordx4 v[148:151], v[146:147], off offset:16
	global_load_dwordx4 v[142:145], v[146:147], off
	s_cmp_gt_i32 s24, 7
	s_waitcnt vmcnt(0)
	v_pk_add_f32 v[128:129], v[128:129], v[144:145]
	v_pk_add_f32 v[126:127], v[126:127], v[142:143]
	v_pk_add_f32 v[124:125], v[124:125], v[144:145]
	v_pk_add_f32 v[122:123], v[122:123], v[142:143]
	v_pk_add_f32 v[116:117], v[116:117], v[144:145]
	v_pk_add_f32 v[114:115], v[114:115], v[142:143]
	v_pk_add_f32 v[108:109], v[108:109], v[144:145]
	v_pk_add_f32 v[106:107], v[106:107], v[142:143]
	v_pk_add_f32 v[96:97], v[96:97], v[144:145]
	v_pk_add_f32 v[94:95], v[94:95], v[142:143]
	v_pk_add_f32 v[92:93], v[92:93], v[144:145]
	v_pk_add_f32 v[90:91], v[90:91], v[142:143]
	v_pk_add_f32 v[84:85], v[84:85], v[144:145]
	v_pk_add_f32 v[82:83], v[82:83], v[142:143]
	v_pk_add_f32 v[76:77], v[76:77], v[144:145]
	v_pk_add_f32 v[74:75], v[74:75], v[142:143]
	v_pk_add_f32 v[142:143], v[120:121], v[150:151]
	v_pk_add_f32 v[144:145], v[118:119], v[148:149]
	v_pk_add_f32 v[118:119], v[112:113], v[150:151]
	v_pk_add_f32 v[120:121], v[110:111], v[148:149]
	v_pk_add_f32 v[110:111], v[104:105], v[150:151]
	v_pk_add_f32 v[112:113], v[102:103], v[148:149]
	v_pk_add_f32 v[102:103], v[100:101], v[150:151]
	v_pk_add_f32 v[104:105], v[98:99], v[148:149]
	v_pk_add_f32 v[98:99], v[88:89], v[150:151]
	v_pk_add_f32 v[100:101], v[86:87], v[148:149]
	v_pk_add_f32 v[86:87], v[80:81], v[150:151]
	v_pk_add_f32 v[88:89], v[78:79], v[148:149]
	v_pk_add_f32 v[78:79], v[72:73], v[150:151]
	v_pk_add_f32 v[80:81], v[70:71], v[148:149]
	v_pk_add_f32 v[70:71], v[68:69], v[150:151]
	v_pk_add_f32 v[72:73], v[66:67], v[148:149]
	global_load_dwordx4 v[66:69], v[146:147], off offset:528
	s_nop 0
	global_load_dwordx4 v[146:149], v[146:147], off offset:512
	s_waitcnt vmcnt(0)
	v_pk_add_f32 v[154:155], v[56:57], v[68:69]
	v_pk_add_f32 v[150:151], v[64:65], v[148:149]
	v_pk_add_f32 v[152:153], v[62:63], v[146:147]
	v_pk_add_f32 v[62:63], v[60:61], v[148:149]
	v_pk_add_f32 v[64:65], v[58:59], v[146:147]
	v_pk_add_f32 v[58:59], v[52:53], v[148:149]
	v_pk_add_f32 v[60:61], v[50:51], v[146:147]
	v_pk_add_f32 v[50:51], v[44:45], v[148:149]
	v_pk_add_f32 v[52:53], v[42:43], v[146:147]
	v_pk_add_f32 v[42:43], v[32:33], v[148:149]
	v_pk_add_f32 v[44:45], v[30:31], v[146:147]
	v_pk_add_f32 v[30:31], v[28:29], v[148:149]
	v_pk_add_f32 v[32:33], v[26:27], v[146:147]
	v_pk_add_f32 v[26:27], v[20:21], v[148:149]
	v_pk_add_f32 v[28:29], v[18:19], v[146:147]
	v_pk_add_f32 v[18:19], v[12:13], v[148:149]
	v_pk_add_f32 v[20:21], v[10:11], v[146:147]
	v_pk_add_f32 v[156:157], v[54:55], v[66:67]
	v_pk_add_f32 v[146:147], v[48:49], v[68:69]
	v_pk_add_f32 v[148:149], v[46:47], v[66:67]
	v_pk_add_f32 v[54:55], v[40:41], v[68:69]
	v_pk_add_f32 v[56:57], v[38:39], v[66:67]
	v_pk_add_f32 v[46:47], v[36:37], v[68:69]
	v_pk_add_f32 v[48:49], v[34:35], v[66:67]
	v_pk_add_f32 v[38:39], v[24:25], v[68:69]
	v_pk_add_f32 v[40:41], v[22:23], v[66:67]
	v_pk_add_f32 v[34:35], v[16:17], v[68:69]
	v_pk_add_f32 v[36:37], v[14:15], v[66:67]
	v_pk_add_f32 v[22:23], v[8:9], v[68:69]
	v_pk_add_f32 v[24:25], v[6:7], v[66:67]
	v_pk_add_f32 v[14:15], v[4:5], v[68:69]
	v_pk_add_f32 v[16:17], v[2:3], v[66:67]
	s_cbranch_scc1 .LBB0_405
;     DEVI void operator()(AccRef acc, const pg8::Unit& u, int wr, int wc, int fr, int fq) const {
;     ...
;                     for (int bj = 0; bj < 2; ++bj) { const f32x4 a = acc[ai][bj][m][0], b = acc[ai][bj][m][1];
;                         float s = (a[0] * a[0] + a[1] * a[1]) + (a[2] * a[2] + a[3] * a[3]) + (b[0] * b[0] + b[1] * b[1]) + (b[2] * b[2] + b[3] * b[3]);
;                         s = xrow16_sum(s);
;                         if (fq == 0) Pt[((ai * 128 + wr * 64 + m * 16 + fr) * 2 + bj) * 4 + wc] = s; }
	v_mul_f32_e32 v0, v127, v127
	v_mul_f32_e32 v2, v129, v129
	v_fmac_f32_e32 v0, v126, v126
	v_fmac_f32_e32 v2, v128, v128
	v_add_f32_e32 v0, v0, v2
	v_mul_f32_e32 v2, v145, v145
	v_fmac_f32_e32 v2, v144, v144
	v_add_f32_e32 v0, v0, v2
	v_mul_f32_e32 v2, v143, v143
	v_fmac_f32_e32 v2, v142, v142
	v_add_f32_e32 v0, v2, v0
	v_mov_b32_e32 v2, v0
	s_nop 1
	v_permlane16_swap_b32_e32 v0, v2
	v_add_f32_e32 v0, v0, v2
	v_mov_b32_e32 v2, v0
	s_nop 1
	v_permlane32_swap_b32_e32 v0, v2
	s_and_saveexec_b64 s[60:61], s[4:5]
	v_add_f32_e32 v0, v0, v2
	ds_write_b32 v162, v0
	s_or_b64 exec, exec, s[60:61]
	v_mul_f32_e32 v0, v153, v153
	v_mul_f32_e32 v2, v151, v151
	v_fmac_f32_e32 v0, v152, v152
	v_fmac_f32_e32 v2, v150, v150
	v_add_f32_e32 v0, v0, v2
	v_mul_f32_e32 v2, v157, v157
	v_fmac_f32_e32 v2, v156, v156
	v_add_f32_e32 v0, v2, v0
	v_mul_f32_e32 v2, v155, v155
	v_fmac_f32_e32 v2, v154, v154
	v_add_f32_e32 v0, v2, v0
	v_mov_b32_e32 v2, v0
	s_nop 1
	v_permlane16_swap_b32_e32 v0, v2
	v_add_f32_e32 v0, v0, v2
	v_mov_b32_e32 v2, v0
	s_nop 1
	v_permlane32_swap_b32_e32 v0, v2
	s_and_saveexec_b64 s[60:61], s[4:5]
	v_add_f32_e32 v0, v0, v2
	ds_write_b32 v162, v0 offset:16
	s_or_b64 exec, exec, s[60:61]
	v_mul_f32_e32 v0, v123, v123
	v_mul_f32_e32 v2, v125, v125
	v_fmac_f32_e32 v0, v122, v122
	v_fmac_f32_e32 v2, v124, v124
	v_add_f32_e32 v0, v0, v2
	v_mul_f32_e32 v2, v121, v121
	v_fmac_f32_e32 v2, v120, v120
	v_add_f32_e32 v0, v0, v2
	v_mul_f32_e32 v2, v119, v119
	v_fmac_f32_e32 v2, v118, v118
	v_add_f32_e32 v0, v2, v0
	v_mov_b32_e32 v2, v0
	s_nop 1
	v_permlane16_swap_b32_e32 v0, v2
	v_add_f32_e32 v0, v0, v2
	v_mov_b32_e32 v2, v0
	s_nop 1
	v_permlane32_swap_b32_e32 v0, v2
	s_and_saveexec_b64 s[60:61], s[4:5]
	v_add_f32_e32 v0, v0, v2
	ds_write_b32 v163, v0
	s_or_b64 exec, exec, s[60:61]
	v_mul_f32_e32 v0, v65, v65
	v_mul_f32_e32 v2, v63, v63
	v_fmac_f32_e32 v0, v64, v64
	v_fmac_f32_e32 v2, v62, v62
	v_add_f32_e32 v0, v0, v2
	v_mul_f32_e32 v2, v149, v149
	v_fmac_f32_e32 v2, v148, v148
	v_add_f32_e32 v0, v0, v2
	v_mul_f32_e32 v2, v147, v147
	v_fmac_f32_e32 v2, v146, v146
	v_add_f32_e32 v0, v2, v0
	v_mov_b32_e32 v2, v0
	s_nop 1
	v_permlane16_swap_b32_e32 v0, v2
	v_add_f32_e32 v0, v0, v2
	v_mov_b32_e32 v2, v0
	s_nop 1
	v_permlane32_swap_b32_e32 v0, v2
	s_and_saveexec_b64 s[60:61], s[4:5]
	v_add_f32_e32 v0, v0, v2
	ds_write_b32 v163, v0 offset:16
	s_or_b64 exec, exec, s[60:61]
	v_mul_f32_e32 v0, v115, v115
	v_mul_f32_e32 v2, v117, v117
	v_fmac_f32_e32 v0, v114, v114
	v_fmac_f32_e32 v2, v116, v116
	v_add_f32_e32 v0, v0, v2
	v_mul_f32_e32 v2, v113, v113
	v_fmac_f32_e32 v2, v112, v112
	v_add_f32_e32 v0, v0, v2
	v_mul_f32_e32 v2, v111, v111
	v_fmac_f32_e32 v2, v110, v110
	v_add_f32_e32 v0, v2, v0
	v_mov_b32_e32 v2, v0
	s_nop 1
	v_permlane16_swap_b32_e32 v0, v2
	v_add_f32_e32 v0, v0, v2
	v_mov_b32_e32 v2, v0
	s_nop 1
	v_permlane32_swap_b32_e32 v0, v2
	s_and_saveexec_b64 s[60:61], s[4:5]
	v_add_f32_e32 v0, v0, v2
	ds_write_b32 v164, v0
	s_or_b64 exec, exec, s[60:61]
	v_mul_f32_e32 v0, v61, v61
	v_mul_f32_e32 v2, v59, v59
	v_fmac_f32_e32 v0, v60, v60
	v_fmac_f32_e32 v2, v58, v58
	v_add_f32_e32 v0, v0, v2
	v_mul_f32_e32 v2, v57, v57
	v_fmac_f32_e32 v2, v56, v56
	v_add_f32_e32 v0, v0, v2
	v_mul_f32_e32 v2, v55, v55
	v_fmac_f32_e32 v2, v54, v54
	v_add_f32_e32 v0, v2, v0
	v_mov_b32_e32 v2, v0
	s_nop 1
	v_permlane16_swap_b32_e32 v0, v2
	v_add_f32_e32 v0, v0, v2
	v_mov_b32_e32 v2, v0
	s_nop 1
	v_permlane32_swap_b32_e32 v0, v2
	s_and_saveexec_b64 s[60:61], s[4:5]
	v_add_f32_e32 v0, v0, v2
	ds_write_b32 v164, v0 offset:16
	s_or_b64 exec, exec, s[60:61]
	v_mul_f32_e32 v0, v107, v107
	v_mul_f32_e32 v2, v109, v109
	v_fmac_f32_e32 v0, v106, v106
	v_fmac_f32_e32 v2, v108, v108
	v_add_f32_e32 v0, v0, v2
	v_mul_f32_e32 v2, v105, v105
	v_fmac_f32_e32 v2, v104, v104
	v_add_f32_e32 v0, v0, v2
	v_mul_f32_e32 v2, v103, v103
	v_fmac_f32_e32 v2, v102, v102
	v_add_f32_e32 v0, v2, v0
	v_mov_b32_e32 v2, v0
	s_nop 1
	v_permlane16_swap_b32_e32 v0, v2
	v_add_f32_e32 v0, v0, v2
	v_mov_b32_e32 v2, v0
	s_nop 1
	v_permlane32_swap_b32_e32 v0, v2
	s_and_saveexec_b64 s[60:61], s[4:5]
	v_add_f32_e32 v0, v0, v2
	ds_write_b32 v165, v0
	s_or_b64 exec, exec, s[60:61]
	v_mul_f32_e32 v0, v53, v53
	v_mul_f32_e32 v2, v51, v51
	v_fmac_f32_e32 v0, v52, v52
	v_fmac_f32_e32 v2, v50, v50
	v_add_f32_e32 v0, v0, v2
	v_mul_f32_e32 v2, v49, v49
	v_fmac_f32_e32 v2, v48, v48
	v_add_f32_e32 v0, v0, v2
	v_mul_f32_e32 v2, v47, v47
	v_fmac_f32_e32 v2, v46, v46
	v_add_f32_e32 v0, v2, v0
	v_mov_b32_e32 v2, v0
	s_nop 1
	v_permlane16_swap_b32_e32 v0, v2
	v_add_f32_e32 v0, v0, v2
	v_mov_b32_e32 v2, v0
	s_nop 1
	v_permlane32_swap_b32_e32 v0, v2
	s_and_saveexec_b64 s[60:61], s[4:5]
	v_add_f32_e32 v0, v0, v2
	ds_write_b32 v165, v0 offset:16
;     DEVI void operator()(AccRef acc, const pg8::Unit& u, int wr, int wc, int fr, int fq) const {
;     ...
;                     for (int bj = 0; bj < 2; ++bj) { const f32x4 a = acc[ai][bj][m][0], b = acc[ai][bj][m][1];
;                         float s = (a[0] * a[0] + a[1] * a[1]) + (a[2] * a[2] + a[3] * a[3]) + (b[0] * b[0] + b[1] * b[1]) + (b[2] * b[2] + b[3] * b[3]);
;                         s = xrow16_sum(s);
;                         if (fq == 0) Pt[((ai * 128 + wr * 64 + m * 16 + fr) * 2 + bj) * 4 + wc] = s; }
	s_or_b64 exec, exec, s[60:61]
	v_mul_f32_e32 v0, v95, v95
	v_mul_f32_e32 v2, v97, v97
	v_fmac_f32_e32 v0, v94, v94
	v_fmac_f32_e32 v2, v96, v96
	v_add_f32_e32 v0, v0, v2
	v_mul_f32_e32 v2, v101, v101
	v_fmac_f32_e32 v2, v100, v100
	v_add_f32_e32 v0, v0, v2
	v_mul_f32_e32 v2, v99, v99
	v_fmac_f32_e32 v2, v98, v98
	v_add_f32_e32 v0, v2, v0
	v_mov_b32_e32 v2, v0
	s_nop 1
	v_permlane16_swap_b32_e32 v0, v2
	v_add_f32_e32 v0, v0, v2
	v_mov_b32_e32 v2, v0
	s_nop 1
	v_permlane32_swap_b32_e32 v0, v2
	s_and_saveexec_b64 s[60:61], s[4:5]
	v_add_f32_e32 v0, v0, v2
	ds_write_b32 v166, v0
	s_or_b64 exec, exec, s[60:61]
	v_mul_f32_e32 v0, v45, v45
	v_mul_f32_e32 v2, v43, v43
	v_fmac_f32_e32 v0, v44, v44
	v_fmac_f32_e32 v2, v42, v42
	v_add_f32_e32 v0, v0, v2
	v_mul_f32_e32 v2, v41, v41
	v_fmac_f32_e32 v2, v40, v40
	v_add_f32_e32 v0, v0, v2
	v_mul_f32_e32 v2, v39, v39
	v_fmac_f32_e32 v2, v38, v38
	v_add_f32_e32 v0, v2, v0
	v_mov_b32_e32 v2, v0
	s_nop 1
	v_permlane16_swap_b32_e32 v0, v2
	v_add_f32_e32 v0, v0, v2
	v_mov_b32_e32 v2, v0
	s_nop 1
	v_permlane32_swap_b32_e32 v0, v2
	s_and_saveexec_b64 s[60:61], s[4:5]
	v_add_f32_e32 v0, v0, v2
	ds_write_b32 v166, v0 offset:16
	s_or_b64 exec, exec, s[60:61]
	v_mul_f32_e32 v0, v91, v91
	v_mul_f32_e32 v2, v93, v93
	v_fmac_f32_e32 v0, v90, v90
	v_fmac_f32_e32 v2, v92, v92
	v_add_f32_e32 v0, v0, v2
	v_mul_f32_e32 v2, v89, v89
	v_fmac_f32_e32 v2, v88, v88
	v_add_f32_e32 v0, v0, v2
	v_mul_f32_e32 v2, v87, v87
	v_fmac_f32_e32 v2, v86, v86
	v_add_f32_e32 v0, v2, v0
	v_mov_b32_e32 v2, v0
	s_nop 1
	v_permlane16_swap_b32_e32 v0, v2
	v_add_f32_e32 v0, v0, v2
	v_mov_b32_e32 v2, v0
	s_nop 1
	v_permlane32_swap_b32_e32 v0, v2
	s_and_saveexec_b64 s[60:61], s[4:5]
	v_add_f32_e32 v0, v0, v2
	ds_write_b32 v167, v0
	s_or_b64 exec, exec, s[60:61]
	v_mul_f32_e32 v0, v33, v33
	v_mul_f32_e32 v2, v31, v31
	v_fmac_f32_e32 v0, v32, v32
	v_fmac_f32_e32 v2, v30, v30
	v_add_f32_e32 v0, v0, v2
	v_mul_f32_e32 v2, v37, v37
	v_fmac_f32_e32 v2, v36, v36
	v_add_f32_e32 v0, v0, v2
	v_mul_f32_e32 v2, v35, v35
	v_fmac_f32_e32 v2, v34, v34
	v_add_f32_e32 v0, v2, v0
	v_mov_b32_e32 v2, v0
	s_nop 1
	v_permlane16_swap_b32_e32 v0, v2
	v_add_f32_e32 v0, v0, v2
	v_mov_b32_e32 v2, v0
	s_nop 1
	v_permlane32_swap_b32_e32 v0, v2
	s_and_saveexec_b64 s[60:61], s[4:5]
	v_add_f32_e32 v0, v0, v2
	ds_write_b32 v167, v0 offset:16
	s_or_b64 exec, exec, s[60:61]
	v_mul_f32_e32 v0, v83, v83
	v_mul_f32_e32 v2, v85, v85
	v_fmac_f32_e32 v0, v82, v82
	v_fmac_f32_e32 v2, v84, v84
	v_add_f32_e32 v0, v0, v2
	v_mul_f32_e32 v2, v81, v81
	v_fmac_f32_e32 v2, v80, v80
	v_add_f32_e32 v0, v0, v2
	v_mul_f32_e32 v2, v79, v79
	v_fmac_f32_e32 v2, v78, v78
	v_add_f32_e32 v0, v2, v0
	v_mov_b32_e32 v2, v0
	s_nop 1
	v_permlane16_swap_b32_e32 v0, v2
	v_add_f32_e32 v0, v0, v2
	v_mov_b32_e32 v2, v0
	s_nop 1
	v_permlane32_swap_b32_e32 v0, v2
	s_and_saveexec_b64 s[60:61], s[4:5]
	v_add_f32_e32 v0, v0, v2
	ds_write_b32 v168, v0
	s_or_b64 exec, exec, s[60:61]
	v_mul_f32_e32 v0, v29, v29
	v_mul_f32_e32 v2, v27, v27
	v_fmac_f32_e32 v0, v28, v28
	v_fmac_f32_e32 v2, v26, v26
	v_add_f32_e32 v0, v0, v2
	v_mul_f32_e32 v2, v25, v25
	v_fmac_f32_e32 v2, v24, v24
	v_add_f32_e32 v0, v0, v2
	v_mul_f32_e32 v2, v23, v23
	v_fmac_f32_e32 v2, v22, v22
	v_add_f32_e32 v0, v2, v0
	v_mov_b32_e32 v2, v0
	s_nop 1
	v_permlane16_swap_b32_e32 v0, v2
	v_add_f32_e32 v0, v0, v2
	v_mov_b32_e32 v2, v0
	s_nop 1
	v_permlane32_swap_b32_e32 v0, v2
	s_and_saveexec_b64 s[60:61], s[4:5]
	v_add_f32_e32 v0, v0, v2
	ds_write_b32 v168, v0 offset:16
	s_or_b64 exec, exec, s[60:61]
	v_mul_f32_e32 v0, v75, v75
	v_mul_f32_e32 v2, v77, v77
	v_fmac_f32_e32 v0, v74, v74
	v_fmac_f32_e32 v2, v76, v76
	v_add_f32_e32 v0, v0, v2
	v_mul_f32_e32 v2, v73, v73
	v_fmac_f32_e32 v2, v72, v72
	v_add_f32_e32 v0, v0, v2
	v_mul_f32_e32 v2, v71, v71
	v_fmac_f32_e32 v2, v70, v70
	v_add_f32_e32 v0, v2, v0
	v_mov_b32_e32 v2, v0
	s_nop 1
	v_permlane16_swap_b32_e32 v0, v2
	v_add_f32_e32 v0, v0, v2
	v_mov_b32_e32 v2, v0
	s_nop 1
	v_permlane32_swap_b32_e32 v0, v2
	s_and_saveexec_b64 s[60:61], s[4:5]
	v_add_f32_e32 v0, v0, v2
	ds_write_b32 v169, v0
	s_or_b64 exec, exec, s[60:61]
	v_mul_f32_e32 v0, v21, v21
	v_mul_f32_e32 v2, v19, v19
	v_fmac_f32_e32 v0, v20, v20
	v_fmac_f32_e32 v2, v18, v18
	v_add_f32_e32 v0, v0, v2
	v_mul_f32_e32 v2, v17, v17
	v_fmac_f32_e32 v2, v16, v16
	v_add_f32_e32 v0, v0, v2
	v_mul_f32_e32 v2, v15, v15
	v_fmac_f32_e32 v2, v14, v14
	v_add_f32_e32 v0, v2, v0
	v_mov_b32_e32 v2, v0
	s_nop 1
	v_permlane16_swap_b32_e32 v0, v2
	v_add_f32_e32 v0, v0, v2
	v_mov_b32_e32 v2, v0
	s_nop 1
	v_permlane32_swap_b32_e32 v0, v2
	s_and_saveexec_b64 s[60:61], s[4:5]
	s_cbranch_execz .LBB0_404
	v_add_f32_e32 v0, v0, v2
	ds_write_b32 v169, v0 offset:16
	s_branch .LBB0_404

.LBB0_511:
	s_add_u32 s18, s14, 0x100
	s_addc_u32 s19, s15, 0
	s_add_i32 s84, 0, 0x10000
	v_add_u32_e32 v0, s84, v189
	ds_read_b128 v[122:125], v0
	ds_read_b128 v[126:129], v0 offset:1024
	ds_read_b128 v[130:133], v0 offset:2048
	ds_read_b128 v[134:137], v0 offset:3072
	s_cmp_eq_u32 s83, 40
	s_cselect_b32 s23, s9, s19
	s_cselect_b32 s22, s8, s18
	s_cselect_b32 s21, s11, s82
	s_cselect_b32 s20, s10, s81
	v_lshl_add_u64 v[186:187], s[14:15], 0, v[184:185]
	s_add_i32 m0, s46, 0xc000
	ds_read_b128 v[146:149], v193
	ds_read_b128 v[150:153], v193 offset:1024
	ds_read_b128 v[154:157], v193 offset:2048
	ds_read_b128 v[158:161], v193 offset:3072
	ds_read_b128 v[162:165], v193 offset:4096
	ds_read_b128 v[166:169], v193 offset:5120
	ds_read_b128 v[170:173], v193 offset:6144
	ds_read_b128 v[174:177], v193 offset:7168
	global_load_lds_dwordx4 v[186:187], off
	v_lshl_add_u64 v[186:187], s[14:15], 0, v[182:183]
	s_add_i32 m0, s46, 0xe000
	s_nop 0
	global_load_lds_dwordx4 v[186:187], off
	s_waitcnt lgkmcnt(8)
	s_barrier
	s_waitcnt lgkmcnt(0)
	s_setprio 1
	s_waitcnt lgkmcnt(0)
	v_mfma_f32_16x16x32_bf16 v[142:145], v[122:125], v[146:149], v[142:145]
	v_mfma_f32_16x16x32_bf16 v[138:141], v[130:133], v[146:149], v[138:141]
	v_mfma_f32_16x16x32_bf16 v[110:113], v[122:125], v[154:157], v[110:113]
	v_mfma_f32_16x16x32_bf16 v[106:109], v[130:133], v[154:157], v[106:109]
	v_mfma_f32_16x16x32_bf16 v[94:97], v[122:125], v[162:165], v[94:97]
	v_mfma_f32_16x16x32_bf16 v[90:93], v[130:133], v[162:165], v[90:93]
	v_mfma_f32_16x16x32_bf16 v[78:81], v[122:125], v[170:173], v[78:81]
	v_mfma_f32_16x16x32_bf16 v[74:77], v[130:133], v[170:173], v[74:77]
	v_mfma_f32_16x16x32_bf16 v[142:145], v[126:129], v[150:153], v[142:145]
	v_mfma_f32_16x16x32_bf16 v[138:141], v[134:137], v[150:153], v[138:141]
	v_mfma_f32_16x16x32_bf16 v[110:113], v[126:129], v[158:161], v[110:113]
	v_mfma_f32_16x16x32_bf16 v[106:109], v[134:137], v[158:161], v[106:109]
	v_mfma_f32_16x16x32_bf16 v[94:97], v[126:129], v[166:169], v[94:97]
	v_mfma_f32_16x16x32_bf16 v[90:93], v[134:137], v[166:169], v[90:93]
	v_mfma_f32_16x16x32_bf16 v[78:81], v[126:129], v[174:177], v[78:81]
	v_mfma_f32_16x16x32_bf16 v[74:77], v[134:137], v[174:177], v[74:77]
	s_setprio 0
	s_barrier
	s_add_i32 s85, 0, 0x14000
	s_add_i32 s14, s84, s25
	v_add_u32_e32 v0, s85, v189
	v_lshl_add_u64 v[186:187], s[20:21], 0, v[180:181]
	s_mov_b32 m0, s14
	ds_read_b128 v[194:197], v0
	ds_read_b128 v[200:203], v0 offset:1024
	ds_read_b128 v[204:207], v0 offset:2048
	ds_read_b128 v[208:211], v0 offset:3072
	global_load_lds_dwordx4 v[186:187], off
	v_lshl_add_u64 v[198:199], s[20:21], 0, v[178:179]
	s_add_i32 m0, s14, 0x2000
	s_nop 0
	global_load_lds_dwordx4 v[198:199], off
	s_waitcnt vmcnt(10)
	s_barrier
	s_waitcnt lgkmcnt(0)
	s_setprio 1
	s_waitcnt lgkmcnt(0)
	v_mfma_f32_16x16x32_bf16 v[118:121], v[194:197], v[146:149], v[118:121]
	v_mfma_f32_16x16x32_bf16 v[114:117], v[204:207], v[146:149], v[114:117]
	v_mfma_f32_16x16x32_bf16 v[102:105], v[194:197], v[154:157], v[102:105]
	v_mfma_f32_16x16x32_bf16 v[98:101], v[204:207], v[154:157], v[98:101]
	v_mfma_f32_16x16x32_bf16 v[86:89], v[194:197], v[162:165], v[86:89]
	v_mfma_f32_16x16x32_bf16 v[82:85], v[204:207], v[162:165], v[82:85]
	v_mfma_f32_16x16x32_bf16 v[70:73], v[194:197], v[170:173], v[70:73]
	v_mfma_f32_16x16x32_bf16 v[66:69], v[204:207], v[170:173], v[66:69]
	v_mfma_f32_16x16x32_bf16 v[118:121], v[200:203], v[150:153], v[118:121]
	v_mfma_f32_16x16x32_bf16 v[114:117], v[208:211], v[150:153], v[114:117]
	v_mfma_f32_16x16x32_bf16 v[102:105], v[200:203], v[158:161], v[102:105]
	v_mfma_f32_16x16x32_bf16 v[98:101], v[208:211], v[158:161], v[98:101]
	v_mfma_f32_16x16x32_bf16 v[86:89], v[200:203], v[166:169], v[86:89]
	v_mfma_f32_16x16x32_bf16 v[82:85], v[208:211], v[166:169], v[82:85]
	v_mfma_f32_16x16x32_bf16 v[70:73], v[200:203], v[174:177], v[70:73]
	v_mfma_f32_16x16x32_bf16 v[66:69], v[208:211], v[174:177], v[66:69]
	s_setprio 0
	s_mov_b32 m0, s46
	v_lshl_add_u64 v[212:213], s[22:23], 0, v[180:181]
	s_barrier
	ds_read_b128 v[146:149], v193 offset:16384
	ds_read_b128 v[150:153], v193 offset:17408
	ds_read_b128 v[154:157], v193 offset:18432
	ds_read_b128 v[158:161], v193 offset:19456
	ds_read_b128 v[162:165], v193 offset:20480
	ds_read_b128 v[166:169], v193 offset:21504
	ds_read_b128 v[170:173], v193 offset:22528
	ds_read_b128 v[174:177], v193 offset:23552
	global_load_lds_dwordx4 v[212:213], off
	v_lshl_add_u64 v[214:215], s[22:23], 0, v[178:179]
	s_mov_b32 m0, s57
	s_nop 0
	global_load_lds_dwordx4 v[214:215], off
	s_barrier
	s_waitcnt lgkmcnt(0)
	s_setprio 1
	s_waitcnt lgkmcnt(0)
	v_mfma_f32_16x16x32_bf16 v[62:65], v[122:125], v[146:149], v[62:65]
	v_mfma_f32_16x16x32_bf16 v[58:61], v[130:133], v[146:149], v[58:61]
	v_mfma_f32_16x16x32_bf16 v[46:49], v[122:125], v[154:157], v[46:49]
	v_mfma_f32_16x16x32_bf16 v[42:45], v[130:133], v[154:157], v[42:45]
	v_mfma_f32_16x16x32_bf16 v[30:33], v[122:125], v[162:165], v[30:33]
	v_mfma_f32_16x16x32_bf16 v[26:29], v[130:133], v[162:165], v[26:29]
	v_mfma_f32_16x16x32_bf16 v[14:17], v[122:125], v[170:173], v[14:17]
	v_mfma_f32_16x16x32_bf16 v[10:13], v[130:133], v[170:173], v[10:13]
	v_mfma_f32_16x16x32_bf16 v[62:65], v[126:129], v[150:153], v[62:65]
	v_mfma_f32_16x16x32_bf16 v[58:61], v[134:137], v[150:153], v[58:61]
	v_mfma_f32_16x16x32_bf16 v[46:49], v[126:129], v[158:161], v[46:49]
	v_mfma_f32_16x16x32_bf16 v[42:45], v[134:137], v[158:161], v[42:45]
	v_mfma_f32_16x16x32_bf16 v[30:33], v[126:129], v[166:169], v[30:33]
	v_mfma_f32_16x16x32_bf16 v[26:29], v[134:137], v[166:169], v[26:29]
	v_mfma_f32_16x16x32_bf16 v[14:17], v[126:129], v[174:177], v[14:17]
	v_mfma_f32_16x16x32_bf16 v[10:13], v[134:137], v[174:177], v[10:13]
	s_setprio 0
	s_barrier
	s_add_u32 s14, s20, 0xb0000
	s_addc_u32 s15, s21, 0
	s_add_i32 s84, s85, s25
	v_lshl_add_u64 v[122:123], s[14:15], 0, v[180:181]
	s_mov_b32 m0, s84
	s_nop 0
	global_load_lds_dwordx4 v[122:123], off
	v_lshl_add_u64 v[122:123], s[14:15], 0, v[178:179]
	s_add_i32 m0, s84, 0x2000
	s_nop 0
	global_load_lds_dwordx4 v[122:123], off
	s_waitcnt vmcnt(8)
	s_barrier
	s_setprio 1
	v_mfma_f32_16x16x32_bf16 v[54:57], v[194:197], v[146:149], v[54:57]
	v_mfma_f32_16x16x32_bf16 v[50:53], v[204:207], v[146:149], v[50:53]
	v_mfma_f32_16x16x32_bf16 v[38:41], v[194:197], v[154:157], v[38:41]
	v_mfma_f32_16x16x32_bf16 v[34:37], v[204:207], v[154:157], v[34:37]
	v_mfma_f32_16x16x32_bf16 v[22:25], v[194:197], v[162:165], v[22:25]
	v_mfma_f32_16x16x32_bf16 v[18:21], v[204:207], v[162:165], v[18:21]
	v_mfma_f32_16x16x32_bf16 v[6:9], v[194:197], v[170:173], v[6:9]
	v_mfma_f32_16x16x32_bf16 v[2:5], v[204:207], v[170:173], v[2:5]
	v_mfma_f32_16x16x32_bf16 v[54:57], v[200:203], v[150:153], v[54:57]
	v_mfma_f32_16x16x32_bf16 v[50:53], v[208:211], v[150:153], v[50:53]
	v_mfma_f32_16x16x32_bf16 v[38:41], v[200:203], v[158:161], v[38:41]
	v_mfma_f32_16x16x32_bf16 v[34:37], v[208:211], v[158:161], v[34:37]
	v_mfma_f32_16x16x32_bf16 v[22:25], v[200:203], v[166:169], v[22:25]
	v_mfma_f32_16x16x32_bf16 v[18:21], v[208:211], v[166:169], v[18:21]
	v_mfma_f32_16x16x32_bf16 v[6:9], v[200:203], v[174:177], v[6:9]
	v_mfma_f32_16x16x32_bf16 v[2:5], v[208:211], v[174:177], v[2:5]
	s_setprio 0
	s_add_i32 s84, 0, 0x18000
	v_add_u32_e32 v0, s84, v189
	s_barrier
	ds_read_b128 v[122:125], v0
	ds_read_b128 v[126:129], v0 offset:1024
	ds_read_b128 v[130:133], v0 offset:2048
	ds_read_b128 v[134:137], v0 offset:3072
	s_add_u32 s14, s22, 0xb0000
	s_addc_u32 s15, s23, 0
	s_mov_b32 m0, s59
	v_lshl_add_u64 v[194:195], s[14:15], 0, v[180:181]
	ds_read_b128 v[146:149], v193 offset:32768
	ds_read_b128 v[150:153], v193 offset:33792
	ds_read_b128 v[154:157], v193 offset:34816
	ds_read_b128 v[158:161], v193 offset:35840
	ds_read_b128 v[162:165], v193 offset:36864
	ds_read_b128 v[166:169], v193 offset:37888
	ds_read_b128 v[170:173], v193 offset:38912
	ds_read_b128 v[174:177], v193 offset:39936
	global_load_lds_dwordx4 v[194:195], off
	v_lshl_add_u64 v[194:195], s[14:15], 0, v[178:179]
	s_mov_b32 m0, s60
	s_nop 0
	global_load_lds_dwordx4 v[194:195], off
	s_waitcnt lgkmcnt(8)
	s_barrier
	s_waitcnt lgkmcnt(0)
	s_setprio 1
	s_waitcnt lgkmcnt(0)
	v_mfma_f32_16x16x32_bf16 v[142:145], v[122:125], v[146:149], v[142:145]
	v_mfma_f32_16x16x32_bf16 v[138:141], v[130:133], v[146:149], v[138:141]
	v_mfma_f32_16x16x32_bf16 v[110:113], v[122:125], v[154:157], v[110:113]
	v_mfma_f32_16x16x32_bf16 v[106:109], v[130:133], v[154:157], v[106:109]
	v_mfma_f32_16x16x32_bf16 v[94:97], v[122:125], v[162:165], v[94:97]
	v_mfma_f32_16x16x32_bf16 v[90:93], v[130:133], v[162:165], v[90:93]
	v_mfma_f32_16x16x32_bf16 v[78:81], v[122:125], v[170:173], v[78:81]
	v_mfma_f32_16x16x32_bf16 v[74:77], v[130:133], v[170:173], v[74:77]
	v_mfma_f32_16x16x32_bf16 v[142:145], v[126:129], v[150:153], v[142:145]
	v_mfma_f32_16x16x32_bf16 v[138:141], v[134:137], v[150:153], v[138:141]
	v_mfma_f32_16x16x32_bf16 v[110:113], v[126:129], v[158:161], v[110:113]
	v_mfma_f32_16x16x32_bf16 v[106:109], v[134:137], v[158:161], v[106:109]
	v_mfma_f32_16x16x32_bf16 v[94:97], v[126:129], v[166:169], v[94:97]
	v_mfma_f32_16x16x32_bf16 v[90:93], v[134:137], v[166:169], v[90:93]
	v_mfma_f32_16x16x32_bf16 v[78:81], v[126:129], v[174:177], v[78:81]
	v_mfma_f32_16x16x32_bf16 v[74:77], v[134:137], v[174:177], v[74:77]
	s_setprio 0
	s_barrier
	s_add_i32 s22, 0, 0x1c000
	s_add_i32 s14, s84, s25
	v_add_u32_e32 v0, s22, v189
	v_lshl_add_u64 v[186:187], v[186:187], 0, s[48:49]
	s_mov_b32 m0, s14
	ds_read_b128 v[194:197], v0
	ds_read_b128 v[200:203], v0 offset:1024
	ds_read_b128 v[204:207], v0 offset:2048
	ds_read_b128 v[208:211], v0 offset:3072
	global_load_lds_dwordx4 v[186:187], off
	v_lshl_add_u64 v[186:187], v[198:199], 0, s[48:49]
	s_add_i32 m0, s14, 0x2000
	s_nop 0
	global_load_lds_dwordx4 v[186:187], off
	s_waitcnt vmcnt(10)
	s_barrier
	s_waitcnt lgkmcnt(0)
	s_setprio 1
	s_waitcnt lgkmcnt(0)
	v_mfma_f32_16x16x32_bf16 v[118:121], v[194:197], v[146:149], v[118:121]
	v_mfma_f32_16x16x32_bf16 v[114:117], v[204:207], v[146:149], v[114:117]
	v_mfma_f32_16x16x32_bf16 v[102:105], v[194:197], v[154:157], v[102:105]
	v_mfma_f32_16x16x32_bf16 v[98:101], v[204:207], v[154:157], v[98:101]
	v_mfma_f32_16x16x32_bf16 v[86:89], v[194:197], v[162:165], v[86:89]
	v_mfma_f32_16x16x32_bf16 v[82:85], v[204:207], v[162:165], v[82:85]
	v_mfma_f32_16x16x32_bf16 v[70:73], v[194:197], v[170:173], v[70:73]
	v_mfma_f32_16x16x32_bf16 v[66:69], v[204:207], v[170:173], v[66:69]
	v_mfma_f32_16x16x32_bf16 v[118:121], v[200:203], v[150:153], v[118:121]
	v_mfma_f32_16x16x32_bf16 v[114:117], v[208:211], v[150:153], v[114:117]
	v_mfma_f32_16x16x32_bf16 v[102:105], v[200:203], v[158:161], v[102:105]
	v_mfma_f32_16x16x32_bf16 v[98:101], v[208:211], v[158:161], v[98:101]
	v_mfma_f32_16x16x32_bf16 v[86:89], v[200:203], v[166:169], v[86:89]
	v_mfma_f32_16x16x32_bf16 v[82:85], v[208:211], v[166:169], v[82:85]
	v_mfma_f32_16x16x32_bf16 v[70:73], v[200:203], v[174:177], v[70:73]
	v_mfma_f32_16x16x32_bf16 v[66:69], v[208:211], v[174:177], v[66:69]
	s_setprio 0
	s_mov_b32 m0, s74
	v_lshl_add_u64 v[186:187], v[212:213], 0, s[48:49]
	s_barrier
	ds_read_b128 v[146:149], v193 offset:49152
	ds_read_b128 v[150:153], v193 offset:50176
	ds_read_b128 v[154:157], v193 offset:51200
	ds_read_b128 v[158:161], v193 offset:52224
	ds_read_b128 v[162:165], v193 offset:53248
	ds_read_b128 v[166:169], v193 offset:54272
	ds_read_b128 v[170:173], v193 offset:55296
	ds_read_b128 v[174:177], v193 offset:56320
	global_load_lds_dwordx4 v[186:187], off
	v_lshl_add_u64 v[186:187], v[214:215], 0, s[48:49]
	s_mov_b32 m0, s75
	s_nop 0
	global_load_lds_dwordx4 v[186:187], off
	s_barrier
;     DEVI void operator()(AccRef acc, const pg8::Unit& u, int wr, int wc, int fr, int fq) const {
;         unsigned o = (unsigned)((u.pm * 256 + wr * 64 + fr) * DM + u.pn * 256 + wc * 32 + 4 * fq) * 4u;
;         const bool lo = fr < 8;
;         unsigned os = (unsigned)((u.pm * 256 + wr * 64 + (fr & 7)) * DM + u.pn * 256 + wc * 32 + 4 * fq) * 4u + (lo ? 0u : 64u);
; #pragma unroll
;         for (int ai = 0; ai < 2; ++ai) {
;             asm volatile("" : "+v"(o), "+v"(os));
;             f32x4 b[4][2][2];
; #pragma unroll
;             for (int m = 0; m < 4; ++m)
; #pragma unroll
;                 for (int bj = 0; bj < 2; ++bj)
; #pragma unroll
;                     for (int n = 0; n < 2; ++n) b[m][bj][n] = *(const f32x4*)((const char*)base + o + (unsigned)(m * 16 * DM * 4 + bj * 512 + n * 64));
	s_waitcnt lgkmcnt(0)
	s_setprio 1
	s_waitcnt lgkmcnt(0)
	v_mfma_f32_16x16x32_bf16 v[62:65], v[122:125], v[146:149], v[62:65]
	v_mfma_f32_16x16x32_bf16 v[58:61], v[130:133], v[146:149], v[58:61]
	v_mfma_f32_16x16x32_bf16 v[46:49], v[122:125], v[154:157], v[46:49]
	v_mfma_f32_16x16x32_bf16 v[42:45], v[130:133], v[154:157], v[42:45]
	v_mfma_f32_16x16x32_bf16 v[30:33], v[122:125], v[162:165], v[30:33]
	v_mfma_f32_16x16x32_bf16 v[26:29], v[130:133], v[162:165], v[26:29]
	v_mfma_f32_16x16x32_bf16 v[14:17], v[122:125], v[170:173], v[14:17]
	v_mfma_f32_16x16x32_bf16 v[10:13], v[130:133], v[170:173], v[10:13]
	v_mfma_f32_16x16x32_bf16 v[62:65], v[126:129], v[150:153], v[62:65]
	v_mfma_f32_16x16x32_bf16 v[58:61], v[134:137], v[150:153], v[58:61]
	v_mfma_f32_16x16x32_bf16 v[46:49], v[126:129], v[158:161], v[46:49]
	v_mfma_f32_16x16x32_bf16 v[42:45], v[134:137], v[158:161], v[42:45]
	v_mfma_f32_16x16x32_bf16 v[30:33], v[126:129], v[166:169], v[30:33]
	v_mfma_f32_16x16x32_bf16 v[26:29], v[134:137], v[166:169], v[26:29]
	v_mfma_f32_16x16x32_bf16 v[14:17], v[126:129], v[174:177], v[14:17]
	v_mfma_f32_16x16x32_bf16 v[10:13], v[134:137], v[174:177], v[10:13]
	s_setprio 0
	s_barrier
	s_add_u32 s14, s20, 0xb0080
	s_addc_u32 s15, s21, 0
	s_add_i32 s20, s22, s25
	v_lshl_add_u64 v[122:123], s[14:15], 0, v[180:181]
	s_mov_b32 m0, s20
	s_nop 0
	global_load_lds_dwordx4 v[122:123], off
	v_lshl_add_u64 v[122:123], s[14:15], 0, v[178:179]
	s_add_i32 m0, s20, 0x2000
	s_nop 0
	global_load_lds_dwordx4 v[122:123], off
	s_waitcnt vmcnt(8)
	s_barrier
	s_setprio 1
	v_mfma_f32_16x16x32_bf16 v[54:57], v[194:197], v[146:149], v[54:57]
	v_mfma_f32_16x16x32_bf16 v[50:53], v[204:207], v[146:149], v[50:53]
	v_mfma_f32_16x16x32_bf16 v[38:41], v[194:197], v[154:157], v[38:41]
	v_mfma_f32_16x16x32_bf16 v[34:37], v[204:207], v[154:157], v[34:37]
	v_mfma_f32_16x16x32_bf16 v[22:25], v[194:197], v[162:165], v[22:25]
	v_mfma_f32_16x16x32_bf16 v[18:21], v[204:207], v[162:165], v[18:21]
	v_mfma_f32_16x16x32_bf16 v[6:9], v[194:197], v[170:173], v[6:9]
	v_mfma_f32_16x16x32_bf16 v[2:5], v[204:207], v[170:173], v[2:5]
	v_mfma_f32_16x16x32_bf16 v[54:57], v[200:203], v[150:153], v[54:57]
	v_mfma_f32_16x16x32_bf16 v[50:53], v[208:211], v[150:153], v[50:53]
	v_mfma_f32_16x16x32_bf16 v[38:41], v[200:203], v[158:161], v[38:41]
	v_mfma_f32_16x16x32_bf16 v[34:37], v[208:211], v[158:161], v[34:37]
	v_mfma_f32_16x16x32_bf16 v[22:25], v[200:203], v[166:169], v[22:25]
	v_mfma_f32_16x16x32_bf16 v[18:21], v[208:211], v[166:169], v[18:21]
	v_mfma_f32_16x16x32_bf16 v[6:9], v[200:203], v[174:177], v[6:9]
	v_mfma_f32_16x16x32_bf16 v[2:5], v[208:211], v[174:177], v[2:5]
	s_setprio 0
	s_add_i32 s83, s83, 2
	s_add_u32 s81, s81, 0x100
	s_addc_u32 s82, s82, 0
	s_cmp_gt_u32 s83, 41
	s_mov_b64 s[14:15], s[18:19]
	s_barrier
	s_cbranch_scc0 .LBB0_511
	s_lshl_b32 s14, s79, 8
	s_add_i32 s14, s14, s61
	v_or_b32_e32 v0, s14, v188
	s_lshl_b32 s15, s80, 8
	v_or_b32_e32 v122, s14, v190
	v_lshl_add_u32 v0, v0, 10, s15
	v_lshl_add_u32 v122, v122, 10, s15
	v_or_b32_e32 v0, v0, v192
	v_or_b32_e32 v122, v122, v192
	v_lshlrev_b32_e32 v0, 2, v0
	v_lshl_or_b32 v186, v122, 2, v191
	s_mov_b32 s80, s77
	s_mov_b32 s79, s78
	s_mov_b64 s[18:19], s[10:11]
	s_mov_b64 s[14:15], s[8:9]
	v_add_u32_e32 v187, 0x8000, v186
	s_add_u32 s98, s12, 0x0
	s_addc_u32 s99, s13, 0
	global_load_dwordx4 v[194:197], v0, s[98:99]
	global_load_dwordx4 v[200:203], v0, s[98:99] offset:64
	global_load_dwordx4 v[204:207], v0, s[98:99] offset:512
	global_load_dwordx4 v[208:211], v0, s[98:99] offset:576
	s_add_u32 s98, s12, 0x10000
	s_addc_u32 s99, s13, 0
	global_load_dwordx4 v[174:177], v0, s[98:99]
	global_load_dwordx4 v[170:173], v0, s[98:99] offset:64
	global_load_dwordx4 v[166:169], v0, s[98:99] offset:512
	global_load_dwordx4 v[162:165], v0, s[98:99] offset:576
	s_add_u32 s98, s12, 0x20000
	s_addc_u32 s99, s13, 0
	global_load_dwordx4 v[158:161], v0, s[98:99]
	global_load_dwordx4 v[154:157], v0, s[98:99] offset:64
	global_load_dwordx4 v[150:153], v0, s[98:99] offset:512
	global_load_dwordx4 v[146:149], v0, s[98:99] offset:576
	s_add_u32 s98, s12, 0x30000
	s_addc_u32 s99, s13, 0
	global_load_dwordx4 v[134:137], v0, s[98:99]
	global_load_dwordx4 v[130:133], v0, s[98:99] offset:64
	global_load_dwordx4 v[126:129], v0, s[98:99] offset:512
	global_load_dwordx4 v[122:125], v0, s[98:99] offset:576
	s_waitcnt vmcnt(12)
; template <int CTRL> DEVI float dpp(float x) { return __builtin_bit_cast(float, __builtin_amdgcn_mov_dpp(__builtin_bit_cast(int, x), CTRL, 0xf, 0xf, true)); }
;     DEVI void operator()(AccRef acc, const pg8::Unit& u, int wr, int wc, int fr, int fq) const {
;     ...
;         for (int ai = 0; ai < 2; ++ai) {
;             asm volatile("" : "+v"(o), "+v"(os));
;             f32x4 b[4][2][2];
; #pragma unroll
;             for (int m = 0; m < 4; ++m)
; #pragma unroll
;                 for (int bj = 0; bj < 2; ++bj)
; #pragma unroll
;                     for (int n = 0; n < 2; ++n) b[m][bj][n] = *(const f32x4*)((const char*)base + o + (unsigned)(m * 16 * DM * 4 + bj * 512 + n * 64));
; #pragma unroll
;             for (int m = 0; m < 4; ++m)
; #pragma unroll
;                 for (int bj = 0; bj < 2; ++bj) { const f32x4 d0 = b[m][bj][0] + alpha * acc[ai][bj][m][0], d1 = b[m][bj][1] + alpha * acc[ai][bj][m][1];
;                     f32x4 t0, t1;
; #pragma unroll
;                     for (int i = 0; i < 4; ++i) { t0[i] = dpp<0x128>(d0[i]); t1[i] = dpp<0x128>(d1[i]); }
;                     const f32x4 sa = lo ? d0 : t1, sb = lo ? t0 : d1;
;                     const unsigned oo = os + (unsigned)(m * 16 * DM * 4 + bj * 512);
;                     *(f32x4*)((char*)out + oo) = sa; *(f32x4*)((char*)out + oo + 8u * DM * 4u) = sb; }
;             o += 128u * DM * 4u; os += 128u * DM * 4u; }
	v_pk_fma_f32 v[142:143], v[142:143], 0.5, v[194:195] op_sel_hi:[1,0,1]
	v_pk_fma_f32 v[144:145], v[144:145], 0.5, v[196:197] op_sel_hi:[1,0,1]
	v_pk_fma_f32 v[138:139], v[138:139], 0.5, v[200:201] op_sel_hi:[1,0,1]
	v_pk_fma_f32 v[140:141], v[140:141], 0.5, v[202:203] op_sel_hi:[1,0,1]
	v_pk_fma_f32 v[118:119], v[118:119], 0.5, v[204:205] op_sel_hi:[1,0,1]
	v_pk_fma_f32 v[120:121], v[120:121], 0.5, v[206:207] op_sel_hi:[1,0,1]
	v_pk_fma_f32 v[114:115], v[114:115], 0.5, v[208:209] op_sel_hi:[1,0,1]
	v_pk_fma_f32 v[116:117], v[116:117], 0.5, v[210:211] op_sel_hi:[1,0,1]
	s_mov_b64 vcc, s[4:5]
	v_cndmask_b32_dpp v194, v138, v142, vcc row_ror:8 row_mask:0xf bank_mask:0xf bound_ctrl:1
	v_cndmask_b32_dpp v195, v139, v143, vcc row_ror:8 row_mask:0xf bank_mask:0xf bound_ctrl:1
	v_cndmask_b32_dpp v196, v140, v144, vcc row_ror:8 row_mask:0xf bank_mask:0xf bound_ctrl:1
	v_cndmask_b32_dpp v197, v141, v145, vcc row_ror:8 row_mask:0xf bank_mask:0xf bound_ctrl:1
	v_cndmask_b32_dpp v204, v114, v118, vcc row_ror:8 row_mask:0xf bank_mask:0xf bound_ctrl:1
	v_cndmask_b32_dpp v205, v115, v119, vcc row_ror:8 row_mask:0xf bank_mask:0xf bound_ctrl:1
	v_cndmask_b32_dpp v206, v116, v120, vcc row_ror:8 row_mask:0xf bank_mask:0xf bound_ctrl:1
	v_cndmask_b32_dpp v207, v117, v121, vcc row_ror:8 row_mask:0xf bank_mask:0xf bound_ctrl:1
	s_not_b64 vcc, s[4:5]
	v_cndmask_b32_dpp v200, v142, v138, vcc row_ror:8 row_mask:0xf bank_mask:0xf bound_ctrl:1
	v_cndmask_b32_dpp v201, v143, v139, vcc row_ror:8 row_mask:0xf bank_mask:0xf bound_ctrl:1
	v_cndmask_b32_dpp v202, v144, v140, vcc row_ror:8 row_mask:0xf bank_mask:0xf bound_ctrl:1
	v_cndmask_b32_dpp v203, v145, v141, vcc row_ror:8 row_mask:0xf bank_mask:0xf bound_ctrl:1
	v_cndmask_b32_dpp v208, v118, v114, vcc row_ror:8 row_mask:0xf bank_mask:0xf bound_ctrl:1
	v_cndmask_b32_dpp v209, v119, v115, vcc row_ror:8 row_mask:0xf bank_mask:0xf bound_ctrl:1
	v_cndmask_b32_dpp v210, v120, v116, vcc row_ror:8 row_mask:0xf bank_mask:0xf bound_ctrl:1
	v_cndmask_b32_dpp v211, v121, v117, vcc row_ror:8 row_mask:0xf bank_mask:0xf bound_ctrl:1
	s_add_u32 s100, s28, 0x0
	s_addc_u32 s101, s29, 0
	global_store_dwordx4 v186, v[194:197], s[100:101]
	global_store_dwordx4 v187, v[200:203], s[100:101]
	global_store_dwordx4 v186, v[204:207], s[100:101] offset:512
	global_store_dwordx4 v187, v[208:211], s[100:101] offset:512
	s_add_u32 s98, s12, 0x80000
	s_addc_u32 s99, s13, 0
	global_load_dwordx4 v[142:145], v0, s[98:99]
	global_load_dwordx4 v[138:141], v0, s[98:99] offset:64
	global_load_dwordx4 v[118:121], v0, s[98:99] offset:512
	global_load_dwordx4 v[114:117], v0, s[98:99] offset:576
	s_waitcnt vmcnt(16)
	v_pk_fma_f32 v[110:111], v[110:111], 0.5, v[174:175] op_sel_hi:[1,0,1]
	v_pk_fma_f32 v[112:113], v[112:113], 0.5, v[176:177] op_sel_hi:[1,0,1]
	v_pk_fma_f32 v[106:107], v[106:107], 0.5, v[170:171] op_sel_hi:[1,0,1]
	v_pk_fma_f32 v[108:109], v[108:109], 0.5, v[172:173] op_sel_hi:[1,0,1]
	v_pk_fma_f32 v[102:103], v[102:103], 0.5, v[166:167] op_sel_hi:[1,0,1]
	v_pk_fma_f32 v[104:105], v[104:105], 0.5, v[168:169] op_sel_hi:[1,0,1]
	v_pk_fma_f32 v[98:99], v[98:99], 0.5, v[162:163] op_sel_hi:[1,0,1]
	v_pk_fma_f32 v[100:101], v[100:101], 0.5, v[164:165] op_sel_hi:[1,0,1]
	s_mov_b64 vcc, s[4:5]
	v_cndmask_b32_dpp v174, v106, v110, vcc row_ror:8 row_mask:0xf bank_mask:0xf bound_ctrl:1
	v_cndmask_b32_dpp v175, v107, v111, vcc row_ror:8 row_mask:0xf bank_mask:0xf bound_ctrl:1
	v_cndmask_b32_dpp v176, v108, v112, vcc row_ror:8 row_mask:0xf bank_mask:0xf bound_ctrl:1
	v_cndmask_b32_dpp v177, v109, v113, vcc row_ror:8 row_mask:0xf bank_mask:0xf bound_ctrl:1
	v_cndmask_b32_dpp v166, v98, v102, vcc row_ror:8 row_mask:0xf bank_mask:0xf bound_ctrl:1
	v_cndmask_b32_dpp v167, v99, v103, vcc row_ror:8 row_mask:0xf bank_mask:0xf bound_ctrl:1
	v_cndmask_b32_dpp v168, v100, v104, vcc row_ror:8 row_mask:0xf bank_mask:0xf bound_ctrl:1
	v_cndmask_b32_dpp v169, v101, v105, vcc row_ror:8 row_mask:0xf bank_mask:0xf bound_ctrl:1
	s_not_b64 vcc, s[4:5]
	v_cndmask_b32_dpp v170, v110, v106, vcc row_ror:8 row_mask:0xf bank_mask:0xf bound_ctrl:1
	v_cndmask_b32_dpp v171, v111, v107, vcc row_ror:8 row_mask:0xf bank_mask:0xf bound_ctrl:1
	v_cndmask_b32_dpp v172, v112, v108, vcc row_ror:8 row_mask:0xf bank_mask:0xf bound_ctrl:1
	v_cndmask_b32_dpp v173, v113, v109, vcc row_ror:8 row_mask:0xf bank_mask:0xf bound_ctrl:1
	v_cndmask_b32_dpp v162, v102, v98, vcc row_ror:8 row_mask:0xf bank_mask:0xf bound_ctrl:1
	v_cndmask_b32_dpp v163, v103, v99, vcc row_ror:8 row_mask:0xf bank_mask:0xf bound_ctrl:1
	v_cndmask_b32_dpp v164, v104, v100, vcc row_ror:8 row_mask:0xf bank_mask:0xf bound_ctrl:1
	v_cndmask_b32_dpp v165, v105, v101, vcc row_ror:8 row_mask:0xf bank_mask:0xf bound_ctrl:1
	s_add_u32 s100, s28, 0x10000
	s_addc_u32 s101, s29, 0
	global_store_dwordx4 v186, v[174:177], s[100:101]
	global_store_dwordx4 v187, v[170:173], s[100:101]
	global_store_dwordx4 v186, v[166:169], s[100:101] offset:512
	global_store_dwordx4 v187, v[162:165], s[100:101] offset:512
	s_add_u32 s98, s12, 0x90000
	s_addc_u32 s99, s13, 0
	global_load_dwordx4 v[110:113], v0, s[98:99]
	global_load_dwordx4 v[106:109], v0, s[98:99] offset:64
	global_load_dwordx4 v[102:105], v0, s[98:99] offset:512
	global_load_dwordx4 v[98:101], v0, s[98:99] offset:576
	s_waitcnt vmcnt(20)
; template <int CTRL> DEVI float dpp(float x) { return __builtin_bit_cast(float, __builtin_amdgcn_mov_dpp(__builtin_bit_cast(int, x), CTRL, 0xf, 0xf, true)); }
;     DEVI void operator()(AccRef acc, const pg8::Unit& u, int wr, int wc, int fr, int fq) const {
;     ...
;         for (int ai = 0; ai < 2; ++ai) {
;             asm volatile("" : "+v"(o), "+v"(os));
;             f32x4 b[4][2][2];
; #pragma unroll
;             for (int m = 0; m < 4; ++m)
; #pragma unroll
;                 for (int bj = 0; bj < 2; ++bj)
; #pragma unroll
;                     for (int n = 0; n < 2; ++n) b[m][bj][n] = *(const f32x4*)((const char*)base + o + (unsigned)(m * 16 * DM * 4 + bj * 512 + n * 64));
; #pragma unroll
;             for (int m = 0; m < 4; ++m)
; #pragma unroll
;                 for (int bj = 0; bj < 2; ++bj) { const f32x4 d0 = b[m][bj][0] + alpha * acc[ai][bj][m][0], d1 = b[m][bj][1] + alpha * acc[ai][bj][m][1];
;                     f32x4 t0, t1;
; #pragma unroll
;                     for (int i = 0; i < 4; ++i) { t0[i] = dpp<0x128>(d0[i]); t1[i] = dpp<0x128>(d1[i]); }
;                     const f32x4 sa = lo ? d0 : t1, sb = lo ? t0 : d1;
;                     const unsigned oo = os + (unsigned)(m * 16 * DM * 4 + bj * 512);
;                     *(f32x4*)((char*)out + oo) = sa; *(f32x4*)((char*)out + oo + 8u * DM * 4u) = sb; }
;             o += 128u * DM * 4u; os += 128u * DM * 4u; }
	v_pk_fma_f32 v[94:95], v[94:95], 0.5, v[158:159] op_sel_hi:[1,0,1]
	v_pk_fma_f32 v[96:97], v[96:97], 0.5, v[160:161] op_sel_hi:[1,0,1]
	v_pk_fma_f32 v[90:91], v[90:91], 0.5, v[154:155] op_sel_hi:[1,0,1]
	v_pk_fma_f32 v[92:93], v[92:93], 0.5, v[156:157] op_sel_hi:[1,0,1]
	v_pk_fma_f32 v[86:87], v[86:87], 0.5, v[150:151] op_sel_hi:[1,0,1]
	v_pk_fma_f32 v[88:89], v[88:89], 0.5, v[152:153] op_sel_hi:[1,0,1]
	v_pk_fma_f32 v[82:83], v[82:83], 0.5, v[146:147] op_sel_hi:[1,0,1]
	v_pk_fma_f32 v[84:85], v[84:85], 0.5, v[148:149] op_sel_hi:[1,0,1]
	s_mov_b64 vcc, s[4:5]
	v_cndmask_b32_dpp v158, v90, v94, vcc row_ror:8 row_mask:0xf bank_mask:0xf bound_ctrl:1
	v_cndmask_b32_dpp v159, v91, v95, vcc row_ror:8 row_mask:0xf bank_mask:0xf bound_ctrl:1
	v_cndmask_b32_dpp v160, v92, v96, vcc row_ror:8 row_mask:0xf bank_mask:0xf bound_ctrl:1
	v_cndmask_b32_dpp v161, v93, v97, vcc row_ror:8 row_mask:0xf bank_mask:0xf bound_ctrl:1
	v_cndmask_b32_dpp v150, v82, v86, vcc row_ror:8 row_mask:0xf bank_mask:0xf bound_ctrl:1
	v_cndmask_b32_dpp v151, v83, v87, vcc row_ror:8 row_mask:0xf bank_mask:0xf bound_ctrl:1
	v_cndmask_b32_dpp v152, v84, v88, vcc row_ror:8 row_mask:0xf bank_mask:0xf bound_ctrl:1
	v_cndmask_b32_dpp v153, v85, v89, vcc row_ror:8 row_mask:0xf bank_mask:0xf bound_ctrl:1
	s_not_b64 vcc, s[4:5]
	v_cndmask_b32_dpp v154, v94, v90, vcc row_ror:8 row_mask:0xf bank_mask:0xf bound_ctrl:1
	v_cndmask_b32_dpp v155, v95, v91, vcc row_ror:8 row_mask:0xf bank_mask:0xf bound_ctrl:1
	v_cndmask_b32_dpp v156, v96, v92, vcc row_ror:8 row_mask:0xf bank_mask:0xf bound_ctrl:1
	v_cndmask_b32_dpp v157, v97, v93, vcc row_ror:8 row_mask:0xf bank_mask:0xf bound_ctrl:1
	v_cndmask_b32_dpp v146, v86, v82, vcc row_ror:8 row_mask:0xf bank_mask:0xf bound_ctrl:1
	v_cndmask_b32_dpp v147, v87, v83, vcc row_ror:8 row_mask:0xf bank_mask:0xf bound_ctrl:1
	v_cndmask_b32_dpp v148, v88, v84, vcc row_ror:8 row_mask:0xf bank_mask:0xf bound_ctrl:1
	v_cndmask_b32_dpp v149, v89, v85, vcc row_ror:8 row_mask:0xf bank_mask:0xf bound_ctrl:1
	s_add_u32 s100, s28, 0x20000
	s_addc_u32 s101, s29, 0
	global_store_dwordx4 v186, v[158:161], s[100:101]
	global_store_dwordx4 v187, v[154:157], s[100:101]
	global_store_dwordx4 v186, v[150:153], s[100:101] offset:512
	global_store_dwordx4 v187, v[146:149], s[100:101] offset:512
	s_add_u32 s98, s12, 0xa0000
	s_addc_u32 s99, s13, 0
	global_load_dwordx4 v[94:97], v0, s[98:99]
	global_load_dwordx4 v[90:93], v0, s[98:99] offset:64
	global_load_dwordx4 v[86:89], v0, s[98:99] offset:512
	global_load_dwordx4 v[82:85], v0, s[98:99] offset:576
	s_waitcnt vmcnt(24)
	v_pk_fma_f32 v[78:79], v[78:79], 0.5, v[134:135] op_sel_hi:[1,0,1]
	v_pk_fma_f32 v[80:81], v[80:81], 0.5, v[136:137] op_sel_hi:[1,0,1]
	v_pk_fma_f32 v[74:75], v[74:75], 0.5, v[130:131] op_sel_hi:[1,0,1]
	v_pk_fma_f32 v[76:77], v[76:77], 0.5, v[132:133] op_sel_hi:[1,0,1]
	v_pk_fma_f32 v[70:71], v[70:71], 0.5, v[126:127] op_sel_hi:[1,0,1]
	v_pk_fma_f32 v[72:73], v[72:73], 0.5, v[128:129] op_sel_hi:[1,0,1]
	v_pk_fma_f32 v[66:67], v[66:67], 0.5, v[122:123] op_sel_hi:[1,0,1]
	v_pk_fma_f32 v[68:69], v[68:69], 0.5, v[124:125] op_sel_hi:[1,0,1]
	s_mov_b64 vcc, s[4:5]
	v_cndmask_b32_dpp v134, v74, v78, vcc row_ror:8 row_mask:0xf bank_mask:0xf bound_ctrl:1
	v_cndmask_b32_dpp v135, v75, v79, vcc row_ror:8 row_mask:0xf bank_mask:0xf bound_ctrl:1
	v_cndmask_b32_dpp v136, v76, v80, vcc row_ror:8 row_mask:0xf bank_mask:0xf bound_ctrl:1
	v_cndmask_b32_dpp v137, v77, v81, vcc row_ror:8 row_mask:0xf bank_mask:0xf bound_ctrl:1
	v_cndmask_b32_dpp v126, v66, v70, vcc row_ror:8 row_mask:0xf bank_mask:0xf bound_ctrl:1
	v_cndmask_b32_dpp v127, v67, v71, vcc row_ror:8 row_mask:0xf bank_mask:0xf bound_ctrl:1
	v_cndmask_b32_dpp v128, v68, v72, vcc row_ror:8 row_mask:0xf bank_mask:0xf bound_ctrl:1
	v_cndmask_b32_dpp v129, v69, v73, vcc row_ror:8 row_mask:0xf bank_mask:0xf bound_ctrl:1
	s_not_b64 vcc, s[4:5]
	v_cndmask_b32_dpp v130, v78, v74, vcc row_ror:8 row_mask:0xf bank_mask:0xf bound_ctrl:1
	v_cndmask_b32_dpp v131, v79, v75, vcc row_ror:8 row_mask:0xf bank_mask:0xf bound_ctrl:1
	v_cndmask_b32_dpp v132, v80, v76, vcc row_ror:8 row_mask:0xf bank_mask:0xf bound_ctrl:1
	v_cndmask_b32_dpp v133, v81, v77, vcc row_ror:8 row_mask:0xf bank_mask:0xf bound_ctrl:1
	v_cndmask_b32_dpp v122, v70, v66, vcc row_ror:8 row_mask:0xf bank_mask:0xf bound_ctrl:1
	v_cndmask_b32_dpp v123, v71, v67, vcc row_ror:8 row_mask:0xf bank_mask:0xf bound_ctrl:1
	v_cndmask_b32_dpp v124, v72, v68, vcc row_ror:8 row_mask:0xf bank_mask:0xf bound_ctrl:1
	v_cndmask_b32_dpp v125, v73, v69, vcc row_ror:8 row_mask:0xf bank_mask:0xf bound_ctrl:1
	s_add_u32 s100, s28, 0x30000
	s_addc_u32 s101, s29, 0
	global_store_dwordx4 v186, v[134:137], s[100:101]
	global_store_dwordx4 v187, v[130:133], s[100:101]
	global_store_dwordx4 v186, v[126:129], s[100:101] offset:512
	global_store_dwordx4 v187, v[122:125], s[100:101] offset:512
	s_add_u32 s98, s12, 0xb0000
	s_addc_u32 s99, s13, 0
	global_load_dwordx4 v[78:81], v0, s[98:99]
	global_load_dwordx4 v[74:77], v0, s[98:99] offset:64
	global_load_dwordx4 v[70:73], v0, s[98:99] offset:512
	global_load_dwordx4 v[66:69], v0, s[98:99] offset:576
	s_waitcnt vmcnt(24)
; template <int CTRL> DEVI float dpp(float x) { return __builtin_bit_cast(float, __builtin_amdgcn_mov_dpp(__builtin_bit_cast(int, x), CTRL, 0xf, 0xf, true)); }
;     DEVI void operator()(AccRef acc, const pg8::Unit& u, int wr, int wc, int fr, int fq) const {
;     ...
;         for (int ai = 0; ai < 2; ++ai) {
;             asm volatile("" : "+v"(o), "+v"(os));
;             f32x4 b[4][2][2];
; #pragma unroll
;             for (int m = 0; m < 4; ++m)
; #pragma unroll
;                 for (int bj = 0; bj < 2; ++bj)
; #pragma unroll
;                     for (int n = 0; n < 2; ++n) b[m][bj][n] = *(const f32x4*)((const char*)base + o + (unsigned)(m * 16 * DM * 4 + bj * 512 + n * 64));
; #pragma unroll
;             for (int m = 0; m < 4; ++m)
; #pragma unroll
;                 for (int bj = 0; bj < 2; ++bj) { const f32x4 d0 = b[m][bj][0] + alpha * acc[ai][bj][m][0], d1 = b[m][bj][1] + alpha * acc[ai][bj][m][1];
;                     f32x4 t0, t1;
; #pragma unroll
;                     for (int i = 0; i < 4; ++i) { t0[i] = dpp<0x128>(d0[i]); t1[i] = dpp<0x128>(d1[i]); }
;                     const f32x4 sa = lo ? d0 : t1, sb = lo ? t0 : d1;
;                     const unsigned oo = os + (unsigned)(m * 16 * DM * 4 + bj * 512);
;                     *(f32x4*)((char*)out + oo) = sa; *(f32x4*)((char*)out + oo + 8u * DM * 4u) = sb; }
;             o += 128u * DM * 4u; os += 128u * DM * 4u; }
	v_pk_fma_f32 v[62:63], v[62:63], 0.5, v[142:143] op_sel_hi:[1,0,1]
	v_pk_fma_f32 v[64:65], v[64:65], 0.5, v[144:145] op_sel_hi:[1,0,1]
	v_pk_fma_f32 v[58:59], v[58:59], 0.5, v[138:139] op_sel_hi:[1,0,1]
	v_pk_fma_f32 v[60:61], v[60:61], 0.5, v[140:141] op_sel_hi:[1,0,1]
	v_pk_fma_f32 v[54:55], v[54:55], 0.5, v[118:119] op_sel_hi:[1,0,1]
	v_pk_fma_f32 v[56:57], v[56:57], 0.5, v[120:121] op_sel_hi:[1,0,1]
	v_pk_fma_f32 v[50:51], v[50:51], 0.5, v[114:115] op_sel_hi:[1,0,1]
	v_pk_fma_f32 v[52:53], v[52:53], 0.5, v[116:117] op_sel_hi:[1,0,1]
	s_mov_b64 vcc, s[4:5]
	v_cndmask_b32_dpp v142, v58, v62, vcc row_ror:8 row_mask:0xf bank_mask:0xf bound_ctrl:1
	v_cndmask_b32_dpp v143, v59, v63, vcc row_ror:8 row_mask:0xf bank_mask:0xf bound_ctrl:1
	v_cndmask_b32_dpp v144, v60, v64, vcc row_ror:8 row_mask:0xf bank_mask:0xf bound_ctrl:1
	v_cndmask_b32_dpp v145, v61, v65, vcc row_ror:8 row_mask:0xf bank_mask:0xf bound_ctrl:1
	v_cndmask_b32_dpp v118, v50, v54, vcc row_ror:8 row_mask:0xf bank_mask:0xf bound_ctrl:1
	v_cndmask_b32_dpp v119, v51, v55, vcc row_ror:8 row_mask:0xf bank_mask:0xf bound_ctrl:1
	v_cndmask_b32_dpp v120, v52, v56, vcc row_ror:8 row_mask:0xf bank_mask:0xf bound_ctrl:1
	v_cndmask_b32_dpp v121, v53, v57, vcc row_ror:8 row_mask:0xf bank_mask:0xf bound_ctrl:1
	s_not_b64 vcc, s[4:5]
	v_cndmask_b32_dpp v138, v62, v58, vcc row_ror:8 row_mask:0xf bank_mask:0xf bound_ctrl:1
	v_cndmask_b32_dpp v139, v63, v59, vcc row_ror:8 row_mask:0xf bank_mask:0xf bound_ctrl:1
	v_cndmask_b32_dpp v140, v64, v60, vcc row_ror:8 row_mask:0xf bank_mask:0xf bound_ctrl:1
	v_cndmask_b32_dpp v141, v65, v61, vcc row_ror:8 row_mask:0xf bank_mask:0xf bound_ctrl:1
	v_cndmask_b32_dpp v114, v54, v50, vcc row_ror:8 row_mask:0xf bank_mask:0xf bound_ctrl:1
	v_cndmask_b32_dpp v115, v55, v51, vcc row_ror:8 row_mask:0xf bank_mask:0xf bound_ctrl:1
	v_cndmask_b32_dpp v116, v56, v52, vcc row_ror:8 row_mask:0xf bank_mask:0xf bound_ctrl:1
	v_cndmask_b32_dpp v117, v57, v53, vcc row_ror:8 row_mask:0xf bank_mask:0xf bound_ctrl:1
	s_add_u32 s100, s28, 0x80000
	s_addc_u32 s101, s29, 0
	global_store_dwordx4 v186, v[142:145], s[100:101]
	global_store_dwordx4 v187, v[138:141], s[100:101]
	global_store_dwordx4 v186, v[118:121], s[100:101] offset:512
	global_store_dwordx4 v187, v[114:117], s[100:101] offset:512
	s_waitcnt vmcnt(20)
	v_pk_fma_f32 v[46:47], v[46:47], 0.5, v[110:111] op_sel_hi:[1,0,1]
	v_pk_fma_f32 v[48:49], v[48:49], 0.5, v[112:113] op_sel_hi:[1,0,1]
	v_pk_fma_f32 v[42:43], v[42:43], 0.5, v[106:107] op_sel_hi:[1,0,1]
	v_pk_fma_f32 v[44:45], v[44:45], 0.5, v[108:109] op_sel_hi:[1,0,1]
	v_pk_fma_f32 v[38:39], v[38:39], 0.5, v[102:103] op_sel_hi:[1,0,1]
	v_pk_fma_f32 v[40:41], v[40:41], 0.5, v[104:105] op_sel_hi:[1,0,1]
	v_pk_fma_f32 v[34:35], v[34:35], 0.5, v[98:99] op_sel_hi:[1,0,1]
	v_pk_fma_f32 v[36:37], v[36:37], 0.5, v[100:101] op_sel_hi:[1,0,1]
	s_mov_b64 vcc, s[4:5]
	v_cndmask_b32_dpp v110, v42, v46, vcc row_ror:8 row_mask:0xf bank_mask:0xf bound_ctrl:1
	v_cndmask_b32_dpp v111, v43, v47, vcc row_ror:8 row_mask:0xf bank_mask:0xf bound_ctrl:1
	v_cndmask_b32_dpp v112, v44, v48, vcc row_ror:8 row_mask:0xf bank_mask:0xf bound_ctrl:1
	v_cndmask_b32_dpp v113, v45, v49, vcc row_ror:8 row_mask:0xf bank_mask:0xf bound_ctrl:1
	v_cndmask_b32_dpp v102, v34, v38, vcc row_ror:8 row_mask:0xf bank_mask:0xf bound_ctrl:1
	v_cndmask_b32_dpp v103, v35, v39, vcc row_ror:8 row_mask:0xf bank_mask:0xf bound_ctrl:1
	v_cndmask_b32_dpp v104, v36, v40, vcc row_ror:8 row_mask:0xf bank_mask:0xf bound_ctrl:1
	v_cndmask_b32_dpp v105, v37, v41, vcc row_ror:8 row_mask:0xf bank_mask:0xf bound_ctrl:1
	s_not_b64 vcc, s[4:5]
	v_cndmask_b32_dpp v106, v46, v42, vcc row_ror:8 row_mask:0xf bank_mask:0xf bound_ctrl:1
	v_cndmask_b32_dpp v107, v47, v43, vcc row_ror:8 row_mask:0xf bank_mask:0xf bound_ctrl:1
	v_cndmask_b32_dpp v108, v48, v44, vcc row_ror:8 row_mask:0xf bank_mask:0xf bound_ctrl:1
	v_cndmask_b32_dpp v109, v49, v45, vcc row_ror:8 row_mask:0xf bank_mask:0xf bound_ctrl:1
	v_cndmask_b32_dpp v98, v38, v34, vcc row_ror:8 row_mask:0xf bank_mask:0xf bound_ctrl:1
	v_cndmask_b32_dpp v99, v39, v35, vcc row_ror:8 row_mask:0xf bank_mask:0xf bound_ctrl:1
	v_cndmask_b32_dpp v100, v40, v36, vcc row_ror:8 row_mask:0xf bank_mask:0xf bound_ctrl:1
	v_cndmask_b32_dpp v101, v41, v37, vcc row_ror:8 row_mask:0xf bank_mask:0xf bound_ctrl:1
	s_add_u32 s100, s28, 0x90000
	s_addc_u32 s101, s29, 0
	global_store_dwordx4 v186, v[110:113], s[100:101]
	global_store_dwordx4 v187, v[106:109], s[100:101]
	global_store_dwordx4 v186, v[102:105], s[100:101] offset:512
	global_store_dwordx4 v187, v[98:101], s[100:101] offset:512
	s_waitcnt vmcnt(16)
; template <int CTRL> DEVI float dpp(float x) { return __builtin_bit_cast(float, __builtin_amdgcn_mov_dpp(__builtin_bit_cast(int, x), CTRL, 0xf, 0xf, true)); }
;     DEVI void operator()(AccRef acc, const pg8::Unit& u, int wr, int wc, int fr, int fq) const {
;     ...
;         for (int ai = 0; ai < 2; ++ai) {
;             asm volatile("" : "+v"(o), "+v"(os));
;             f32x4 b[4][2][2];
; #pragma unroll
;             for (int m = 0; m < 4; ++m)
; #pragma unroll
;                 for (int bj = 0; bj < 2; ++bj)
; #pragma unroll
;                     for (int n = 0; n < 2; ++n) b[m][bj][n] = *(const f32x4*)((const char*)base + o + (unsigned)(m * 16 * DM * 4 + bj * 512 + n * 64));
; #pragma unroll
;             for (int m = 0; m < 4; ++m)
; #pragma unroll
;                 for (int bj = 0; bj < 2; ++bj) { const f32x4 d0 = b[m][bj][0] + alpha * acc[ai][bj][m][0], d1 = b[m][bj][1] + alpha * acc[ai][bj][m][1];
;                     f32x4 t0, t1;
; #pragma unroll
;                     for (int i = 0; i < 4; ++i) { t0[i] = dpp<0x128>(d0[i]); t1[i] = dpp<0x128>(d1[i]); }
;                     const f32x4 sa = lo ? d0 : t1, sb = lo ? t0 : d1;
;                     const unsigned oo = os + (unsigned)(m * 16 * DM * 4 + bj * 512);
;                     *(f32x4*)((char*)out + oo) = sa; *(f32x4*)((char*)out + oo + 8u * DM * 4u) = sb; }
;             o += 128u * DM * 4u; os += 128u * DM * 4u; }
;     }
	v_pk_fma_f32 v[30:31], v[30:31], 0.5, v[94:95] op_sel_hi:[1,0,1]
	v_pk_fma_f32 v[32:33], v[32:33], 0.5, v[96:97] op_sel_hi:[1,0,1]
	v_pk_fma_f32 v[26:27], v[26:27], 0.5, v[90:91] op_sel_hi:[1,0,1]
	v_pk_fma_f32 v[28:29], v[28:29], 0.5, v[92:93] op_sel_hi:[1,0,1]
	v_pk_fma_f32 v[22:23], v[22:23], 0.5, v[86:87] op_sel_hi:[1,0,1]
	v_pk_fma_f32 v[24:25], v[24:25], 0.5, v[88:89] op_sel_hi:[1,0,1]
	v_pk_fma_f32 v[18:19], v[18:19], 0.5, v[82:83] op_sel_hi:[1,0,1]
	v_pk_fma_f32 v[20:21], v[20:21], 0.5, v[84:85] op_sel_hi:[1,0,1]
	s_mov_b64 vcc, s[4:5]
	v_cndmask_b32_dpp v94, v26, v30, vcc row_ror:8 row_mask:0xf bank_mask:0xf bound_ctrl:1
	v_cndmask_b32_dpp v95, v27, v31, vcc row_ror:8 row_mask:0xf bank_mask:0xf bound_ctrl:1
	v_cndmask_b32_dpp v96, v28, v32, vcc row_ror:8 row_mask:0xf bank_mask:0xf bound_ctrl:1
	v_cndmask_b32_dpp v97, v29, v33, vcc row_ror:8 row_mask:0xf bank_mask:0xf bound_ctrl:1
	v_cndmask_b32_dpp v86, v18, v22, vcc row_ror:8 row_mask:0xf bank_mask:0xf bound_ctrl:1
	v_cndmask_b32_dpp v87, v19, v23, vcc row_ror:8 row_mask:0xf bank_mask:0xf bound_ctrl:1
	v_cndmask_b32_dpp v88, v20, v24, vcc row_ror:8 row_mask:0xf bank_mask:0xf bound_ctrl:1
	v_cndmask_b32_dpp v89, v21, v25, vcc row_ror:8 row_mask:0xf bank_mask:0xf bound_ctrl:1
	s_not_b64 vcc, s[4:5]
	v_cndmask_b32_dpp v90, v30, v26, vcc row_ror:8 row_mask:0xf bank_mask:0xf bound_ctrl:1
	v_cndmask_b32_dpp v91, v31, v27, vcc row_ror:8 row_mask:0xf bank_mask:0xf bound_ctrl:1
	v_cndmask_b32_dpp v92, v32, v28, vcc row_ror:8 row_mask:0xf bank_mask:0xf bound_ctrl:1
	v_cndmask_b32_dpp v93, v33, v29, vcc row_ror:8 row_mask:0xf bank_mask:0xf bound_ctrl:1
	v_cndmask_b32_dpp v82, v22, v18, vcc row_ror:8 row_mask:0xf bank_mask:0xf bound_ctrl:1
	v_cndmask_b32_dpp v83, v23, v19, vcc row_ror:8 row_mask:0xf bank_mask:0xf bound_ctrl:1
	v_cndmask_b32_dpp v84, v24, v20, vcc row_ror:8 row_mask:0xf bank_mask:0xf bound_ctrl:1
	v_cndmask_b32_dpp v85, v25, v21, vcc row_ror:8 row_mask:0xf bank_mask:0xf bound_ctrl:1
	s_add_u32 s100, s28, 0xa0000
	s_addc_u32 s101, s29, 0
	global_store_dwordx4 v186, v[94:97], s[100:101]
	global_store_dwordx4 v187, v[90:93], s[100:101]
	global_store_dwordx4 v186, v[86:89], s[100:101] offset:512
	global_store_dwordx4 v187, v[82:85], s[100:101] offset:512
	s_waitcnt vmcnt(12)
	v_pk_fma_f32 v[14:15], v[14:15], 0.5, v[78:79] op_sel_hi:[1,0,1]
	v_pk_fma_f32 v[16:17], v[16:17], 0.5, v[80:81] op_sel_hi:[1,0,1]
	v_pk_fma_f32 v[10:11], v[10:11], 0.5, v[74:75] op_sel_hi:[1,0,1]
	v_pk_fma_f32 v[12:13], v[12:13], 0.5, v[76:77] op_sel_hi:[1,0,1]
	v_pk_fma_f32 v[6:7], v[6:7], 0.5, v[70:71] op_sel_hi:[1,0,1]
	v_pk_fma_f32 v[8:9], v[8:9], 0.5, v[72:73] op_sel_hi:[1,0,1]
	v_pk_fma_f32 v[2:3], v[2:3], 0.5, v[66:67] op_sel_hi:[1,0,1]
	v_pk_fma_f32 v[4:5], v[4:5], 0.5, v[68:69] op_sel_hi:[1,0,1]
	s_mov_b64 vcc, s[4:5]
	v_cndmask_b32_dpp v78, v10, v14, vcc row_ror:8 row_mask:0xf bank_mask:0xf bound_ctrl:1
	v_cndmask_b32_dpp v79, v11, v15, vcc row_ror:8 row_mask:0xf bank_mask:0xf bound_ctrl:1
	v_cndmask_b32_dpp v80, v12, v16, vcc row_ror:8 row_mask:0xf bank_mask:0xf bound_ctrl:1
	v_cndmask_b32_dpp v81, v13, v17, vcc row_ror:8 row_mask:0xf bank_mask:0xf bound_ctrl:1
	v_cndmask_b32_dpp v70, v2, v6, vcc row_ror:8 row_mask:0xf bank_mask:0xf bound_ctrl:1
	v_cndmask_b32_dpp v71, v3, v7, vcc row_ror:8 row_mask:0xf bank_mask:0xf bound_ctrl:1
	v_cndmask_b32_dpp v72, v4, v8, vcc row_ror:8 row_mask:0xf bank_mask:0xf bound_ctrl:1
	v_cndmask_b32_dpp v73, v5, v9, vcc row_ror:8 row_mask:0xf bank_mask:0xf bound_ctrl:1
	s_not_b64 vcc, s[4:5]
	v_cndmask_b32_dpp v74, v14, v10, vcc row_ror:8 row_mask:0xf bank_mask:0xf bound_ctrl:1
	v_cndmask_b32_dpp v75, v15, v11, vcc row_ror:8 row_mask:0xf bank_mask:0xf bound_ctrl:1
	v_cndmask_b32_dpp v76, v16, v12, vcc row_ror:8 row_mask:0xf bank_mask:0xf bound_ctrl:1
	v_cndmask_b32_dpp v77, v17, v13, vcc row_ror:8 row_mask:0xf bank_mask:0xf bound_ctrl:1
	v_cndmask_b32_dpp v66, v6, v2, vcc row_ror:8 row_mask:0xf bank_mask:0xf bound_ctrl:1
	v_cndmask_b32_dpp v67, v7, v3, vcc row_ror:8 row_mask:0xf bank_mask:0xf bound_ctrl:1
	v_cndmask_b32_dpp v68, v8, v4, vcc row_ror:8 row_mask:0xf bank_mask:0xf bound_ctrl:1
	v_cndmask_b32_dpp v69, v9, v5, vcc row_ror:8 row_mask:0xf bank_mask:0xf bound_ctrl:1
	s_add_u32 s100, s28, 0xb0000
	s_addc_u32 s101, s29, 0
	global_store_dwordx4 v186, v[78:81], s[100:101]
	global_store_dwordx4 v187, v[74:77], s[100:101]
	global_store_dwordx4 v186, v[70:73], s[100:101] offset:512
	global_store_dwordx4 v187, v[66:69], s[100:101] offset:512
	s_and_b64 vcc, exec, s[6:7]
	s_cbranch_vccz .LBB0_500
	s_waitcnt vmcnt(0)
	s_cmpk_gt_u32 s24, 0xff
	s_cbranch_scc1 .LBB0_515
	s_barrier

.LBB0_524:
	s_and_b64 vcc, exec, s[22:23]
	s_cbranch_vccz .LBB0_526
	s_add_i32 s7, 0, 0x10000
	v_add_u32_e32 v0, s7, v147
	ds_read_b128 v[2:5], v0
	ds_read_b128 v[6:9], v0 offset:1024
	ds_read_b128 v[10:13], v0 offset:2048
	ds_read_b128 v[14:17], v0 offset:3072
	ds_read_b128 v[18:21], v149
	ds_read_b128 v[22:25], v149 offset:1024
	ds_read_b128 v[26:29], v149 offset:2048
	ds_read_b128 v[30:33], v149 offset:3072
	ds_read_b128 v[34:37], v149 offset:4096
	ds_read_b128 v[38:41], v149 offset:5120
	ds_read_b128 v[42:45], v149 offset:6144
	ds_read_b128 v[46:49], v149 offset:7168
	s_waitcnt lgkmcnt(8)
	s_barrier
	s_waitcnt lgkmcnt(0)
	s_setprio 1
	s_waitcnt lgkmcnt(0)
	v_mfma_f32_16x16x32_bf16 v[50:53], v[2:5], v[18:21], 0
	v_mfma_f32_16x16x32_bf16 v[62:65], v[10:13], v[26:29], 0
	v_mfma_f32_16x16x32_bf16 v[66:69], v[2:5], v[34:37], 0
	v_mfma_f32_16x16x32_bf16 v[70:73], v[10:13], v[34:37], 0
	v_mfma_f32_16x16x32_bf16 v[74:77], v[2:5], v[42:45], 0
	v_mfma_f32_16x16x32_bf16 v[78:81], v[10:13], v[42:45], 0
	v_mfma_f32_16x16x32_bf16 v[50:53], v[6:9], v[22:25], v[50:53]
	v_mfma_f32_16x16x32_bf16 v[54:57], v[10:13], v[18:21], 0
	v_mfma_f32_16x16x32_bf16 v[58:61], v[2:5], v[26:29], 0
	v_mfma_f32_16x16x32_bf16 v[62:65], v[14:17], v[30:33], v[62:65]
	v_mfma_f32_16x16x32_bf16 v[66:69], v[6:9], v[38:41], v[66:69]
	v_mfma_f32_16x16x32_bf16 v[70:73], v[14:17], v[38:41], v[70:73]
	v_mfma_f32_16x16x32_bf16 v[74:77], v[6:9], v[46:49], v[74:77]
	v_mfma_f32_16x16x32_bf16 v[80:83], v[14:17], v[46:49], v[78:81]
	v_mfma_f32_16x16x32_bf16 v[194:197], v[14:17], v[22:25], v[54:57]
	v_mfma_f32_16x16x32_bf16 v[212:215], v[6:9], v[30:33], v[58:61]
	s_setprio 0
	s_barrier
	s_add_i32 s9, 0, 0x14000
	v_lshl_add_u64 v[144:145], s[18:19], 0, v[136:137]
	s_add_i32 s7, s7, s25
	v_add_u32_e32 v0, s9, v147
	v_lshl_add_u64 v[78:79], v[144:145], 0, s[50:51]
	s_mov_b32 m0, s7
	v_lshl_add_u64 v[198:199], s[18:19], 0, v[132:133]
	ds_read_b128 v[84:87], v0
	ds_read_b128 v[88:91], v0 offset:1024
	ds_read_b128 v[92:95], v0 offset:2048
	ds_read_b128 v[96:99], v0 offset:3072
	global_load_lds_dwordx4 v[78:79], off
	v_lshl_add_u64 v[78:79], v[198:199], 0, s[50:51]
	s_add_i32 m0, s7, 0x2000
	s_nop 0
	global_load_lds_dwordx4 v[78:79], off
	s_waitcnt vmcnt(10)
	s_barrier
	s_waitcnt lgkmcnt(0)
	s_setprio 1
	s_waitcnt lgkmcnt(0)
	v_mfma_f32_16x16x32_bf16 v[100:103], v[84:87], v[18:21], 0
	v_mfma_f32_16x16x32_bf16 v[18:21], v[92:95], v[18:21], 0
	v_mfma_f32_16x16x32_bf16 v[104:107], v[88:91], v[22:25], v[100:103]
	v_mfma_f32_16x16x32_bf16 v[18:21], v[96:99], v[22:25], v[18:21]
	v_mfma_f32_16x16x32_bf16 v[22:25], v[84:87], v[26:29], 0
	v_mfma_f32_16x16x32_bf16 v[26:29], v[92:95], v[26:29], 0
	v_mfma_f32_16x16x32_bf16 v[22:25], v[88:91], v[30:33], v[22:25]
	v_mfma_f32_16x16x32_bf16 v[26:29], v[96:99], v[30:33], v[26:29]
	v_mfma_f32_16x16x32_bf16 v[30:33], v[84:87], v[34:37], 0
	v_mfma_f32_16x16x32_bf16 v[34:37], v[92:95], v[34:37], 0
	v_mfma_f32_16x16x32_bf16 v[30:33], v[88:91], v[38:41], v[30:33]
	v_mfma_f32_16x16x32_bf16 v[34:37], v[96:99], v[38:41], v[34:37]
	v_mfma_f32_16x16x32_bf16 v[38:41], v[84:87], v[42:45], 0
	v_mfma_f32_16x16x32_bf16 v[42:45], v[92:95], v[42:45], 0
	v_mfma_f32_16x16x32_bf16 v[38:41], v[88:91], v[46:49], v[38:41]
	v_mfma_f32_16x16x32_bf16 v[42:45], v[96:99], v[46:49], v[42:45]
	s_setprio 0
	v_lshl_add_u64 v[140:141], s[20:21], 0, v[138:139]
	s_mov_b32 m0, s11
	v_lshl_add_u64 v[78:79], v[140:141], 0, s[50:51]
	v_lshl_add_u64 v[142:143], s[20:21], 0, v[134:135]
	s_barrier
	ds_read_b128 v[46:49], v149 offset:16384
	ds_read_b128 v[100:103], v149 offset:17408
	ds_read_b128 v[108:111], v149 offset:18432
	ds_read_b128 v[112:115], v149 offset:19456
	ds_read_b128 v[116:119], v149 offset:20480
	ds_read_b128 v[120:123], v149 offset:21504
	ds_read_b128 v[124:127], v149 offset:22528
	ds_read_b128 v[128:131], v149 offset:23552
	global_load_lds_dwordx4 v[78:79], off
	v_lshl_add_u64 v[78:79], v[142:143], 0, s[50:51]
	s_mov_b32 m0, s57
	s_nop 0
	global_load_lds_dwordx4 v[78:79], off
	s_barrier
	s_waitcnt lgkmcnt(0)
	s_setprio 1
	s_waitcnt lgkmcnt(0)
	v_mfma_f32_16x16x32_bf16 v[150:153], v[2:5], v[46:49], 0
	v_mfma_f32_16x16x32_bf16 v[154:157], v[10:13], v[46:49], 0
	v_mfma_f32_16x16x32_bf16 v[158:161], v[2:5], v[108:111], 0
	v_mfma_f32_16x16x32_bf16 v[166:169], v[2:5], v[116:119], 0
	v_mfma_f32_16x16x32_bf16 v[2:5], v[2:5], v[124:127], 0
	v_mfma_f32_16x16x32_bf16 v[54:57], v[6:9], v[100:103], v[150:153]
	v_mfma_f32_16x16x32_bf16 v[152:155], v[14:17], v[100:103], v[154:157]
	v_mfma_f32_16x16x32_bf16 v[156:159], v[6:9], v[112:115], v[158:161]
	v_mfma_f32_16x16x32_bf16 v[166:169], v[6:9], v[120:123], v[166:169]
	v_mfma_f32_16x16x32_bf16 v[2:5], v[6:9], v[128:131], v[2:5]
	v_mfma_f32_16x16x32_bf16 v[6:9], v[10:13], v[124:127], 0
	v_mfma_f32_16x16x32_bf16 v[162:165], v[10:13], v[108:111], 0
	v_mfma_f32_16x16x32_bf16 v[170:173], v[10:13], v[116:119], 0
	v_mfma_f32_16x16x32_bf16 v[6:9], v[14:17], v[128:131], v[6:9]
	v_mfma_f32_16x16x32_bf16 v[160:163], v[14:17], v[112:115], v[162:165]
	v_mfma_f32_16x16x32_bf16 v[170:173], v[14:17], v[120:123], v[170:173]
	s_setprio 0
	s_barrier
	s_add_u32 s14, s18, 0x40100
	s_addc_u32 s15, s19, 0
	s_add_i32 s7, s9, s25
	v_lshl_add_u64 v[10:11], s[14:15], 0, v[136:137]
	s_mov_b32 m0, s7
	s_nop 0
	global_load_lds_dwordx4 v[10:11], off
	v_lshl_add_u64 v[10:11], s[14:15], 0, v[132:133]
	s_add_i32 m0, s7, 0x2000
	s_nop 0
	global_load_lds_dwordx4 v[10:11], off
	s_barrier
	s_setprio 1
	v_mfma_f32_16x16x32_bf16 v[10:13], v[84:87], v[46:49], 0
	v_mfma_f32_16x16x32_bf16 v[174:177], v[88:91], v[100:103], v[10:13]
	v_mfma_f32_16x16x32_bf16 v[10:13], v[92:95], v[46:49], 0
	v_mfma_f32_16x16x32_bf16 v[178:181], v[96:99], v[100:103], v[10:13]
	v_mfma_f32_16x16x32_bf16 v[10:13], v[84:87], v[108:111], 0
	v_mfma_f32_16x16x32_bf16 v[182:185], v[88:91], v[112:115], v[10:13]
	v_mfma_f32_16x16x32_bf16 v[10:13], v[92:95], v[108:111], 0
	v_mfma_f32_16x16x32_bf16 v[186:189], v[96:99], v[112:115], v[10:13]
	v_mfma_f32_16x16x32_bf16 v[10:13], v[84:87], v[116:119], 0
	v_mfma_f32_16x16x32_bf16 v[190:193], v[88:91], v[120:123], v[10:13]
	v_mfma_f32_16x16x32_bf16 v[10:13], v[92:95], v[116:119], 0
	v_mfma_f32_16x16x32_bf16 v[200:203], v[96:99], v[120:123], v[10:13]
	v_mfma_f32_16x16x32_bf16 v[10:13], v[84:87], v[124:127], 0
	v_mfma_f32_16x16x32_bf16 v[204:207], v[88:91], v[128:131], v[10:13]
	v_mfma_f32_16x16x32_bf16 v[10:13], v[92:95], v[124:127], 0
	v_mfma_f32_16x16x32_bf16 v[208:211], v[96:99], v[128:131], v[10:13]
	s_setprio 0
	s_add_i32 s7, 0, 0x18000
	v_add_u32_e32 v0, s7, v147
	s_barrier
	s_nop 2
	ds_read_b128 v[10:13], v0
	ds_read_b128 v[14:17], v0 offset:1024
	v_mov_b64_e32 v[164:165], v[220:221]
	ds_read_b128 v[218:221], v0 offset:2048
	v_mov_b64_e32 v[58:59], v[222:223]
	ds_read_b128 v[222:225], v0 offset:3072
	s_add_u32 s14, s20, 0x40100
	s_addc_u32 s15, s21, 0
	s_mov_b32 m0, s58
	v_lshl_add_u64 v[78:79], s[14:15], 0, v[138:139]
	ds_read_b128 v[46:49], v149 offset:32768
	ds_read_b128 v[88:91], v149 offset:33792
	ds_read_b128 v[96:99], v149 offset:34816
	ds_read_b128 v[226:229], v149 offset:35840
	ds_read_b128 v[230:233], v149 offset:36864
	ds_read_b128 v[234:237], v149 offset:37888
	ds_read_b128 v[238:241], v149 offset:38912
	ds_read_b128 v[242:245], v149 offset:39936
	global_load_lds_dwordx4 v[78:79], off
	v_lshl_add_u64 v[78:79], s[14:15], 0, v[134:135]
	s_mov_b32 m0, s59
	v_mov_b32_e32 v151, v1
	global_load_lds_dwordx4 v[78:79], off
	s_waitcnt lgkmcnt(8)
	s_barrier
	s_waitcnt lgkmcnt(0)
	s_setprio 1
	s_waitcnt lgkmcnt(0)
	v_mfma_f32_16x16x32_bf16 v[50:53], v[10:13], v[46:49], v[50:53]
	v_mfma_f32_16x16x32_bf16 v[124:127], v[14:17], v[88:91], v[50:53]
	v_mfma_f32_16x16x32_bf16 v[50:53], v[218:221], v[46:49], v[194:197]
	v_mfma_f32_16x16x32_bf16 v[116:119], v[222:225], v[88:91], v[50:53]
	v_mfma_f32_16x16x32_bf16 v[50:53], v[10:13], v[96:99], v[212:215]
	v_mfma_f32_16x16x32_bf16 v[108:111], v[14:17], v[226:229], v[50:53]
	v_mfma_f32_16x16x32_bf16 v[50:53], v[218:221], v[96:99], v[62:65]
	v_mfma_f32_16x16x32_bf16 v[100:103], v[222:225], v[226:229], v[50:53]
	v_mfma_f32_16x16x32_bf16 v[50:53], v[10:13], v[230:233], v[66:69]
	v_mfma_f32_16x16x32_bf16 v[92:95], v[14:17], v[234:237], v[50:53]
	v_mfma_f32_16x16x32_bf16 v[50:53], v[218:221], v[230:233], v[70:73]
	v_mfma_f32_16x16x32_bf16 v[84:87], v[222:225], v[234:237], v[50:53]
	v_mfma_f32_16x16x32_bf16 v[50:53], v[10:13], v[238:241], v[74:77]
	v_mfma_f32_16x16x32_bf16 v[76:79], v[14:17], v[242:245], v[50:53]
	v_mfma_f32_16x16x32_bf16 v[50:53], v[218:221], v[238:241], v[80:83]
	v_mfma_f32_16x16x32_bf16 v[64:67], v[222:225], v[242:245], v[50:53]
	s_setprio 0
	s_barrier
	s_add_i32 s9, 0, 0x1c000
	s_add_i32 s7, s7, s25
	v_add_u32_e32 v0, s9, v147
	s_nop 1
	v_lshl_add_u64 v[50:51], v[144:145], 0, s[62:63]
	s_mov_b32 m0, s7
	ds_read_b128 v[246:249], v0
	v_mov_b32_e32 v150, v148
	v_mov_b32_e32 v148, v254
	v_mov_b32_e32 v254, v216
	v_mov_b32_e32 v1, v217
	v_mov_b64_e32 v[216:217], v[252:253]
	ds_read_b128 v[250:253], v0 offset:1024
	ds_read_b128 v[194:197], v0 offset:2048
	ds_read_b128 v[212:215], v0 offset:3072
	global_load_lds_dwordx4 v[50:51], off
	v_lshl_add_u64 v[50:51], v[198:199], 0, s[62:63]
	s_add_i32 m0, s7, 0x2000
	s_nop 0
	global_load_lds_dwordx4 v[50:51], off
	s_waitcnt vmcnt(10)
	s_barrier
; template <class Epi, class Sched>
; __device__ __forceinline__ void gemm_phase(PG8_LAS unsigned char* lds, const Gemm g, const Sched& S, const Epi& E, int wv) {
;     ...
;         if constexpr (Epi::HOIST) if (pre) { PG8_ITER_F(0); t0_ = 2; }
	s_waitcnt lgkmcnt(0)
	s_setprio 1
	s_waitcnt lgkmcnt(0)
	v_mfma_f32_16x16x32_bf16 v[18:21], v[194:197], v[46:49], v[18:21]
	v_mfma_f32_16x16x32_bf16 v[120:123], v[212:215], v[88:91], v[18:21]
	v_mfma_f32_16x16x32_bf16 v[18:21], v[246:249], v[96:99], v[22:25]
	v_mfma_f32_16x16x32_bf16 v[112:115], v[250:253], v[226:229], v[18:21]
	v_mfma_f32_16x16x32_bf16 v[18:21], v[194:197], v[96:99], v[26:29]
	v_mfma_f32_16x16x32_bf16 v[50:53], v[246:249], v[46:49], v[104:107]
	v_mfma_f32_16x16x32_bf16 v[104:107], v[212:215], v[226:229], v[18:21]
	v_mfma_f32_16x16x32_bf16 v[18:21], v[246:249], v[230:233], v[30:33]
	v_mfma_f32_16x16x32_bf16 v[96:99], v[250:253], v[234:237], v[18:21]
	v_mfma_f32_16x16x32_bf16 v[18:21], v[194:197], v[230:233], v[34:37]
	v_mfma_f32_16x16x32_bf16 v[128:131], v[250:253], v[88:91], v[50:53]
	v_mfma_f32_16x16x32_bf16 v[88:91], v[212:215], v[234:237], v[18:21]
	v_mfma_f32_16x16x32_bf16 v[18:21], v[246:249], v[238:241], v[38:41]
	v_mfma_f32_16x16x32_bf16 v[80:83], v[250:253], v[242:245], v[18:21]
	v_mfma_f32_16x16x32_bf16 v[18:21], v[194:197], v[238:241], v[42:45]
	v_mfma_f32_16x16x32_bf16 v[72:75], v[212:215], v[242:245], v[18:21]
	s_setprio 0
	s_mov_b32 m0, s60
	s_nop 4
	v_lshl_add_u64 v[18:19], v[140:141], 0, s[62:63]
	s_barrier
	ds_read_b128 v[24:27], v149 offset:49152
	ds_read_b128 v[32:35], v149 offset:50176
	ds_read_b128 v[40:43], v149 offset:51200
	ds_read_b128 v[226:229], v149 offset:52224
	ds_read_b128 v[230:233], v149 offset:53248
	ds_read_b128 v[234:237], v149 offset:54272
	ds_read_b128 v[238:241], v149 offset:55296
	ds_read_b128 v[242:245], v149 offset:56320
	global_load_lds_dwordx4 v[18:19], off
	v_lshl_add_u64 v[18:19], v[142:143], 0, s[62:63]
	s_mov_b32 m0, s61
	s_nop 0
	global_load_lds_dwordx4 v[18:19], off
	s_barrier
	s_waitcnt lgkmcnt(0)
	s_setprio 1
	s_waitcnt lgkmcnt(0)
	v_mfma_f32_16x16x32_bf16 v[18:21], v[10:13], v[24:27], v[54:57]
	v_mfma_f32_16x16x32_bf16 v[60:63], v[14:17], v[32:35], v[18:21]
	v_mfma_f32_16x16x32_bf16 v[18:21], v[218:221], v[24:27], v[152:155]
	v_mfma_f32_16x16x32_bf16 v[52:55], v[222:225], v[32:35], v[18:21]
	v_mfma_f32_16x16x32_bf16 v[18:21], v[10:13], v[40:43], v[156:159]
	v_mfma_f32_16x16x32_bf16 v[44:47], v[14:17], v[226:229], v[18:21]
	v_mfma_f32_16x16x32_bf16 v[18:21], v[218:221], v[40:43], v[160:163]
	v_mfma_f32_16x16x32_bf16 v[36:39], v[222:225], v[226:229], v[18:21]
	v_mfma_f32_16x16x32_bf16 v[18:21], v[10:13], v[230:233], v[166:169]
	v_mfma_f32_16x16x32_bf16 v[2:5], v[10:13], v[238:241], v[2:5]
	v_mfma_f32_16x16x32_bf16 v[28:31], v[14:17], v[234:237], v[18:21]
	v_mfma_f32_16x16x32_bf16 v[18:21], v[218:221], v[230:233], v[170:173]
	v_mfma_f32_16x16x32_bf16 v[12:15], v[14:17], v[242:245], v[2:5]
	v_mfma_f32_16x16x32_bf16 v[2:5], v[218:221], v[238:241], v[6:9]
	v_mov_b64_e32 v[220:221], v[164:165]
	v_mfma_f32_16x16x32_bf16 v[20:23], v[222:225], v[234:237], v[18:21]
	v_mfma_f32_16x16x32_bf16 v[4:7], v[222:225], v[242:245], v[2:5]
	v_mov_b64_e32 v[222:223], v[58:59]
	s_setprio 0
	s_barrier
	s_add_u32 s14, s18, 0x40180
	s_addc_u32 s15, s19, 0
	s_add_i32 s7, s9, s25
	v_lshl_add_u64 v[2:3], s[14:15], 0, v[136:137]
	s_mov_b32 m0, s7
	s_nop 0
	global_load_lds_dwordx4 v[2:3], off
	v_lshl_add_u64 v[2:3], s[14:15], 0, v[132:133]
	s_add_i32 m0, s7, 0x2000
	s_nop 0
	global_load_lds_dwordx4 v[2:3], off
	s_waitcnt vmcnt(8)
	s_barrier
	s_setprio 1
	v_mfma_f32_16x16x32_bf16 v[8:11], v[246:249], v[24:27], v[174:177]
	v_mfma_f32_16x16x32_bf16 v[68:71], v[250:253], v[32:35], v[8:11]
	v_mfma_f32_16x16x32_bf16 v[8:11], v[194:197], v[24:27], v[178:181]
	v_mfma_f32_16x16x32_bf16 v[56:59], v[212:215], v[32:35], v[8:11]
	v_mfma_f32_16x16x32_bf16 v[8:11], v[246:249], v[40:43], v[182:185]
	v_mfma_f32_16x16x32_bf16 v[48:51], v[250:253], v[226:229], v[8:11]
	v_mfma_f32_16x16x32_bf16 v[8:11], v[194:197], v[40:43], v[186:189]
	v_mfma_f32_16x16x32_bf16 v[40:43], v[212:215], v[226:229], v[8:11]
	v_mfma_f32_16x16x32_bf16 v[8:11], v[246:249], v[230:233], v[190:193]
	v_mfma_f32_16x16x32_bf16 v[32:35], v[250:253], v[234:237], v[8:11]
	v_mfma_f32_16x16x32_bf16 v[8:11], v[194:197], v[230:233], v[200:203]
	v_mfma_f32_16x16x32_bf16 v[24:27], v[212:215], v[234:237], v[8:11]
	v_mfma_f32_16x16x32_bf16 v[8:11], v[246:249], v[238:241], v[204:207]
	v_mfma_f32_16x16x32_bf16 v[16:19], v[250:253], v[242:245], v[8:11]
	v_mov_b64_e32 v[252:253], v[216:217]
	v_mov_b32_e32 v217, v1
	v_mov_b32_e32 v216, v254
	v_mfma_f32_16x16x32_bf16 v[8:11], v[194:197], v[238:241], v[208:211]
	v_mov_b32_e32 v254, v148
	v_mov_b32_e32 v148, v150
	v_mov_b32_e32 v1, v151
	v_mfma_f32_16x16x32_bf16 v[8:11], v[212:215], v[242:245], v[8:11]
	s_setprio 0
	s_barrier
	s_mov_b32 s22, 2
	s_branch .LBB0_527

; template <class Epi, class Sched>
; __device__ __forceinline__ void gemm_phase(PG8_LAS unsigned char* lds, const Gemm g, const Sched& S, const Epi& E, int wv) {
;     ...
;     for (;;) {
;         const bool has_next = S.next(ui + 1, nxt);
;         const char* nA = has_next ? (const char*)g.A + (size_t)nxt.pm * tstepA : cA; const char* nB = has_next ? (const char*)g.Bt + (size_t)nxt.pn * tstep : cB;
;         int t0_ = 0;
;         if constexpr (Epi::HOIST) if (pre) { PG8_ITER_F(0); t0_ = 2; }
;         for (int t = t0_; t < nt; t += 2) { PG8_ITER_N(t); }
.LBB0_528:
	s_add_u32 s20, s81, s46
	s_addc_u32 s21, s82, 0
	s_add_u32 s83, s79, s46
	s_addc_u32 s84, s80, 0
	s_add_i32 s85, 0, 0x10000
	v_add_u32_e32 v0, s85, v147
	ds_read_b128 v[150:153], v0
	ds_read_b128 v[154:157], v0 offset:1024
	ds_read_b128 v[158:161], v0 offset:2048
	ds_read_b128 v[162:165], v0 offset:3072
	s_cmp_eq_u32 s46, s18
	s_cselect_b32 s23, s9, s21
	s_cselect_b32 s22, s76, s20
	s_cselect_b32 s21, s7, s84
	s_cselect_b32 s20, s77, s83
	s_add_i32 s84, s11, 0xc000
	v_lshl_add_u64 v[140:141], v[144:145], 0, s[46:47]
	s_mov_b32 m0, s84
	s_add_i32 s83, s11, 0xe000
	ds_read_b128 v[166:169], v149
	ds_read_b128 v[170:173], v149 offset:1024
	ds_read_b128 v[174:177], v149 offset:2048
	ds_read_b128 v[178:181], v149 offset:3072
	ds_read_b128 v[182:185], v149 offset:4096
	ds_read_b128 v[186:189], v149 offset:5120
	ds_read_b128 v[190:193], v149 offset:6144
	ds_read_b128 v[194:197], v149 offset:7168
	global_load_lds_dwordx4 v[140:141], off
	v_lshl_add_u64 v[140:141], v[2:3], 0, s[46:47]
	s_mov_b32 m0, s83
	s_nop 0
	global_load_lds_dwordx4 v[140:141], off
	s_waitcnt lgkmcnt(8)
	s_barrier
	s_waitcnt lgkmcnt(0)
	s_setprio 1
	s_waitcnt lgkmcnt(0)
	v_mfma_f32_16x16x32_bf16 v[124:127], v[150:153], v[166:169], v[124:127]
	v_mfma_f32_16x16x32_bf16 v[116:119], v[158:161], v[166:169], v[116:119]
	v_mfma_f32_16x16x32_bf16 v[108:111], v[150:153], v[174:177], v[108:111]
	v_mfma_f32_16x16x32_bf16 v[100:103], v[158:161], v[174:177], v[100:103]
	v_mfma_f32_16x16x32_bf16 v[92:95], v[150:153], v[182:185], v[92:95]
	v_mfma_f32_16x16x32_bf16 v[84:87], v[158:161], v[182:185], v[84:87]
	v_mfma_f32_16x16x32_bf16 v[76:79], v[150:153], v[190:193], v[76:79]
	v_mfma_f32_16x16x32_bf16 v[64:67], v[158:161], v[190:193], v[64:67]
	v_mfma_f32_16x16x32_bf16 v[124:127], v[154:157], v[170:173], v[124:127]
	v_mfma_f32_16x16x32_bf16 v[116:119], v[162:165], v[170:173], v[116:119]
	v_mfma_f32_16x16x32_bf16 v[108:111], v[154:157], v[178:181], v[108:111]
	v_mfma_f32_16x16x32_bf16 v[100:103], v[162:165], v[178:181], v[100:103]
	v_mfma_f32_16x16x32_bf16 v[92:95], v[154:157], v[186:189], v[92:95]
	v_mfma_f32_16x16x32_bf16 v[84:87], v[162:165], v[186:189], v[84:87]
	v_mfma_f32_16x16x32_bf16 v[76:79], v[154:157], v[194:197], v[76:79]
	v_mfma_f32_16x16x32_bf16 v[64:67], v[162:165], v[194:197], v[64:67]
	s_setprio 0
	s_barrier
	s_add_i32 s88, 0, 0x14000
	s_add_i32 s85, s85, s25
	v_add_u32_e32 v0, s88, v147
	v_lshl_add_u64 v[140:141], s[20:21], 0, v[136:137]
	s_mov_b32 m0, s85
	ds_read_b128 v[200:203], v0
	ds_read_b128 v[204:207], v0 offset:1024
	ds_read_b128 v[208:211], v0 offset:2048
	ds_read_b128 v[212:215], v0 offset:3072
	global_load_lds_dwordx4 v[140:141], off
	v_lshl_add_u64 v[142:143], s[20:21], 0, v[132:133]
	s_add_i32 m0, s85, 0x2000
	s_nop 0
	global_load_lds_dwordx4 v[142:143], off
	s_waitcnt vmcnt(10)
	s_barrier
	s_waitcnt lgkmcnt(0)
	s_setprio 1
	s_waitcnt lgkmcnt(0)
	v_mfma_f32_16x16x32_bf16 v[128:131], v[200:203], v[166:169], v[128:131]
	v_mfma_f32_16x16x32_bf16 v[120:123], v[208:211], v[166:169], v[120:123]
	v_mfma_f32_16x16x32_bf16 v[112:115], v[200:203], v[174:177], v[112:115]
	v_mfma_f32_16x16x32_bf16 v[104:107], v[208:211], v[174:177], v[104:107]
	v_mfma_f32_16x16x32_bf16 v[96:99], v[200:203], v[182:185], v[96:99]
	v_mfma_f32_16x16x32_bf16 v[88:91], v[208:211], v[182:185], v[88:91]
	v_mfma_f32_16x16x32_bf16 v[80:83], v[200:203], v[190:193], v[80:83]
	v_mfma_f32_16x16x32_bf16 v[72:75], v[208:211], v[190:193], v[72:75]
	v_mfma_f32_16x16x32_bf16 v[128:131], v[204:207], v[170:173], v[128:131]
	v_mfma_f32_16x16x32_bf16 v[120:123], v[212:215], v[170:173], v[120:123]
	v_mfma_f32_16x16x32_bf16 v[112:115], v[204:207], v[178:181], v[112:115]
	v_mfma_f32_16x16x32_bf16 v[104:107], v[212:215], v[178:181], v[104:107]
	v_mfma_f32_16x16x32_bf16 v[96:99], v[204:207], v[186:189], v[96:99]
	v_mfma_f32_16x16x32_bf16 v[88:91], v[212:215], v[186:189], v[88:91]
	v_mfma_f32_16x16x32_bf16 v[80:83], v[204:207], v[194:197], v[80:83]
	v_mfma_f32_16x16x32_bf16 v[72:75], v[212:215], v[194:197], v[72:75]
	s_setprio 0
	s_mov_b32 m0, s11
	v_lshl_add_u64 v[198:199], s[22:23], 0, v[138:139]
	s_barrier
	ds_read_b128 v[166:169], v149 offset:16384
	ds_read_b128 v[170:173], v149 offset:17408
	ds_read_b128 v[174:177], v149 offset:18432
	ds_read_b128 v[178:181], v149 offset:19456
	ds_read_b128 v[182:185], v149 offset:20480
	ds_read_b128 v[186:189], v149 offset:21504
	ds_read_b128 v[190:193], v149 offset:22528
	ds_read_b128 v[194:197], v149 offset:23552
	global_load_lds_dwordx4 v[198:199], off
	v_lshl_add_u64 v[218:219], s[22:23], 0, v[134:135]
	s_mov_b32 m0, s57
	s_nop 0
	global_load_lds_dwordx4 v[218:219], off
	s_barrier
	s_waitcnt lgkmcnt(0)
	s_setprio 1
	s_waitcnt lgkmcnt(0)
	v_mfma_f32_16x16x32_bf16 v[60:63], v[150:153], v[166:169], v[60:63]
	v_mfma_f32_16x16x32_bf16 v[52:55], v[158:161], v[166:169], v[52:55]
	v_mfma_f32_16x16x32_bf16 v[44:47], v[150:153], v[174:177], v[44:47]
	v_mfma_f32_16x16x32_bf16 v[36:39], v[158:161], v[174:177], v[36:39]
	v_mfma_f32_16x16x32_bf16 v[28:31], v[150:153], v[182:185], v[28:31]
	v_mfma_f32_16x16x32_bf16 v[20:23], v[158:161], v[182:185], v[20:23]
	v_mfma_f32_16x16x32_bf16 v[12:15], v[150:153], v[190:193], v[12:15]
	v_mfma_f32_16x16x32_bf16 v[4:7], v[158:161], v[190:193], v[4:7]
	v_mfma_f32_16x16x32_bf16 v[60:63], v[154:157], v[170:173], v[60:63]
	v_mfma_f32_16x16x32_bf16 v[52:55], v[162:165], v[170:173], v[52:55]
	v_mfma_f32_16x16x32_bf16 v[44:47], v[154:157], v[178:181], v[44:47]
	v_mfma_f32_16x16x32_bf16 v[36:39], v[162:165], v[178:181], v[36:39]
	v_mfma_f32_16x16x32_bf16 v[28:31], v[154:157], v[186:189], v[28:31]
	v_mfma_f32_16x16x32_bf16 v[20:23], v[162:165], v[186:189], v[20:23]
	v_mfma_f32_16x16x32_bf16 v[12:15], v[154:157], v[194:197], v[12:15]
	v_mfma_f32_16x16x32_bf16 v[4:7], v[162:165], v[194:197], v[4:7]
	s_setprio 0
	s_barrier
	s_add_u32 s86, s20, 0x40000
	s_addc_u32 s87, s21, 0
	s_add_i32 s85, s88, s25
	v_lshl_add_u64 v[150:151], s[86:87], 0, v[136:137]
	s_mov_b32 m0, s85
	s_nop 0
	global_load_lds_dwordx4 v[150:151], off
	v_lshl_add_u64 v[150:151], s[86:87], 0, v[132:133]
	s_add_i32 m0, s85, 0x2000
	s_nop 0
	global_load_lds_dwordx4 v[150:151], off
	s_waitcnt vmcnt(8)
	s_barrier
	s_setprio 1
	v_mfma_f32_16x16x32_bf16 v[68:71], v[200:203], v[166:169], v[68:71]
	v_mfma_f32_16x16x32_bf16 v[56:59], v[208:211], v[166:169], v[56:59]
	v_mfma_f32_16x16x32_bf16 v[48:51], v[200:203], v[174:177], v[48:51]
	v_mfma_f32_16x16x32_bf16 v[40:43], v[208:211], v[174:177], v[40:43]
	v_mfma_f32_16x16x32_bf16 v[32:35], v[200:203], v[182:185], v[32:35]
	v_mfma_f32_16x16x32_bf16 v[24:27], v[208:211], v[182:185], v[24:27]
	v_mfma_f32_16x16x32_bf16 v[16:19], v[200:203], v[190:193], v[16:19]
	v_mfma_f32_16x16x32_bf16 v[8:11], v[208:211], v[190:193], v[8:11]
	v_mfma_f32_16x16x32_bf16 v[68:71], v[204:207], v[170:173], v[68:71]
	v_mfma_f32_16x16x32_bf16 v[56:59], v[212:215], v[170:173], v[56:59]
	v_mfma_f32_16x16x32_bf16 v[48:51], v[204:207], v[178:181], v[48:51]
	v_mfma_f32_16x16x32_bf16 v[40:43], v[212:215], v[178:181], v[40:43]
	v_mfma_f32_16x16x32_bf16 v[32:35], v[204:207], v[186:189], v[32:35]
	v_mfma_f32_16x16x32_bf16 v[24:27], v[212:215], v[186:189], v[24:27]
	v_mfma_f32_16x16x32_bf16 v[16:19], v[204:207], v[194:197], v[16:19]
	v_mfma_f32_16x16x32_bf16 v[8:11], v[212:215], v[194:197], v[8:11]
	s_setprio 0
	s_add_i32 s85, 0, 0x18000
	v_add_u32_e32 v0, s85, v147
	s_barrier
	ds_read_b128 v[150:153], v0
	ds_read_b128 v[154:157], v0 offset:1024
	ds_read_b128 v[158:161], v0 offset:2048
	ds_read_b128 v[162:165], v0 offset:3072
	s_add_u32 s22, s22, 0x40000
	s_addc_u32 s23, s23, 0
	s_mov_b32 m0, s58
	v_lshl_add_u64 v[200:201], s[22:23], 0, v[138:139]
	ds_read_b128 v[166:169], v149 offset:32768
	ds_read_b128 v[170:173], v149 offset:33792
	ds_read_b128 v[174:177], v149 offset:34816
	ds_read_b128 v[178:181], v149 offset:35840
	ds_read_b128 v[182:185], v149 offset:36864
	ds_read_b128 v[186:189], v149 offset:37888
	ds_read_b128 v[190:193], v149 offset:38912
	ds_read_b128 v[194:197], v149 offset:39936
	global_load_lds_dwordx4 v[200:201], off
	v_lshl_add_u64 v[200:201], s[22:23], 0, v[134:135]
	s_mov_b32 m0, s59
	s_nop 0
	global_load_lds_dwordx4 v[200:201], off
	s_waitcnt lgkmcnt(8)
	s_barrier
	s_waitcnt lgkmcnt(0)
	s_setprio 1
	s_waitcnt lgkmcnt(0)
	v_mfma_f32_16x16x32_bf16 v[124:127], v[150:153], v[166:169], v[124:127]
	v_mfma_f32_16x16x32_bf16 v[116:119], v[158:161], v[166:169], v[116:119]
	v_mfma_f32_16x16x32_bf16 v[108:111], v[150:153], v[174:177], v[108:111]
	v_mfma_f32_16x16x32_bf16 v[100:103], v[158:161], v[174:177], v[100:103]
	v_mfma_f32_16x16x32_bf16 v[92:95], v[150:153], v[182:185], v[92:95]
	v_mfma_f32_16x16x32_bf16 v[84:87], v[158:161], v[182:185], v[84:87]
	v_mfma_f32_16x16x32_bf16 v[76:79], v[150:153], v[190:193], v[76:79]
	v_mfma_f32_16x16x32_bf16 v[64:67], v[158:161], v[190:193], v[64:67]
	v_mfma_f32_16x16x32_bf16 v[124:127], v[154:157], v[170:173], v[124:127]
	v_mfma_f32_16x16x32_bf16 v[116:119], v[162:165], v[170:173], v[116:119]
	v_mfma_f32_16x16x32_bf16 v[108:111], v[154:157], v[178:181], v[108:111]
	v_mfma_f32_16x16x32_bf16 v[100:103], v[162:165], v[178:181], v[100:103]
	v_mfma_f32_16x16x32_bf16 v[92:95], v[154:157], v[186:189], v[92:95]
	v_mfma_f32_16x16x32_bf16 v[84:87], v[162:165], v[186:189], v[84:87]
	v_mfma_f32_16x16x32_bf16 v[76:79], v[154:157], v[194:197], v[76:79]
	v_mfma_f32_16x16x32_bf16 v[64:67], v[162:165], v[194:197], v[64:67]
	s_setprio 0
	s_barrier
	s_add_i32 s22, 0, 0x1c000
	s_add_i32 s23, s85, s25
	v_add_u32_e32 v0, s22, v147
	v_lshl_add_u64 v[140:141], v[140:141], 0, s[48:49]
	s_mov_b32 m0, s23
	ds_read_b128 v[200:203], v0
	ds_read_b128 v[204:207], v0 offset:1024
	ds_read_b128 v[208:211], v0 offset:2048
	ds_read_b128 v[212:215], v0 offset:3072
	global_load_lds_dwordx4 v[140:141], off
	v_lshl_add_u64 v[140:141], v[142:143], 0, s[48:49]
	s_add_i32 m0, s23, 0x2000
	s_nop 0
	global_load_lds_dwordx4 v[140:141], off
	s_waitcnt vmcnt(10)
	s_barrier
	s_waitcnt lgkmcnt(0)
	s_setprio 1
	s_waitcnt lgkmcnt(0)
	v_mfma_f32_16x16x32_bf16 v[128:131], v[200:203], v[166:169], v[128:131]
	v_mfma_f32_16x16x32_bf16 v[120:123], v[208:211], v[166:169], v[120:123]
	v_mfma_f32_16x16x32_bf16 v[112:115], v[200:203], v[174:177], v[112:115]
	v_mfma_f32_16x16x32_bf16 v[104:107], v[208:211], v[174:177], v[104:107]
	v_mfma_f32_16x16x32_bf16 v[96:99], v[200:203], v[182:185], v[96:99]
	v_mfma_f32_16x16x32_bf16 v[88:91], v[208:211], v[182:185], v[88:91]
	v_mfma_f32_16x16x32_bf16 v[80:83], v[200:203], v[190:193], v[80:83]
	v_mfma_f32_16x16x32_bf16 v[72:75], v[208:211], v[190:193], v[72:75]
	v_mfma_f32_16x16x32_bf16 v[128:131], v[204:207], v[170:173], v[128:131]
	v_mfma_f32_16x16x32_bf16 v[120:123], v[212:215], v[170:173], v[120:123]
	v_mfma_f32_16x16x32_bf16 v[112:115], v[204:207], v[178:181], v[112:115]
	v_mfma_f32_16x16x32_bf16 v[104:107], v[212:215], v[178:181], v[104:107]
	v_mfma_f32_16x16x32_bf16 v[96:99], v[204:207], v[186:189], v[96:99]
	v_mfma_f32_16x16x32_bf16 v[88:91], v[212:215], v[186:189], v[88:91]
	v_mfma_f32_16x16x32_bf16 v[80:83], v[204:207], v[194:197], v[80:83]
	v_mfma_f32_16x16x32_bf16 v[72:75], v[212:215], v[194:197], v[72:75]
	s_setprio 0
	s_mov_b32 m0, s60
	v_lshl_add_u64 v[140:141], v[198:199], 0, s[48:49]
	s_barrier
; DEVI unsigned cvtpk(float lo, float hi) { unsigned r; asm volatile("v_cvt_pk_bf16_f32 %0, %1, %2" : "=v"(r) : "v"(lo), "v"(hi)); return r; }
; DEVI float sigmoidf_(float x) { return __builtin_amdgcn_rcpf(1.f + __expf(-x)); }
;     DEVI void operator()(AccRef acc, const pg8::Unit& u, int wr, int wc, int fr, int fq) const {
;         const int row0 = u.pm * 256 + wr * 64 + fr, col = u.pn * 128 + wc * 32 + 8 * fq;
; #pragma unroll
;         for (int ai = 0; ai < 2; ++ai)
; #pragma unroll
;             for (int m = 0; m < 4; ++m) { bf16_t* rowp = Hm + (size_t)(row0 + ai * 128 + m * 16) * DFF + col; float h[8];
; #pragma unroll
;                 for (int j = 0; j < 8; ++j) { const float gt = acc[ai][0][m][j >> 2][j & 3], up = acc[ai][1][m][j >> 2][j & 3]; h[j] = gt * sigmoidf_(gt) * up; }
;                 u32x4 w; w.x = cvtpk(h[0], h[1]); w.y = cvtpk(h[2], h[3]); w.z = cvtpk(h[4], h[5]); w.w = cvtpk(h[6], h[7]);
;                 if (ai == 0 && m == 0) asm volatile("s_waitcnt vmcnt(0)" ::: "memory");
	ds_read_b128 v[166:169], v149 offset:49152
	ds_read_b128 v[170:173], v149 offset:50176
	ds_read_b128 v[174:177], v149 offset:51200
	ds_read_b128 v[178:181], v149 offset:52224
	ds_read_b128 v[182:185], v149 offset:53248
	ds_read_b128 v[186:189], v149 offset:54272
	ds_read_b128 v[190:193], v149 offset:55296
	ds_read_b128 v[194:197], v149 offset:56320
	global_load_lds_dwordx4 v[140:141], off
	v_lshl_add_u64 v[140:141], v[218:219], 0, s[48:49]
	s_mov_b32 m0, s61
	s_nop 0
	global_load_lds_dwordx4 v[140:141], off
	s_barrier
	s_waitcnt lgkmcnt(0)
	s_setprio 1
	s_waitcnt lgkmcnt(0)
	v_mfma_f32_16x16x32_bf16 v[60:63], v[150:153], v[166:169], v[60:63]
	v_mfma_f32_16x16x32_bf16 v[52:55], v[158:161], v[166:169], v[52:55]
	v_mfma_f32_16x16x32_bf16 v[44:47], v[150:153], v[174:177], v[44:47]
	v_mfma_f32_16x16x32_bf16 v[36:39], v[158:161], v[174:177], v[36:39]
	v_mfma_f32_16x16x32_bf16 v[28:31], v[150:153], v[182:185], v[28:31]
	v_mfma_f32_16x16x32_bf16 v[20:23], v[158:161], v[182:185], v[20:23]
	v_mfma_f32_16x16x32_bf16 v[12:15], v[150:153], v[190:193], v[12:15]
	v_mfma_f32_16x16x32_bf16 v[4:7], v[158:161], v[190:193], v[4:7]
	v_mfma_f32_16x16x32_bf16 v[60:63], v[154:157], v[170:173], v[60:63]
	v_mfma_f32_16x16x32_bf16 v[52:55], v[162:165], v[170:173], v[52:55]
	v_mfma_f32_16x16x32_bf16 v[44:47], v[154:157], v[178:181], v[44:47]
	v_mfma_f32_16x16x32_bf16 v[36:39], v[162:165], v[178:181], v[36:39]
	v_mfma_f32_16x16x32_bf16 v[28:31], v[154:157], v[186:189], v[28:31]
	v_mfma_f32_16x16x32_bf16 v[20:23], v[162:165], v[186:189], v[20:23]
	v_mfma_f32_16x16x32_bf16 v[12:15], v[154:157], v[194:197], v[12:15]
	v_mfma_f32_16x16x32_bf16 v[4:7], v[162:165], v[194:197], v[4:7]
	s_setprio 0
	s_barrier
	s_add_u32 s20, s20, 0x40080
	s_addc_u32 s21, s21, 0
	s_add_i32 s22, s22, s25
	v_lshl_add_u64 v[140:141], s[20:21], 0, v[136:137]
	s_mov_b32 m0, s22
	s_nop 0
	global_load_lds_dwordx4 v[140:141], off
	v_lshl_add_u64 v[140:141], s[20:21], 0, v[132:133]
	s_add_i32 m0, s22, 0x2000
	s_nop 0
	global_load_lds_dwordx4 v[140:141], off
	s_waitcnt vmcnt(8)
	s_barrier
	s_setprio 1
	v_mfma_f32_16x16x32_bf16 v[68:71], v[200:203], v[166:169], v[68:71]
	v_mfma_f32_16x16x32_bf16 v[56:59], v[208:211], v[166:169], v[56:59]
	v_mfma_f32_16x16x32_bf16 v[48:51], v[200:203], v[174:177], v[48:51]
	v_mfma_f32_16x16x32_bf16 v[40:43], v[208:211], v[174:177], v[40:43]
	v_mfma_f32_16x16x32_bf16 v[32:35], v[200:203], v[182:185], v[32:35]
	v_mfma_f32_16x16x32_bf16 v[24:27], v[208:211], v[182:185], v[24:27]
	v_mfma_f32_16x16x32_bf16 v[16:19], v[200:203], v[190:193], v[16:19]
	v_mfma_f32_16x16x32_bf16 v[8:11], v[208:211], v[190:193], v[8:11]
	v_mfma_f32_16x16x32_bf16 v[68:71], v[204:207], v[170:173], v[68:71]
	v_mfma_f32_16x16x32_bf16 v[56:59], v[212:215], v[170:173], v[56:59]
	v_mfma_f32_16x16x32_bf16 v[48:51], v[204:207], v[178:181], v[48:51]
	v_mfma_f32_16x16x32_bf16 v[40:43], v[212:215], v[178:181], v[40:43]
	v_mfma_f32_16x16x32_bf16 v[32:35], v[204:207], v[186:189], v[32:35]
	v_mfma_f32_16x16x32_bf16 v[24:27], v[212:215], v[186:189], v[24:27]
	v_mfma_f32_16x16x32_bf16 v[16:19], v[204:207], v[194:197], v[16:19]
	v_mfma_f32_16x16x32_bf16 v[8:11], v[212:215], v[194:197], v[8:11]
	s_setprio 0
	s_add_i32 s78, s78, 2
	s_add_u32 s79, s79, 0x100
	s_addc_u32 s80, s80, 0
	s_add_u32 s81, s81, 0x100
	s_addc_u32 s82, s82, 0
	s_add_u32 s18, s18, 0xffffff00
	s_addc_u32 s19, s19, -1
	v_lshl_add_u64 v[2:3], v[2:3], 0, s[50:51]
	s_cmp_gt_u32 s78, 13
	v_lshl_add_u64 v[144:145], v[144:145], 0, s[50:51]
	s_barrier
	s_cbranch_scc0 .LBB0_528
	s_add_u32 s18, s76, 0x40080
	s_addc_u32 s19, s9, 0
	s_mov_b32 m0, s84
	v_lshl_add_u64 v[2:3], s[18:19], 0, v[138:139]
	global_load_lds_dwordx4 v[2:3], off
	v_lshl_add_u64 v[2:3], s[18:19], 0, v[134:135]
	s_mov_b32 m0, s83
	v_lshl_or_b32 v140, s75, 7, v148
	global_load_lds_dwordx4 v[2:3], off
	v_mul_f32_e32 v2, 0xbfb8aa3b, v124
	v_exp_f32_e32 v142, v2
	v_mul_f32_e32 v2, 0xbfb8aa3b, v125
	v_exp_f32_e32 v143, v2
	v_lshl_add_u32 v0, s10, 8, v146
	v_add_f32_e32 v142, 1.0, v142
	v_rcp_f32_e32 v144, v142
	v_add_f32_e32 v142, 1.0, v143
	v_rcp_f32_e32 v145, v142
	v_ashrrev_i32_e32 v141, 31, v140
	v_mul_f32_e32 v124, v124, v144
	v_mul_f32_e32 v124, v124, v128
	v_mul_f32_e32 v128, 0xbfb8aa3b, v126
	v_mul_f32_e32 v144, 0xbfb8aa3b, v127
	v_exp_f32_e32 v128, v128
	v_exp_f32_e32 v144, v144
	v_mul_f32_e32 v125, v125, v145
	v_mul_f32_e32 v125, v125, v129
	v_add_f32_e32 v128, 1.0, v128
	v_add_f32_e32 v129, 1.0, v144
	v_mul_f32_e32 v144, 0xbfb8aa3b, v116
	v_rcp_f32_e32 v128, v128
	v_exp_f32_e32 v144, v144
	v_rcp_f32_e32 v129, v129
	v_mov_b64_e32 v[2:3], s[68:69]
	v_mul_f32_e32 v126, v126, v128
	v_add_f32_e32 v128, 1.0, v144
	v_mul_f32_e32 v127, v127, v129
	v_rcp_f32_e32 v128, v128
	v_mul_f32_e32 v129, 0xbfb8aa3b, v117
	v_exp_f32_e32 v129, v129
	v_mad_i64_i32 v[142:143], s[18:19], v0, s3, v[2:3]
	v_mul_f32_e32 v116, v116, v128
	v_mul_f32_e32 v120, v116, v120
	v_add_f32_e32 v116, 1.0, v129
	v_mul_f32_e32 v128, 0xbfb8aa3b, v118
	v_rcp_f32_e32 v116, v116
	v_exp_f32_e32 v128, v128
	v_mul_f32_e32 v129, 0xbfb8aa3b, v119
	v_exp_f32_e32 v129, v129
	v_mul_f32_e32 v116, v117, v116
	v_add_f32_e32 v117, 1.0, v128
	v_rcp_f32_e32 v117, v117
	v_mul_f32_e32 v121, v116, v121
	v_add_f32_e32 v128, 1.0, v129
	v_rcp_f32_e32 v128, v128
	v_mul_f32_e32 v116, v118, v117
	v_cvt_pk_bf16_f32 v118, v124, v125
	v_mul_f32_e32 v124, 0xbfb8aa3b, v108
	v_exp_f32_e32 v124, v124
	v_mul_f32_e32 v125, 0xbfb8aa3b, v109
	v_exp_f32_e32 v125, v125
	v_mul_f32_e32 v129, v116, v122
	v_add_f32_e32 v124, 1.0, v124
	v_rcp_f32_e32 v124, v124
	v_mul_f32_e32 v116, v119, v128
	v_mul_f32_e32 v128, v116, v123
	v_lshlrev_b64 v[116:117], 1, v[140:141]
	v_lshl_add_u64 v[122:123], v[142:143], 0, v[116:117]
	v_add_f32_e32 v125, 1.0, v125
	v_mul_f32_e32 v108, v108, v124
	v_mul_f32_e32 v126, v126, v130
	v_mul_f32_e32 v127, v127, v131
	v_cvt_pk_bf16_f32 v119, v126, v127
	v_cvt_pk_bf16_f32 v120, v120, v121
	v_cvt_pk_bf16_f32 v121, v129, v128
	s_waitcnt vmcnt(0)
; DEVI unsigned cvtpk(float lo, float hi) { unsigned r; asm volatile("v_cvt_pk_bf16_f32 %0, %1, %2" : "=v"(r) : "v"(lo), "v"(hi)); return r; }
; DEVI float sigmoidf_(float x) { return __builtin_amdgcn_rcpf(1.f + __expf(-x)); }
;     DEVI void operator()(AccRef acc, const pg8::Unit& u, int wr, int wc, int fr, int fq) const {
;         const int row0 = u.pm * 256 + wr * 64 + fr, col = u.pn * 128 + wc * 32 + 8 * fq;
; #pragma unroll
;         for (int ai = 0; ai < 2; ++ai)
; #pragma unroll
;             for (int m = 0; m < 4; ++m) { bf16_t* rowp = Hm + (size_t)(row0 + ai * 128 + m * 16) * DFF + col; float h[8];
; #pragma unroll
;                 for (int j = 0; j < 8; ++j) { const float gt = acc[ai][0][m][j >> 2][j & 3], up = acc[ai][1][m][j >> 2][j & 3]; h[j] = gt * sigmoidf_(gt) * up; }
;                 u32x4 w; w.x = cvtpk(h[0], h[1]); w.y = cvtpk(h[2], h[3]); w.z = cvtpk(h[4], h[5]); w.w = cvtpk(h[6], h[7]);
;                 if (ai == 0 && m == 0) asm volatile("s_waitcnt vmcnt(0)" ::: "memory");
;                 __builtin_nontemporal_store(w, (u32x4*)rowp); }
	v_rcp_f32_e32 v125, v125
	flat_store_dwordx4 v[122:123], v[118:121]
	v_mul_f32_e32 v108, v108, v112
	v_mul_f32_e32 v112, 0xbfb8aa3b, v110
	v_mul_f32_e32 v118, 0xbfb8aa3b, v111
	v_exp_f32_e32 v112, v112
	v_exp_f32_e32 v118, v118
	v_mul_f32_e32 v109, v109, v125
	v_mul_f32_e32 v109, v109, v113
	v_add_f32_e32 v112, 1.0, v112
	v_add_f32_e32 v113, 1.0, v118
	v_mul_f32_e32 v118, 0xbfb8aa3b, v100
	v_rcp_f32_e32 v112, v112
	v_exp_f32_e32 v118, v118
	v_rcp_f32_e32 v113, v113
	s_mov_b64 s[22:23], -1
	v_mul_f32_e32 v110, v110, v112
	v_add_f32_e32 v112, 1.0, v118
	v_mul_f32_e32 v111, v111, v113
	v_rcp_f32_e32 v112, v112
	v_mul_f32_e32 v113, 0xbfb8aa3b, v101
	v_exp_f32_e32 v113, v113
	v_mul_f32_e32 v110, v110, v114
	v_mul_f32_e32 v100, v100, v112
	v_mul_f32_e32 v104, v100, v104
	v_add_f32_e32 v100, 1.0, v113
	v_mul_f32_e32 v112, 0xbfb8aa3b, v102
	v_rcp_f32_e32 v100, v100
	v_exp_f32_e32 v112, v112
	v_mul_f32_e32 v113, 0xbfb8aa3b, v103
	v_exp_f32_e32 v113, v113
	v_mul_f32_e32 v100, v101, v100
	v_add_f32_e32 v101, 1.0, v112
	v_rcp_f32_e32 v101, v101
	v_add_f32_e32 v112, 1.0, v113
	v_rcp_f32_e32 v112, v112
	v_mul_f32_e32 v105, v100, v105
	v_mul_f32_e32 v100, v102, v101
	v_mul_f32_e32 v106, v100, v106
	v_mul_f32_e32 v100, v103, v112
	v_mul_f32_e32 v103, v100, v107
	v_mul_f32_e32 v111, v111, v115
	v_cvt_pk_bf16_f32 v100, v108, v109
	v_cvt_pk_bf16_f32 v101, v110, v111
	v_cvt_pk_bf16_f32 v102, v104, v105
	v_cvt_pk_bf16_f32 v103, v106, v103
	v_mul_f32_e32 v106, 0xbfb8aa3b, v92
	v_exp_f32_e32 v106, v106
	v_mul_f32_e32 v107, 0xbfb8aa3b, v93
	v_exp_f32_e32 v107, v107
	v_or_b32_e32 v104, 16, v0
	v_add_f32_e32 v106, 1.0, v106
	v_rcp_f32_e32 v106, v106
	v_mad_i64_i32 v[104:105], s[18:19], v104, s3, v[2:3]
	v_lshl_add_u64 v[104:105], v[104:105], 0, v[116:117]
	v_add_f32_e32 v107, 1.0, v107
	v_mul_f32_e32 v92, v92, v106
	v_rcp_f32_e32 v107, v107
	flat_store_dwordx4 v[104:105], v[100:103]
	v_mul_f32_e32 v92, v92, v96
	v_mul_f32_e32 v96, 0xbfb8aa3b, v94
	v_mul_f32_e32 v100, 0xbfb8aa3b, v95
	v_exp_f32_e32 v96, v96
	v_exp_f32_e32 v100, v100
	v_mul_f32_e32 v93, v93, v107
	v_mul_f32_e32 v93, v93, v97
	v_add_f32_e32 v96, 1.0, v96
	v_add_f32_e32 v97, 1.0, v100
	v_mul_f32_e32 v100, 0xbfb8aa3b, v84
	v_rcp_f32_e32 v96, v96
	v_exp_f32_e32 v100, v100
	v_rcp_f32_e32 v97, v97
	s_and_b64 vcc, exec, s[4:5]
	v_mul_f32_e32 v94, v94, v96
	v_add_f32_e32 v96, 1.0, v100
	v_mul_f32_e32 v95, v95, v97
	v_rcp_f32_e32 v96, v96
	v_mul_f32_e32 v97, 0xbfb8aa3b, v85
	v_exp_f32_e32 v97, v97
	v_mul_f32_e32 v94, v94, v98
	v_mul_f32_e32 v84, v84, v96
	v_mul_f32_e32 v88, v84, v88
	v_add_f32_e32 v84, 1.0, v97
	v_mul_f32_e32 v96, 0xbfb8aa3b, v86
	v_rcp_f32_e32 v84, v84
	v_exp_f32_e32 v96, v96
	v_mul_f32_e32 v97, 0xbfb8aa3b, v87
	v_exp_f32_e32 v97, v97
	v_mul_f32_e32 v84, v85, v84
	v_add_f32_e32 v85, 1.0, v96
	v_rcp_f32_e32 v85, v85
	v_add_f32_e32 v96, 1.0, v97
	v_rcp_f32_e32 v96, v96
	v_mul_f32_e32 v89, v84, v89
	v_mul_f32_e32 v84, v86, v85
	v_mul_f32_e32 v90, v84, v90
	v_mul_f32_e32 v84, v87, v96
	v_mul_f32_e32 v87, v84, v91
	v_mul_f32_e32 v95, v95, v99
	v_cvt_pk_bf16_f32 v84, v92, v93
	v_cvt_pk_bf16_f32 v85, v94, v95
	v_cvt_pk_bf16_f32 v86, v88, v89
	v_cvt_pk_bf16_f32 v87, v90, v87
	v_mul_f32_e32 v90, 0xbfb8aa3b, v76
	v_exp_f32_e32 v90, v90
	v_mul_f32_e32 v91, 0xbfb8aa3b, v77
	v_exp_f32_e32 v91, v91
	v_or_b32_e32 v88, 32, v0
	v_add_f32_e32 v90, 1.0, v90
	v_rcp_f32_e32 v90, v90
	v_mad_i64_i32 v[88:89], s[18:19], v88, s3, v[2:3]
	v_lshl_add_u64 v[88:89], v[88:89], 0, v[116:117]
	v_add_f32_e32 v91, 1.0, v91
	v_mul_f32_e32 v76, v76, v90
	v_rcp_f32_e32 v91, v91
	flat_store_dwordx4 v[88:89], v[84:87]
	v_mul_f32_e32 v76, v76, v80
	v_mul_f32_e32 v80, 0xbfb8aa3b, v78
	v_mul_f32_e32 v84, 0xbfb8aa3b, v79
	v_exp_f32_e32 v80, v80
	v_exp_f32_e32 v84, v84
	v_mul_f32_e32 v77, v77, v91
	v_mul_f32_e32 v77, v77, v81
	v_add_f32_e32 v80, 1.0, v80
	v_add_f32_e32 v81, 1.0, v84
	v_mul_f32_e32 v84, 0xbfb8aa3b, v64
	v_rcp_f32_e32 v80, v80
	v_exp_f32_e32 v84, v84
	v_rcp_f32_e32 v81, v81
	s_mov_b32 s75, s6
	v_mul_f32_e32 v78, v78, v80
	v_add_f32_e32 v80, 1.0, v84
	v_mul_f32_e32 v79, v79, v81
	v_rcp_f32_e32 v80, v80
	v_mul_f32_e32 v81, 0xbfb8aa3b, v65
	v_exp_f32_e32 v81, v81
	v_mul_f32_e32 v78, v78, v82
	v_mul_f32_e32 v64, v64, v80
	v_mul_f32_e32 v72, v64, v72
	v_add_f32_e32 v64, 1.0, v81
	v_mul_f32_e32 v80, 0xbfb8aa3b, v66
	v_rcp_f32_e32 v64, v64
	v_exp_f32_e32 v80, v80
	v_mul_f32_e32 v81, 0xbfb8aa3b, v67
	v_exp_f32_e32 v81, v81
	v_mul_f32_e32 v64, v65, v64
	v_add_f32_e32 v65, 1.0, v80
	v_rcp_f32_e32 v65, v65
	v_add_f32_e32 v80, 1.0, v81
	v_rcp_f32_e32 v80, v80
	v_mul_f32_e32 v73, v64, v73
	v_mul_f32_e32 v64, v66, v65
	v_mul_f32_e32 v74, v64, v74
	v_mul_f32_e32 v64, v67, v80
	v_mul_f32_e32 v79, v79, v83
	v_mul_f32_e32 v67, v64, v75
	v_cvt_pk_bf16_f32 v64, v76, v77
	v_cvt_pk_bf16_f32 v65, v78, v79
	v_cvt_pk_bf16_f32 v66, v72, v73
	v_or_b32_e32 v72, 48, v0
	v_mad_i64_i32 v[72:73], s[18:19], v72, s3, v[2:3]
	v_lshl_add_u64 v[72:73], v[72:73], 0, v[116:117]
	v_cvt_pk_bf16_f32 v67, v74, v67
	flat_store_dwordx4 v[72:73], v[64:67]
	v_mul_f32_e32 v74, 0xbfb8aa3b, v60
	v_mul_f32_e32 v75, 0xbfb8aa3b, v61
	v_mul_f32_e32 v64, 0xbfb8aa3b, v62
	v_exp_f32_e32 v64, v64
	v_mul_f32_e32 v65, 0xbfb8aa3b, v63
	v_exp_f32_e32 v65, v65
	v_mul_f32_e32 v66, 0xbfb8aa3b, v52
	v_add_f32_e32 v64, 1.0, v64
	v_rcp_f32_e32 v64, v64
	v_add_f32_e32 v65, 1.0, v65
	v_exp_f32_e32 v66, v66
	v_rcp_f32_e32 v65, v65
	v_mul_f32_e32 v62, v62, v64
	v_exp_f32_e32 v74, v74
	v_add_f32_e32 v64, 1.0, v66
	v_mul_f32_e32 v63, v63, v65
	v_rcp_f32_e32 v64, v64
	v_mul_f32_e32 v65, 0xbfb8aa3b, v53
	v_exp_f32_e32 v65, v65
	v_exp_f32_e32 v75, v75
	v_mul_f32_e32 v52, v52, v64
; DEVI unsigned cvtpk(float lo, float hi) { unsigned r; asm volatile("v_cvt_pk_bf16_f32 %0, %1, %2" : "=v"(r) : "v"(lo), "v"(hi)); return r; }
; DEVI float sigmoidf_(float x) { return __builtin_amdgcn_rcpf(1.f + __expf(-x)); }
; #define PG8_WAIT_V(n) asm volatile("s_waitcnt vmcnt(" #n ")" ::: "memory")
; #define PG8_BAR __builtin_amdgcn_s_barrier()
; template <class Epi, class Sched>
; __device__ __forceinline__ void gemm_phase(PG8_LAS unsigned char* lds, const Gemm g, const Sched& S, const Epi& E, int wv) {
;     ...
;         cur = nxt; cA = nA; cB = nB; ++ui;
;     }
;     PG8_WAIT_V(0);
;     if (wr == 0) PG8_BAR;
;     PG8_BAR;
;     DEVI void operator()(AccRef acc, const pg8::Unit& u, int wr, int wc, int fr, int fq) const {
;         const int row0 = u.pm * 256 + wr * 64 + fr, col = u.pn * 128 + wc * 32 + 8 * fq;
; #pragma unroll
;         for (int ai = 0; ai < 2; ++ai)
; #pragma unroll
;             for (int m = 0; m < 4; ++m) { bf16_t* rowp = Hm + (size_t)(row0 + ai * 128 + m * 16) * DFF + col; float h[8];
; #pragma unroll
;                 for (int j = 0; j < 8; ++j) { const float gt = acc[ai][0][m][j >> 2][j & 3], up = acc[ai][1][m][j >> 2][j & 3]; h[j] = gt * sigmoidf_(gt) * up; }
;                 u32x4 w; w.x = cvtpk(h[0], h[1]); w.y = cvtpk(h[2], h[3]); w.z = cvtpk(h[4], h[5]); w.w = cvtpk(h[6], h[7]);
;                 if (ai == 0 && m == 0) asm volatile("s_waitcnt vmcnt(0)" ::: "memory");
;                 __builtin_nontemporal_store(w, (u32x4*)rowp); }
	v_mul_f32_e32 v56, v52, v56
	v_add_f32_e32 v52, 1.0, v65
	v_mul_f32_e32 v64, 0xbfb8aa3b, v54
	v_rcp_f32_e32 v52, v52
	v_exp_f32_e32 v64, v64
	v_mul_f32_e32 v65, 0xbfb8aa3b, v55
	v_exp_f32_e32 v65, v65
	v_mul_f32_e32 v52, v53, v52
	v_add_f32_e32 v53, 1.0, v64
	v_rcp_f32_e32 v53, v53
	v_add_f32_e32 v64, 1.0, v65
	v_add_f32_e32 v74, 1.0, v74
	v_add_f32_e32 v75, 1.0, v75
	v_rcp_f32_e32 v64, v64
	v_rcp_f32_e32 v74, v74
	v_rcp_f32_e32 v75, v75
	v_mul_f32_e32 v57, v52, v57
	v_mul_f32_e32 v52, v54, v53
	v_mul_f32_e32 v58, v52, v58
	v_mul_f32_e32 v52, v55, v64
	v_mul_f32_e32 v60, v60, v74
	v_mul_f32_e32 v61, v61, v75
	v_mul_f32_e32 v55, v52, v59
	v_mul_f32_e32 v60, v60, v68
	v_mul_f32_e32 v61, v61, v69
	v_mul_f32_e32 v62, v62, v70
	v_mul_f32_e32 v63, v63, v71
	v_cvt_pk_bf16_f32 v52, v60, v61
	v_cvt_pk_bf16_f32 v53, v62, v63
	v_cvt_pk_bf16_f32 v54, v56, v57
	v_cvt_pk_bf16_f32 v55, v58, v55
	v_mul_f32_e32 v58, 0xbfb8aa3b, v44
	v_exp_f32_e32 v58, v58
	v_mul_f32_e32 v59, 0xbfb8aa3b, v45
	v_exp_f32_e32 v59, v59
	v_add_u32_e32 v56, 0x80, v0
	v_add_f32_e32 v58, 1.0, v58
	v_rcp_f32_e32 v58, v58
	v_mad_i64_i32 v[56:57], s[18:19], v56, s3, v[2:3]
	v_lshl_add_u64 v[56:57], v[56:57], 0, v[116:117]
	v_add_f32_e32 v59, 1.0, v59
	v_mul_f32_e32 v44, v44, v58
	v_rcp_f32_e32 v59, v59
	flat_store_dwordx4 v[56:57], v[52:55]
	v_mul_f32_e32 v44, v44, v48
	v_mul_f32_e32 v48, 0xbfb8aa3b, v46
	v_mul_f32_e32 v52, 0xbfb8aa3b, v47
	v_exp_f32_e32 v48, v48
	v_exp_f32_e32 v52, v52
	v_mul_f32_e32 v45, v45, v59
	v_mul_f32_e32 v45, v45, v49
	v_add_f32_e32 v48, 1.0, v48
	v_add_f32_e32 v49, 1.0, v52
	v_mul_f32_e32 v52, 0xbfb8aa3b, v36
	v_rcp_f32_e32 v48, v48
	v_exp_f32_e32 v52, v52
	v_rcp_f32_e32 v49, v49
	s_mov_b32 s10, s8
	v_mul_f32_e32 v46, v46, v48
	v_add_f32_e32 v48, 1.0, v52
	v_mul_f32_e32 v47, v47, v49
	v_rcp_f32_e32 v48, v48
	v_mul_f32_e32 v49, 0xbfb8aa3b, v37
	v_exp_f32_e32 v49, v49
	v_mul_f32_e32 v46, v46, v50
	v_mul_f32_e32 v36, v36, v48
	v_mul_f32_e32 v40, v36, v40
	v_add_f32_e32 v36, 1.0, v49
	v_mul_f32_e32 v48, 0xbfb8aa3b, v38
	v_rcp_f32_e32 v36, v36
	v_exp_f32_e32 v48, v48
	v_mul_f32_e32 v49, 0xbfb8aa3b, v39
	v_exp_f32_e32 v49, v49
	v_mul_f32_e32 v36, v37, v36
	v_add_f32_e32 v37, 1.0, v48
	v_rcp_f32_e32 v37, v37
	v_add_f32_e32 v48, 1.0, v49
	v_rcp_f32_e32 v48, v48
	v_mul_f32_e32 v41, v36, v41
	v_mul_f32_e32 v36, v38, v37
	v_mul_f32_e32 v42, v36, v42
	v_mul_f32_e32 v36, v39, v48
	v_mul_f32_e32 v39, v36, v43
	v_mul_f32_e32 v47, v47, v51
	v_cvt_pk_bf16_f32 v36, v44, v45
	v_cvt_pk_bf16_f32 v37, v46, v47
	v_cvt_pk_bf16_f32 v38, v40, v41
	v_cvt_pk_bf16_f32 v39, v42, v39
	v_mul_f32_e32 v42, 0xbfb8aa3b, v28
	v_exp_f32_e32 v42, v42
	v_mul_f32_e32 v43, 0xbfb8aa3b, v29
	v_exp_f32_e32 v43, v43
	v_add_u32_e32 v40, 0x90, v0
	v_add_f32_e32 v42, 1.0, v42
	v_rcp_f32_e32 v42, v42
	v_mad_i64_i32 v[40:41], s[18:19], v40, s3, v[2:3]
	v_lshl_add_u64 v[40:41], v[40:41], 0, v[116:117]
	v_add_f32_e32 v43, 1.0, v43
	v_mul_f32_e32 v28, v28, v42
	v_rcp_f32_e32 v43, v43
	flat_store_dwordx4 v[40:41], v[36:39]
	v_mul_f32_e32 v28, v28, v32
	v_mul_f32_e32 v32, 0xbfb8aa3b, v30
	v_mul_f32_e32 v36, 0xbfb8aa3b, v31
	v_exp_f32_e32 v32, v32
	v_exp_f32_e32 v36, v36
	v_mul_f32_e32 v29, v29, v43
	v_mul_f32_e32 v29, v29, v33
	v_add_f32_e32 v32, 1.0, v32
	v_add_f32_e32 v33, 1.0, v36
	v_mul_f32_e32 v36, 0xbfb8aa3b, v20
	v_rcp_f32_e32 v32, v32
	v_exp_f32_e32 v36, v36
	v_rcp_f32_e32 v33, v33
	s_mov_b64 s[20:21], s[12:13]
	v_mul_f32_e32 v30, v30, v32
	v_add_f32_e32 v32, 1.0, v36
	v_mul_f32_e32 v31, v31, v33
	v_rcp_f32_e32 v32, v32
	v_mul_f32_e32 v33, 0xbfb8aa3b, v21
	v_exp_f32_e32 v33, v33
	v_mul_f32_e32 v30, v30, v34
	v_mul_f32_e32 v20, v20, v32
	v_mul_f32_e32 v24, v20, v24
	v_add_f32_e32 v20, 1.0, v33
	v_mul_f32_e32 v32, 0xbfb8aa3b, v22
	v_rcp_f32_e32 v20, v20
	v_exp_f32_e32 v32, v32
	v_mul_f32_e32 v33, 0xbfb8aa3b, v23
	v_exp_f32_e32 v33, v33
	v_mul_f32_e32 v20, v21, v20
	v_add_f32_e32 v21, 1.0, v32
	v_rcp_f32_e32 v21, v21
	v_add_f32_e32 v32, 1.0, v33
	v_rcp_f32_e32 v32, v32
	v_mul_f32_e32 v25, v20, v25
	v_mul_f32_e32 v20, v22, v21
	v_mul_f32_e32 v26, v20, v26
	v_mul_f32_e32 v20, v23, v32
	v_mul_f32_e32 v23, v20, v27
	v_mul_f32_e32 v31, v31, v35
	v_cvt_pk_bf16_f32 v20, v28, v29
	v_cvt_pk_bf16_f32 v21, v30, v31
	v_cvt_pk_bf16_f32 v22, v24, v25
	v_cvt_pk_bf16_f32 v23, v26, v23
	v_mul_f32_e32 v26, 0xbfb8aa3b, v12
	v_exp_f32_e32 v26, v26
	v_mul_f32_e32 v27, 0xbfb8aa3b, v13
	v_exp_f32_e32 v27, v27
	v_add_u32_e32 v24, 0xa0, v0
	v_add_f32_e32 v26, 1.0, v26
	v_rcp_f32_e32 v26, v26
	v_mad_i64_i32 v[24:25], s[18:19], v24, s3, v[2:3]
	v_lshl_add_u64 v[24:25], v[24:25], 0, v[116:117]
	v_add_f32_e32 v27, 1.0, v27
	v_mul_f32_e32 v12, v12, v26
	v_rcp_f32_e32 v27, v27
	flat_store_dwordx4 v[24:25], v[20:23]
	v_mul_f32_e32 v12, v12, v16
	v_mul_f32_e32 v16, 0xbfb8aa3b, v14
	v_mul_f32_e32 v20, 0xbfb8aa3b, v15
	v_exp_f32_e32 v16, v16
	v_exp_f32_e32 v20, v20
	v_mul_f32_e32 v13, v13, v27
	v_mul_f32_e32 v13, v13, v17
	v_add_f32_e32 v16, 1.0, v16
	v_add_f32_e32 v17, 1.0, v20
	v_mul_f32_e32 v20, 0xbfb8aa3b, v4
	v_rcp_f32_e32 v16, v16
	v_exp_f32_e32 v20, v20
	v_rcp_f32_e32 v17, v17
	v_add_u32_e32 v0, 0xb0, v0
	v_mul_f32_e32 v14, v14, v16
	v_add_f32_e32 v16, 1.0, v20
	v_mul_f32_e32 v15, v15, v17
	v_rcp_f32_e32 v16, v16
	v_mul_f32_e32 v17, 0xbfb8aa3b, v5
	v_exp_f32_e32 v17, v17
	v_mad_i64_i32 v[2:3], s[18:19], v0, s3, v[2:3]
	v_mul_f32_e32 v4, v4, v16
	v_mul_f32_e32 v8, v4, v8
	v_add_f32_e32 v4, 1.0, v17
	v_mul_f32_e32 v16, 0xbfb8aa3b, v6
	v_rcp_f32_e32 v4, v4
	v_exp_f32_e32 v16, v16
	v_mul_f32_e32 v17, 0xbfb8aa3b, v7
	v_exp_f32_e32 v17, v17
	v_mul_f32_e32 v4, v5, v4
	v_add_f32_e32 v5, 1.0, v16
	v_rcp_f32_e32 v5, v5
	v_add_f32_e32 v16, 1.0, v17
	v_rcp_f32_e32 v16, v16
	v_mul_f32_e32 v9, v4, v9
	v_mul_f32_e32 v4, v6, v5
	v_mul_f32_e32 v10, v4, v10
	v_mul_f32_e32 v4, v7, v16
	v_mul_f32_e32 v7, v4, v11
	v_lshl_add_u64 v[2:3], v[2:3], 0, v[116:117]
	s_mov_b64 s[18:19], s[14:15]
	v_mul_f32_e32 v14, v14, v18
	v_mul_f32_e32 v15, v15, v19
	v_cvt_pk_bf16_f32 v4, v12, v13
	v_cvt_pk_bf16_f32 v5, v14, v15
	v_cvt_pk_bf16_f32 v6, v8, v9
	v_cvt_pk_bf16_f32 v7, v10, v7
	flat_store_dwordx4 v[2:3], v[4:7]
	s_cbranch_vccz .LBB0_522
	s_waitcnt vmcnt(0)
	s_cmpk_gt_u32 s24, 0xff
	s_cbranch_scc1 .LBB0_532
	s_barrier
